# prep phase rewritten: one wave = 16 consecutive rows, sliding-window sums, each input row loaded once; attention waves 4-7 static prio
# speedup vs baseline: 1.0113x; 1.0113x over previous
; __global__ void __launch_bounds__(512, 2) mk_fwd(Args args) {
;     ...
;             { const int nu = (G == 256) ? 4 : (1024 - bx + G - 1) / G;
; #pragma unroll 1
;               for (int i = 0; i < nu; ++i) { int bh, qb;
;                   if (G == 256) { const int s = vcu & 3; bh = vcu >> 2; qb = (i == 0) ? 15 - s : (i == 1) ? 8 + s : (i == 2) ? 7 - s : s; }
;                   else { const int u = bx + i * G; bh = u >> 4; qb = 15 - (u & 15); }
;                   attn_unit(bh >> 3, bh & 7, qb, Qb, Kb, Vt, CAT + 256, lds); } }
.LBB0_313:
	v_cmp_lt_u32_e32 vcc, 0xff, v222
	s_cbranch_vccz .Lattn_prio_skip
	s_setprio 1

; __global__ void __launch_bounds__(512, 2) mk_fwd(Args args) {
;     ...
;               for (int i = 0; i < nu; ++i) { int bh, qb;
;                   if (G == 256) { const int s = vcu & 3; bh = vcu >> 2; qb = (i == 0) ? 15 - s : (i == 1) ? 8 + s : (i == 2) ? 7 - s : s; }
;                   else { const int u = bx + i * G; bh = u >> 4; qb = 15 - (u & 15); }
;                   attn_unit(bh >> 3, bh & 7, qb, Qb, Kb, Vt, CAT + 256, lds); } }
;         } break;
.LBB0_357:
	s_setprio 0
	s_mov_b64 s[0:1], 0

; __device__ __forceinline__ void prep_load(PrepRow& d, const PrepArgs& a, int row, int lane) {
;     const bf16_t* pr = a.PA + (size_t)row * PA_LD; const int ts = row & (SEQ - 1);
;     { const int fi = ((lane & 7) * 4) & 15; d.r1 = *(const u32x2*)(pr + 896 + fi); d.r2 = *(const u32x2*)(pr + 912 + fi);
;       d.c = *(const f32x4*)(a.cs + ts * 16 + fi); d.s = *(const f32x4*)(a.sn + ts * 16 + fi); }
;     { const int win = 2 << (lane >> 4); const int n = (ts + 1 < win) ? ts + 1 : win;
; #pragma unroll
;       for (int i = 0; i < 16; ++i) { const int ii = (i < n) ? i : 0; d.pool[i] = *(const u32x2*)(pr - (size_t)ii * PA_LD + 4 * lane); } }
; #pragma unroll
;     for (int j = 0; j < 4; ++j) { const int back = (ts - 3 + j >= 0) ? (3 - j) : 0; d.cv[j] = *(const u32x2*)(pr - (size_t)back * PA_LD + 256 + 4 * lane); }
; }
; __device__ __forceinline__ void prep_phase(const PrepArgs& a, int gw, int NGW, int lane) {
;     PrepRow dA, dB;
;     int row = gw;
;     if (row < TOK) prep_load(dA, a, row, lane);
.LBB0_559:
	s_andn2_b64 vcc, exec, s[0:1]
	s_cbranch_vccnz .LBB0_797
	s_add_u32 s60, s50, 0x12000000
	s_addc_u32 s61, s51, 0
	s_cmp_gt_i32 s18, 1
	s_mov_b64 s[0:1], -1
	s_cbranch_scc0 .LBB0_567
	v_mov_b32_e32 v10, v222
	s_lshl_b32 s1, s45, 3
	v_readfirstlane_b32 s0, v10
	s_ashr_i32 s0, s0, 6
	s_add_i32 s20, s0, s1
	s_cmpk_gt_i32 s20, 0x7fff
	s_cbranch_scc1 .LBB0_566
	s_lshl_b32 s0, s76, 8
	s_ashr_i32 s1, s0, 31
	s_mov_b32 s12, s76
	v_readlane_b32 s64, v253, 16
	s_lshl_b64 s[0:1], s[0:1], 2
	v_readlane_b32 s72, v253, 24
	v_readlane_b32 s73, v253, 25
	v_readlane_b32 s76, v253, 28
	s_add_u32 s0, s72, s0
	s_mov_b32 s76, s12
	s_addc_u32 s1, s73, s1
	s_lshl_b32 s12, s12, 10
	s_ashr_i32 s13, s12, 31
	v_readlane_b32 s70, v253, 22
	s_lshl_b64 s[12:13], s[12:13], 2
	v_readlane_b32 s71, v253, 23
	s_add_u32 s24, s70, s12
	s_addc_u32 s25, s71, s13
	s_mul_i32 s13, s20, 0xa00
	v_and_b32_e32 v13, 63, v10
	s_mul_hi_i32 s12, s20, 0xa00
	s_add_u32 s30, s60, s13
	s_addc_u32 s31, s61, s12
	s_and_b32 s14, s20, 0xfff
	v_lshlrev_b32_e32 v12, 2, v13
	v_and_b32_e32 v14, 12, v12
	s_lshl_b32 s15, s14, 6
	v_lshlrev_b32_e32 v0, 1, v14
	s_add_u32 s12, s54, s15
	s_waitcnt vmcnt(0) lgkmcnt(0)
	v_lshl_add_u64 v[2:3], s[30:31], 0, v[0:1]
	s_addc_u32 s13, s55, 0
	v_lshlrev_b32_e32 v0, 2, v14
	global_load_dwordx2 v[44:45], v[2:3], off offset:1792
	global_load_dwordx2 v[42:43], v[2:3], off offset:1824
	v_lshl_add_u64 v[2:3], s[12:13], 0, v[0:1]
	s_add_u32 s12, s58, s15
	s_addc_u32 s13, s59, 0
	v_bfe_u32 v11, v10, 4, 2
	v_lshl_add_u64 v[6:7], s[12:13], 0, v[0:1]
	v_lshlrev_b32_e64 v122, v11, 2
	s_add_i32 s12, s14, 1
	v_min_u32_e32 v11, s12, v122
	v_cmp_lt_u32_e32 vcc, 2, v11
	v_mov_b32_e32 v15, 0xffffec00
	v_lshlrev_b32_e32 v16, 3, v13
	v_cndmask_b32_e64 v23, 0, -1, vcc
	v_cndmask_b32_e32 v22, 0, v15, vcc
	v_cmp_lt_u32_e32 vcc, 3, v11
	v_mov_b32_e32 v15, 0xffffe200
	v_mov_b32_e32 v17, v1
	v_cndmask_b32_e64 v25, 0, -1, vcc
	v_cndmask_b32_e32 v24, 0, v15, vcc
	v_cmp_lt_u32_e32 vcc, 4, v11
	v_mov_b32_e32 v15, 0xffffd800
	v_lshl_add_u64 v[18:19], s[30:31], 0, v[16:17]
	v_cndmask_b32_e64 v27, 0, -1, vcc
	v_cndmask_b32_e32 v26, 0, v15, vcc
	v_cmp_lt_u32_e32 vcc, 5, v11
	v_lshl_add_u64 v[24:25], v[18:19], 0, v[24:25]
	global_load_dwordx4 v[2:5], v[2:3], off
	s_nop 0
	global_load_dwordx4 v[6:9], v[6:7], off
	v_cndmask_b32_e64 v29, 0, -1, vcc
	v_cndmask_b32_e32 v28, 0, v238, vcc
	v_cmp_lt_u32_e32 vcc, 6, v11
	v_lshl_add_u64 v[26:27], v[18:19], 0, v[26:27]
	v_lshl_add_u64 v[28:29], v[18:19], 0, v[28:29]
	v_cndmask_b32_e64 v31, 0, -1, vcc
	v_cndmask_b32_e32 v30, 0, v239, vcc
	v_cmp_lt_u32_e32 vcc, 7, v11
	v_lshl_add_u64 v[30:31], v[18:19], 0, v[30:31]
	global_load_dwordx2 v[62:63], v[24:25], off
	global_load_dwordx2 v[56:57], v[26:27], off
	global_load_dwordx2 v[50:51], v[28:29], off
	global_load_dwordx2 v[46:47], v[30:31], off
	v_cndmask_b32_e64 v25, 0, -1, vcc
	v_cndmask_b32_e32 v24, 0, v240, vcc
	v_cmp_lt_u32_e32 vcc, 8, v11
	s_cmp_eq_u32 s14, 0
	s_cselect_b32 s37, 0, -1
	v_cndmask_b32_e64 v27, 0, -1, vcc
	v_cndmask_b32_e32 v26, 0, v241, vcc
	v_cmp_lt_u32_e32 vcc, 9, v11
	s_cselect_b32 s36, 0, 0xfffff600
	v_lshl_add_u64 v[24:25], v[18:19], 0, v[24:25]
	v_cndmask_b32_e64 v29, 0, -1, vcc
	v_cndmask_b32_e32 v28, 0, v242, vcc
	v_cmp_lt_u32_e32 vcc, 10, v11
	s_cmp_lt_u32 s14, 3
	v_lshl_add_u64 v[26:27], v[18:19], 0, v[26:27]
	v_cndmask_b32_e64 v31, 0, -1, vcc
	v_cndmask_b32_e32 v30, 0, v243, vcc
	v_cmp_lt_u32_e32 vcc, 11, v11
	v_lshl_add_u64 v[28:29], v[18:19], 0, v[28:29]
	v_lshl_add_u64 v[30:31], v[18:19], 0, v[30:31]
	global_load_dwordx2 v[68:69], v[24:25], off
	global_load_dwordx2 v[60:61], v[26:27], off
	global_load_dwordx2 v[54:55], v[28:29], off
	global_load_dwordx2 v[48:49], v[30:31], off
	v_cndmask_b32_e64 v25, 0, -1, vcc
	v_cndmask_b32_e32 v24, 0, v244, vcc
	v_cmp_lt_u32_e32 vcc, 12, v11
	s_cselect_b32 s12, 0, 0xffffe200
	s_cselect_b32 s13, 0, -1
	v_cndmask_b32_e64 v27, 0, -1, vcc
	v_cndmask_b32_e32 v26, 0, v245, vcc
	v_cmp_lt_u32_e32 vcc, 13, v11
	s_add_u32 s12, s30, s12
	s_addc_u32 s13, s31, s13
	v_cndmask_b32_e64 v29, 0, -1, vcc
	v_cndmask_b32_e32 v28, 0, v223, vcc
	v_cmp_lt_u32_e32 vcc, 14, v11
	v_lshl_add_u64 v[24:25], v[18:19], 0, v[24:25]
	v_lshl_add_u64 v[26:27], v[18:19], 0, v[26:27]
	v_cndmask_b32_e64 v31, 0, -1, vcc
	v_cndmask_b32_e32 v30, 0, v228, vcc
	s_cmp_lt_u32 s14, 2
	v_lshl_add_u64 v[28:29], v[18:19], 0, v[28:29]
	v_lshl_add_u64 v[30:31], v[18:19], 0, v[30:31]
	global_load_dwordx2 v[70:71], v[24:25], off
	global_load_dwordx2 v[66:67], v[26:27], off
	global_load_dwordx2 v[58:59], v[28:29], off
	global_load_dwordx2 v[52:53], v[30:31], off
	v_lshl_add_u64 v[26:27], s[12:13], 0, v[16:17]
	s_cselect_b32 s12, 0, 0xffffec00
	s_cselect_b32 s13, 0, -1
	s_add_u32 s12, s30, s12
	v_cmp_lt_u32_e32 vcc, 15, v11
	s_addc_u32 s13, s31, s13
	v_lshl_add_u64 v[28:29], s[12:13], 0, v[16:17]
	v_cndmask_b32_e64 v25, 0, -1, vcc
	v_cndmask_b32_e32 v24, 0, v227, vcc
	s_add_u32 s12, s30, s36
	v_lshl_add_u64 v[24:25], v[18:19], 0, v[24:25]
	s_addc_u32 s13, s31, s37
	v_lshl_add_u64 v[20:21], v[18:19], 0, s[36:37]
	v_lshl_add_u64 v[22:23], v[18:19], 0, v[22:23]
	v_lshl_add_u64 v[30:31], s[12:13], 0, v[16:17]
	global_load_dwordx2 v[64:65], v[24:25], off
	global_load_dwordx2 v[40:41], v[26:27], off offset:512
	global_load_dwordx2 v[38:39], v[28:29], off offset:512
	global_load_dwordx2 v[36:37], v[30:31], off offset:512
	global_load_dwordx2 v[90:91], v[18:19], off
	global_load_dwordx2 v[86:87], v[20:21], off
	global_load_dwordx2 v[82:83], v[22:23], off
	global_load_dwordx2 v[34:35], v[18:19], off offset:512
	v_bfe_u32 v10, v10, 3, 3
	v_mul_u32_u24_e32 v10, 0x60, v10
	v_lshl_add_u64 v[18:19], s[54:55], 0, v[0:1]
; __device__ __forceinline__ unsigned pk2(float lo, float hi) { f32x2 v = {lo, hi}; bf16x2_t b = __builtin_convertvector(v, bf16x2_t); return __builtin_bit_cast(unsigned, b); }
; __device__ __forceinline__ float bflo(unsigned u) { return __uint_as_float(u << 16); }
; __device__ __forceinline__ float bfhi(unsigned u) { return __uint_as_float(u & 0xffff0000u); }
; __device__ __forceinline__ void prep_load(PrepRow& d, const PrepArgs& a, int row, int lane) {
;     const bf16_t* pr = a.PA + (size_t)row * PA_LD; const int ts = row & (SEQ - 1);
;     { const int fi = ((lane & 7) * 4) & 15; d.r1 = *(const u32x2*)(pr + 896 + fi); d.r2 = *(const u32x2*)(pr + 912 + fi);
;       d.c = *(const f32x4*)(a.cs + ts * 16 + fi); d.s = *(const f32x4*)(a.sn + ts * 16 + fi); }
;     { const int win = 2 << (lane >> 4); const int n = (ts + 1 < win) ? ts + 1 : win;
; #pragma unroll
;       for (int i = 0; i < 16; ++i) { const int ii = (i < n) ? i : 0; d.pool[i] = *(const u32x2*)(pr - (size_t)ii * PA_LD + 4 * lane); } }
; #pragma unroll
;     for (int j = 0; j < 4; ++j) { const int back = (ts - 3 + j >= 0) ? (3 - j) : 0; d.cv[j] = *(const u32x2*)(pr - (size_t)back * PA_LD + 256 + 4 * lane); }
; }
; __device__ __forceinline__ void prep_compute(const PrepRow& d, const PrepArgs& a, int row, int lane) {
;     ...
;     { f32x4 accv = *(const f32x4*)(a.convb + 4 * lane);
; #pragma unroll
;       for (int j = 0; j < 4; ++j) { const float mk = (ts - 3 + j >= 0) ? 1.f : 0.f; const f32x4 v = {bflo(d.cv[j].x), bfhi(d.cv[j].x), bflo(d.cv[j].y), bfhi(d.cv[j].y)};
;           accv += v * mk * *(const f32x4*)(a.convw + j * 256 + 4 * lane); }
;       u32x2 w; w.x = pk2(accv[0], accv[1]); w.y = pk2(accv[2], accv[3]);
;       *(u32x2*)(a.uconv + (size_t)row * 256 + 4 * lane) = w; }
	v_lshl_add_u64 v[20:21], s[58:59], 0, v[0:1]
	v_lshlrev_b32_e32 v0, 1, v10
	v_readlane_b32 s78, v253, 30
	v_readlane_b32 s79, v253, 31
	v_and_b32_e32 v15, 28, v12
	v_lshl_add_u64 v[10:11], s[8:9], 0, v[0:1]
	v_lshlrev_b32_e32 v0, 4, v13
	v_readlane_b32 s65, v253, 17
	v_readlane_b32 s66, v253, 18
	v_readlane_b32 s75, v253, 27
	v_readlane_b32 s78, v254, 58
	v_lshl_add_u64 v[24:25], s[0:1], 0, v[0:1]
	v_lshl_add_u64 v[26:27], s[24:25], 0, v[0:1]
	v_lshlrev_b32_e32 v0, 1, v15
	s_movk_i32 s65, 0xd0
	s_mov_b32 s63, 0x2aaaaaab
	s_movk_i32 s75, 0x5000
	s_movk_i32 s66, 0x4000
	s_movk_i32 s64, 0x2000
	v_readlane_b32 s79, v254, 59
	s_movk_i32 s73, 0x60
	s_movk_i32 s70, 0x6000
	s_mov_b32 s71, 0x30000
	v_cmp_gt_u32_e64 s[38:39], 16, v15
	v_lshl_add_u64 v[22:23], s[10:11], 0, v[16:17]
	v_lshl_add_u64 v[28:29], s[4:5], 0, v[16:17]
	v_lshl_add_u64 v[30:31], v[10:11], 0, v[0:1]
	s_lshl_b32 s12, s35, 4
	v_lshlrev_b32_e32 v0, 1, v14
	v_lshlrev_b32_e32 v32, 1, v12
	v_readlane_b32 s67, v253, 19
	v_readlane_b32 s68, v253, 20
	v_readlane_b32 s69, v253, 21
	v_readlane_b32 s74, v253, 26
	v_readlane_b32 s77, v253, 29
	global_load_dwordx4 v[146:149], v[24:25], off
	global_load_dwordx4 v[150:153], v[26:27], off
	global_load_dwordx4 v[154:157], v[26:27], off offset:1024
	global_load_dwordx4 v[158:161], v[26:27], off offset:2048
	global_load_dwordx4 v[162:165], v[26:27], off offset:3072
	s_cmpk_lg_i32 s35, 0x100
	s_cbranch_scc1 .LBB0_564
	s_waitcnt vmcnt(0)
	v_and_b32_e32 v2, 63, v222
	v_lshlrev_b32_e32 v3, 3, v2
	v_lshrrev_b32_e32 v4, 4, v2
	v_lshlrev_b32_e64 v4, v4, 2
	v_and_b32_e32 v5, 3, v2
	v_lshlrev_b32_e32 v6, 3, v5
	v_lshlrev_b32_e32 v7, 4, v5
	v_lshrrev_b32_e32 v8, 3, v2
	v_mul_u32_u24_e32 v8, 0xc0, v8
	v_and_b32_e32 v9, 7, v2
	v_lshl_add_u32 v8, v9, 3, v8
	v_add_u32_e32 v8, 0x80, v8
	v_lshlrev_b32_e32 v9, 4, v2
	s_lshl_b32 s19, s20, 4
	s_and_b32 s13, s19, 0xfff
	s_mul_i32 s48, s19, 0xa00
	s_add_u32 s30, s60, s48
	s_addc_u32 s31, s61, 0
	s_sub_u32 s14, s30, 0x9600
	s_subb_u32 s15, s31, 0
	s_sub_u32 s16, s30, 0x1e00
	s_subb_u32 s17, s31, 0
	s_add_u32 s30, s30, 0x700
	s_addc_u32 s31, s31, 0
	s_lshl_b32 s48, s13, 6
	s_add_u32 s36, s54, s48
	s_addc_u32 s37, s55, 0
	s_add_u32 s40, s58, s48
	s_addc_u32 s41, s59, 0
	s_mul_i32 s48, s19, 0x600
	s_add_u32 s42, s8, s48
	s_addc_u32 s43, s9, 0
	s_lshl_b32 s48, s19, 11
	s_add_u32 s44, s10, s48
	s_addc_u32 s45, s11, 0
	s_lshl_b32 s48, s19, 9
	s_add_u32 s20, s4, s48
	s_addc_u32 s21, s5, 0
	s_nop 0
	global_load_dwordx4 v[196:199], v9, s[0:1]
	global_load_dwordx4 v[200:203], v9, s[24:25]
	global_load_dwordx4 v[204:207], v9, s[24:25] offset:1024
	global_load_dwordx4 v[208:211], v9, s[24:25] offset:2048
	global_load_dwordx4 v[212:215], v9, s[24:25] offset:3072
	global_load_dwordx2 v[16:17], v3, s[16:17] offset:512
	s_add_u32 s16, s16, 0xa00
	s_addc_u32 s17, s17, 0
	s_nop 0
	global_load_dwordx2 v[18:19], v3, s[16:17] offset:512
	s_add_u32 s16, s16, 0xa00
	s_addc_u32 s17, s17, 0
	s_nop 0
	global_load_dwordx2 v[20:21], v3, s[16:17] offset:512
	s_add_u32 s16, s16, 0xa00
	s_addc_u32 s17, s17, 0
	s_nop 0
	global_load_dwordx2 v[22:23], v3, s[16:17] offset:512
	s_add_u32 s16, s16, 0xa00
	s_addc_u32 s17, s17, 0
	s_nop 0
	global_load_dwordx2 v[24:25], v3, s[16:17] offset:512
	s_add_u32 s16, s16, 0xa00
	s_addc_u32 s17, s17, 0
	s_nop 0
	global_load_dwordx2 v[26:27], v3, s[16:17] offset:512
	s_add_u32 s16, s16, 0xa00
	s_addc_u32 s17, s17, 0
	s_nop 0
	global_load_dwordx2 v[28:29], v3, s[16:17] offset:512
	s_add_u32 s16, s16, 0xa00
	s_addc_u32 s17, s17, 0
	s_nop 0
	global_load_dwordx2 v[30:31], v3, s[16:17] offset:512
	s_add_u32 s16, s16, 0xa00
	s_addc_u32 s17, s17, 0
	s_nop 0
	global_load_dwordx2 v[32:33], v3, s[16:17] offset:512
	s_add_u32 s16, s16, 0xa00
	s_addc_u32 s17, s17, 0
	s_nop 0
	global_load_dwordx2 v[34:35], v3, s[16:17] offset:512
	s_add_u32 s16, s16, 0xa00
	s_addc_u32 s17, s17, 0
	s_nop 0
	global_load_dwordx2 v[36:37], v3, s[16:17] offset:512
	s_add_u32 s16, s16, 0xa00
	s_addc_u32 s17, s17, 0
	s_nop 0
	global_load_dwordx2 v[38:39], v3, s[16:17] offset:512
	s_add_u32 s16, s16, 0xa00
	s_addc_u32 s17, s17, 0
	s_nop 0
	global_load_dwordx2 v[40:41], v3, s[16:17] offset:512
	s_add_u32 s16, s16, 0xa00
	s_addc_u32 s17, s17, 0
	s_nop 0
	global_load_dwordx2 v[42:43], v3, s[16:17] offset:512
	s_add_u32 s16, s16, 0xa00
	s_addc_u32 s17, s17, 0
	s_nop 0
	global_load_dwordx2 v[44:45], v3, s[16:17] offset:512
	s_add_u32 s16, s16, 0xa00
	s_addc_u32 s17, s17, 0
	s_nop 0
	global_load_dwordx2 v[46:47], v3, s[16:17] offset:512
	s_add_u32 s16, s16, 0xa00
	s_addc_u32 s17, s17, 0
	s_nop 0
	global_load_dwordx2 v[48:49], v3, s[16:17] offset:512
	s_add_u32 s16, s16, 0xa00
	s_addc_u32 s17, s17, 0
	s_nop 0
	global_load_dwordx2 v[50:51], v3, s[16:17] offset:512
	s_add_u32 s16, s16, 0xa00
	s_addc_u32 s17, s17, 0
	s_nop 0
	global_load_dwordx2 v[52:53], v3, s[16:17] offset:512
	global_load_dwordx2 v[134:135], v3, s[14:15]
	s_add_u32 s14, s14, 0xa00
	s_addc_u32 s15, s15, 0
	s_nop 0
	global_load_dwordx2 v[136:137], v3, s[14:15]
	s_add_u32 s14, s14, 0xa00
	s_addc_u32 s15, s15, 0
	s_nop 0
	global_load_dwordx2 v[138:139], v3, s[14:15]
	s_add_u32 s14, s14, 0xa00
	s_addc_u32 s15, s15, 0
	s_nop 0
	global_load_dwordx2 v[140:141], v3, s[14:15]
	s_add_u32 s14, s14, 0xa00
	s_addc_u32 s15, s15, 0
	s_nop 0
	global_load_dwordx2 v[142:143], v3, s[14:15]
	s_add_u32 s14, s14, 0xa00
	s_addc_u32 s15, s15, 0
	s_nop 0
	global_load_dwordx2 v[144:145], v3, s[14:15]
	s_add_u32 s14, s14, 0xa00
	s_addc_u32 s15, s15, 0
	s_nop 0
	global_load_dwordx2 v[146:147], v3, s[14:15]
	s_add_u32 s14, s14, 0xa00
	s_addc_u32 s15, s15, 0
	s_nop 0
	global_load_dwordx2 v[148:149], v3, s[14:15]
; __device__ __forceinline__ float bflo(unsigned u) { return __uint_as_float(u << 16); }
; __device__ __forceinline__ float bfhi(unsigned u) { return __uint_as_float(u & 0xffff0000u); }
; __device__ __forceinline__ void prep_load(PrepRow& d, const PrepArgs& a, int row, int lane) {
;     const bf16_t* pr = a.PA + (size_t)row * PA_LD; const int ts = row & (SEQ - 1);
;     { const int fi = ((lane & 7) * 4) & 15; d.r1 = *(const u32x2*)(pr + 896 + fi); d.r2 = *(const u32x2*)(pr + 912 + fi);
;       d.c = *(const f32x4*)(a.cs + ts * 16 + fi); d.s = *(const f32x4*)(a.sn + ts * 16 + fi); }
;     { const int win = 2 << (lane >> 4); const int n = (ts + 1 < win) ? ts + 1 : win;
; #pragma unroll
;       for (int i = 0; i < 16; ++i) { const int ii = (i < n) ? i : 0; d.pool[i] = *(const u32x2*)(pr - (size_t)ii * PA_LD + 4 * lane); } }
; #pragma unroll
;     for (int j = 0; j < 4; ++j) { const int back = (ts - 3 + j >= 0) ? (3 - j) : 0; d.cv[j] = *(const u32x2*)(pr - (size_t)back * PA_LD + 256 + 4 * lane); }
; }
; __device__ __forceinline__ void prep_compute(const PrepRow& d, const PrepArgs& a, int row, int lane) {
;     ...
;     { f32x4 accv = *(const f32x4*)(a.convb + 4 * lane);
; #pragma unroll
;       for (int j = 0; j < 4; ++j) { const float mk = (ts - 3 + j >= 0) ? 1.f : 0.f; const f32x4 v = {bflo(d.cv[j].x), bfhi(d.cv[j].x), bflo(d.cv[j].y), bfhi(d.cv[j].y)};
;           accv += v * mk * *(const f32x4*)(a.convw + j * 256 + 4 * lane); }
	s_add_u32 s14, s14, 0xa00
	s_addc_u32 s15, s15, 0
	s_nop 0
	global_load_dwordx2 v[150:151], v3, s[14:15]
	s_add_u32 s14, s14, 0xa00
	s_addc_u32 s15, s15, 0
	s_nop 0
	global_load_dwordx2 v[152:153], v3, s[14:15]
	s_add_u32 s14, s14, 0xa00
	s_addc_u32 s15, s15, 0
	s_nop 0
	global_load_dwordx2 v[154:155], v3, s[14:15]
	s_add_u32 s14, s14, 0xa00
	s_addc_u32 s15, s15, 0
	s_nop 0
	global_load_dwordx2 v[156:157], v3, s[14:15]
	s_add_u32 s14, s14, 0xa00
	s_addc_u32 s15, s15, 0
	s_nop 0
	global_load_dwordx2 v[158:159], v3, s[14:15]
	s_add_u32 s14, s14, 0xa00
	s_addc_u32 s15, s15, 0
	s_nop 0
	global_load_dwordx2 v[160:161], v3, s[14:15]
	s_add_u32 s14, s14, 0xa00
	s_addc_u32 s15, s15, 0
	s_nop 0
	global_load_dwordx2 v[162:163], v3, s[14:15]
	s_add_u32 s14, s14, 0xa00
	s_addc_u32 s15, s15, 0
	s_nop 0
	global_load_dwordx2 v[164:165], v3, s[14:15]
	s_add_u32 s14, s14, 0xa00
	s_addc_u32 s15, s15, 0
	s_nop 0
	global_load_dwordx2 v[166:167], v3, s[14:15]
	s_add_u32 s14, s14, 0xa00
	s_addc_u32 s15, s15, 0
	s_nop 0
	global_load_dwordx2 v[168:169], v3, s[14:15]
	s_add_u32 s14, s14, 0xa00
	s_addc_u32 s15, s15, 0
	s_nop 0
	global_load_dwordx2 v[170:171], v3, s[14:15]
	s_add_u32 s14, s14, 0xa00
	s_addc_u32 s15, s15, 0
	s_nop 0
	global_load_dwordx2 v[172:173], v3, s[14:15]
	s_add_u32 s14, s14, 0xa00
	s_addc_u32 s15, s15, 0
	s_nop 0
	global_load_dwordx2 v[174:175], v3, s[14:15]
	s_add_u32 s14, s14, 0xa00
	s_addc_u32 s15, s15, 0
	s_nop 0
	global_load_dwordx2 v[176:177], v3, s[14:15]
	s_add_u32 s14, s14, 0xa00
	s_addc_u32 s15, s15, 0
	s_nop 0
	global_load_dwordx2 v[178:179], v3, s[14:15]
	s_add_u32 s14, s14, 0xa00
	s_addc_u32 s15, s15, 0
	s_nop 0
	global_load_dwordx2 v[180:181], v3, s[14:15]
	s_add_u32 s14, s14, 0xa00
	s_addc_u32 s15, s15, 0
	s_nop 0
	global_load_dwordx2 v[182:183], v3, s[14:15]
	s_add_u32 s14, s14, 0xa00
	s_addc_u32 s15, s15, 0
	s_nop 0
	global_load_dwordx2 v[184:185], v3, s[14:15]
	s_add_u32 s14, s14, 0xa00
	s_addc_u32 s15, s15, 0
	s_nop 0
	global_load_dwordx2 v[216:217], v3, s[14:15]
	s_add_u32 s14, s14, 0xa00
	s_addc_u32 s15, s15, 0
	s_nop 0
	global_load_dwordx2 v[218:219], v3, s[14:15]
	s_add_u32 s14, s14, 0xa00
	s_addc_u32 s15, s15, 0
	s_nop 0
	global_load_dwordx2 v[220:221], v3, s[14:15]
	s_add_u32 s14, s14, 0xa00
	s_addc_u32 s15, s15, 0
	s_nop 0
	global_load_dwordx2 v[232:233], v3, s[14:15]
	s_add_u32 s14, s14, 0xa00
	s_addc_u32 s15, s15, 0
	s_nop 0
	global_load_dwordx2 v[234:235], v3, s[14:15]
	s_waitcnt vmcnt(31)
	v_lshlrev_b32_e32 v54, 16, v16
	v_and_b32_e32 v55, 0xffff0000, v16
	v_lshlrev_b32_e32 v56, 16, v17
	v_and_b32_e32 v57, 0xffff0000, v17
	v_lshlrev_b32_e32 v58, 16, v18
	v_and_b32_e32 v59, 0xffff0000, v18
	v_lshlrev_b32_e32 v60, 16, v19
	v_and_b32_e32 v61, 0xffff0000, v19
	v_lshlrev_b32_e32 v62, 16, v20
	v_and_b32_e32 v63, 0xffff0000, v20
	v_lshlrev_b32_e32 v64, 16, v21
	v_and_b32_e32 v65, 0xffff0000, v21
	v_lshlrev_b32_e32 v66, 16, v22
	v_and_b32_e32 v67, 0xffff0000, v22
	v_lshlrev_b32_e32 v68, 16, v23
	v_and_b32_e32 v69, 0xffff0000, v23
	v_lshlrev_b32_e32 v70, 16, v24
	v_and_b32_e32 v71, 0xffff0000, v24
	v_lshlrev_b32_e32 v72, 16, v25
	v_and_b32_e32 v73, 0xffff0000, v25
	v_lshlrev_b32_e32 v74, 16, v26
	v_and_b32_e32 v75, 0xffff0000, v26
	v_lshlrev_b32_e32 v76, 16, v27
	v_and_b32_e32 v77, 0xffff0000, v27
	v_lshlrev_b32_e32 v78, 16, v28
	v_and_b32_e32 v79, 0xffff0000, v28
	v_lshlrev_b32_e32 v80, 16, v29
	v_and_b32_e32 v81, 0xffff0000, v29
	v_lshlrev_b32_e32 v82, 16, v30
	v_and_b32_e32 v83, 0xffff0000, v30
	v_lshlrev_b32_e32 v84, 16, v31
	v_and_b32_e32 v85, 0xffff0000, v31
	v_lshlrev_b32_e32 v86, 16, v32
	v_and_b32_e32 v87, 0xffff0000, v32
	v_lshlrev_b32_e32 v88, 16, v33
	v_and_b32_e32 v89, 0xffff0000, v33
	v_lshlrev_b32_e32 v90, 16, v34
	v_and_b32_e32 v91, 0xffff0000, v34
	v_lshlrev_b32_e32 v92, 16, v35
	v_and_b32_e32 v93, 0xffff0000, v35
	v_lshlrev_b32_e32 v94, 16, v36
	v_and_b32_e32 v95, 0xffff0000, v36
	v_lshlrev_b32_e32 v96, 16, v37
	v_and_b32_e32 v97, 0xffff0000, v37
	v_lshlrev_b32_e32 v98, 16, v38
	v_and_b32_e32 v99, 0xffff0000, v38
	v_lshlrev_b32_e32 v100, 16, v39
	v_and_b32_e32 v101, 0xffff0000, v39
	v_lshlrev_b32_e32 v102, 16, v40
	v_and_b32_e32 v103, 0xffff0000, v40
	v_lshlrev_b32_e32 v104, 16, v41
	v_and_b32_e32 v105, 0xffff0000, v41
	v_lshlrev_b32_e32 v106, 16, v42
	v_and_b32_e32 v107, 0xffff0000, v42
	v_lshlrev_b32_e32 v108, 16, v43
	v_and_b32_e32 v109, 0xffff0000, v43
	v_lshlrev_b32_e32 v110, 16, v44
	v_and_b32_e32 v111, 0xffff0000, v44
	v_lshlrev_b32_e32 v112, 16, v45
	v_and_b32_e32 v113, 0xffff0000, v45
	v_lshlrev_b32_e32 v114, 16, v46
	v_and_b32_e32 v115, 0xffff0000, v46
	v_lshlrev_b32_e32 v116, 16, v47
	v_and_b32_e32 v117, 0xffff0000, v47
	v_lshlrev_b32_e32 v118, 16, v48
	v_and_b32_e32 v119, 0xffff0000, v48
	v_lshlrev_b32_e32 v120, 16, v49
	v_and_b32_e32 v121, 0xffff0000, v49
	v_lshlrev_b32_e32 v122, 16, v50
	v_and_b32_e32 v123, 0xffff0000, v50
	v_lshlrev_b32_e32 v124, 16, v51
	v_and_b32_e32 v125, 0xffff0000, v51
	v_lshlrev_b32_e32 v126, 16, v52
	v_and_b32_e32 v127, 0xffff0000, v52
	v_lshlrev_b32_e32 v128, 16, v53
	v_and_b32_e32 v129, 0xffff0000, v53
	s_cmp_lg_u32 s13, 0
	s_cbranch_scc1 .Lprep_cz
	v_mov_b32_e32 v54, 0
	v_mov_b32_e32 v55, 0
	v_mov_b32_e32 v56, 0
	v_mov_b32_e32 v57, 0
	v_mov_b32_e32 v58, 0
	v_mov_b32_e32 v59, 0
	v_mov_b32_e32 v60, 0
	v_mov_b32_e32 v61, 0
	v_mov_b32_e32 v62, 0
	v_mov_b32_e32 v63, 0
	v_mov_b32_e32 v64, 0
	v_mov_b32_e32 v65, 0
; __device__ __forceinline__ unsigned pk2(float lo, float hi) { f32x2 v = {lo, hi}; bf16x2_t b = __builtin_convertvector(v, bf16x2_t); return __builtin_bit_cast(unsigned, b); }
; __device__ __forceinline__ float bflo(unsigned u) { return __uint_as_float(u << 16); }
; __device__ __forceinline__ float bfhi(unsigned u) { return __uint_as_float(u & 0xffff0000u); }
; __device__ __forceinline__ void prep_compute(const PrepRow& d, const PrepArgs& a, int row, int lane) {
;     ...
;     { f32x4 accv = *(const f32x4*)(a.convb + 4 * lane);
; #pragma unroll
;       for (int j = 0; j < 4; ++j) { const float mk = (ts - 3 + j >= 0) ? 1.f : 0.f; const f32x4 v = {bflo(d.cv[j].x), bfhi(d.cv[j].x), bflo(d.cv[j].y), bfhi(d.cv[j].y)};
;           accv += v * mk * *(const f32x4*)(a.convw + j * 256 + 4 * lane); }
;       u32x2 w; w.x = pk2(accv[0], accv[1]); w.y = pk2(accv[2], accv[3]);
;       *(u32x2*)(a.uconv + (size_t)row * 256 + 4 * lane) = w; }
.Lprep_cz:
	v_mov_b64_e32 v[12:13], v[196:197]
	v_mov_b64_e32 v[14:15], v[198:199]
	v_pk_fma_f32 v[12:13], v[54:55], v[200:201], v[12:13]
	v_pk_fma_f32 v[14:15], v[56:57], v[202:203], v[14:15]
	v_pk_fma_f32 v[12:13], v[58:59], v[204:205], v[12:13]
	v_pk_fma_f32 v[14:15], v[60:61], v[206:207], v[14:15]
	v_pk_fma_f32 v[12:13], v[62:63], v[208:209], v[12:13]
	v_pk_fma_f32 v[14:15], v[64:65], v[210:211], v[14:15]
	v_pk_fma_f32 v[12:13], v[66:67], v[212:213], v[12:13]
	v_pk_fma_f32 v[14:15], v[68:69], v[214:215], v[14:15]
	v_cvt_pk_bf16_f32 v130, v12, v13
	v_cvt_pk_bf16_f32 v131, v14, v15
	global_store_dwordx2 v3, v[130:131], s[20:21]
	s_add_u32 s20, s20, 0x200
	s_addc_u32 s21, s21, 0
	v_mov_b64_e32 v[12:13], v[196:197]
	v_mov_b64_e32 v[14:15], v[198:199]
	v_pk_fma_f32 v[12:13], v[58:59], v[200:201], v[12:13]
	v_pk_fma_f32 v[14:15], v[60:61], v[202:203], v[14:15]
	v_pk_fma_f32 v[12:13], v[62:63], v[204:205], v[12:13]
	v_pk_fma_f32 v[14:15], v[64:65], v[206:207], v[14:15]
	v_pk_fma_f32 v[12:13], v[66:67], v[208:209], v[12:13]
	v_pk_fma_f32 v[14:15], v[68:69], v[210:211], v[14:15]
	v_pk_fma_f32 v[12:13], v[70:71], v[212:213], v[12:13]
	v_pk_fma_f32 v[14:15], v[72:73], v[214:215], v[14:15]
	v_cvt_pk_bf16_f32 v130, v12, v13
	v_cvt_pk_bf16_f32 v131, v14, v15
	global_store_dwordx2 v3, v[130:131], s[20:21]
	s_add_u32 s20, s20, 0x200
	s_addc_u32 s21, s21, 0
	v_mov_b64_e32 v[12:13], v[196:197]
	v_mov_b64_e32 v[14:15], v[198:199]
	v_pk_fma_f32 v[12:13], v[62:63], v[200:201], v[12:13]
	v_pk_fma_f32 v[14:15], v[64:65], v[202:203], v[14:15]
	v_pk_fma_f32 v[12:13], v[66:67], v[204:205], v[12:13]
	v_pk_fma_f32 v[14:15], v[68:69], v[206:207], v[14:15]
	v_pk_fma_f32 v[12:13], v[70:71], v[208:209], v[12:13]
	v_pk_fma_f32 v[14:15], v[72:73], v[210:211], v[14:15]
	v_pk_fma_f32 v[12:13], v[74:75], v[212:213], v[12:13]
	v_pk_fma_f32 v[14:15], v[76:77], v[214:215], v[14:15]
	v_cvt_pk_bf16_f32 v130, v12, v13
	v_cvt_pk_bf16_f32 v131, v14, v15
	global_store_dwordx2 v3, v[130:131], s[20:21]
	s_add_u32 s20, s20, 0x200
	s_addc_u32 s21, s21, 0
	v_mov_b64_e32 v[12:13], v[196:197]
	v_mov_b64_e32 v[14:15], v[198:199]
	v_pk_fma_f32 v[12:13], v[66:67], v[200:201], v[12:13]
	v_pk_fma_f32 v[14:15], v[68:69], v[202:203], v[14:15]
	v_pk_fma_f32 v[12:13], v[70:71], v[204:205], v[12:13]
	v_pk_fma_f32 v[14:15], v[72:73], v[206:207], v[14:15]
	v_pk_fma_f32 v[12:13], v[74:75], v[208:209], v[12:13]
	v_pk_fma_f32 v[14:15], v[76:77], v[210:211], v[14:15]
	v_pk_fma_f32 v[12:13], v[78:79], v[212:213], v[12:13]
	v_pk_fma_f32 v[14:15], v[80:81], v[214:215], v[14:15]
	v_cvt_pk_bf16_f32 v130, v12, v13
	v_cvt_pk_bf16_f32 v131, v14, v15
	global_store_dwordx2 v3, v[130:131], s[20:21]
	s_add_u32 s20, s20, 0x200
	s_addc_u32 s21, s21, 0
	v_mov_b64_e32 v[12:13], v[196:197]
	v_mov_b64_e32 v[14:15], v[198:199]
	v_pk_fma_f32 v[12:13], v[70:71], v[200:201], v[12:13]
	v_pk_fma_f32 v[14:15], v[72:73], v[202:203], v[14:15]
	v_pk_fma_f32 v[12:13], v[74:75], v[204:205], v[12:13]
	v_pk_fma_f32 v[14:15], v[76:77], v[206:207], v[14:15]
	v_pk_fma_f32 v[12:13], v[78:79], v[208:209], v[12:13]
	v_pk_fma_f32 v[14:15], v[80:81], v[210:211], v[14:15]
	v_pk_fma_f32 v[12:13], v[82:83], v[212:213], v[12:13]
	v_pk_fma_f32 v[14:15], v[84:85], v[214:215], v[14:15]
	v_cvt_pk_bf16_f32 v130, v12, v13
	v_cvt_pk_bf16_f32 v131, v14, v15
	global_store_dwordx2 v3, v[130:131], s[20:21]
	s_add_u32 s20, s20, 0x200
	s_addc_u32 s21, s21, 0
	v_mov_b64_e32 v[12:13], v[196:197]
	v_mov_b64_e32 v[14:15], v[198:199]
	v_pk_fma_f32 v[12:13], v[74:75], v[200:201], v[12:13]
	v_pk_fma_f32 v[14:15], v[76:77], v[202:203], v[14:15]
	v_pk_fma_f32 v[12:13], v[78:79], v[204:205], v[12:13]
	v_pk_fma_f32 v[14:15], v[80:81], v[206:207], v[14:15]
	v_pk_fma_f32 v[12:13], v[82:83], v[208:209], v[12:13]
	v_pk_fma_f32 v[14:15], v[84:85], v[210:211], v[14:15]
	v_pk_fma_f32 v[12:13], v[86:87], v[212:213], v[12:13]
	v_pk_fma_f32 v[14:15], v[88:89], v[214:215], v[14:15]
	v_cvt_pk_bf16_f32 v130, v12, v13
	v_cvt_pk_bf16_f32 v131, v14, v15
	global_store_dwordx2 v3, v[130:131], s[20:21]
	s_add_u32 s20, s20, 0x200
	s_addc_u32 s21, s21, 0
	v_mov_b64_e32 v[12:13], v[196:197]
	v_mov_b64_e32 v[14:15], v[198:199]
	v_pk_fma_f32 v[12:13], v[78:79], v[200:201], v[12:13]
	v_pk_fma_f32 v[14:15], v[80:81], v[202:203], v[14:15]
	v_pk_fma_f32 v[12:13], v[82:83], v[204:205], v[12:13]
	v_pk_fma_f32 v[14:15], v[84:85], v[206:207], v[14:15]
	v_pk_fma_f32 v[12:13], v[86:87], v[208:209], v[12:13]
	v_pk_fma_f32 v[14:15], v[88:89], v[210:211], v[14:15]
	v_pk_fma_f32 v[12:13], v[90:91], v[212:213], v[12:13]
	v_pk_fma_f32 v[14:15], v[92:93], v[214:215], v[14:15]
	v_cvt_pk_bf16_f32 v130, v12, v13
	v_cvt_pk_bf16_f32 v131, v14, v15
	global_store_dwordx2 v3, v[130:131], s[20:21]
	s_add_u32 s20, s20, 0x200
	s_addc_u32 s21, s21, 0
	v_mov_b64_e32 v[12:13], v[196:197]
	v_mov_b64_e32 v[14:15], v[198:199]
	v_pk_fma_f32 v[12:13], v[82:83], v[200:201], v[12:13]
	v_pk_fma_f32 v[14:15], v[84:85], v[202:203], v[14:15]
	v_pk_fma_f32 v[12:13], v[86:87], v[204:205], v[12:13]
	v_pk_fma_f32 v[14:15], v[88:89], v[206:207], v[14:15]
	v_pk_fma_f32 v[12:13], v[90:91], v[208:209], v[12:13]
	v_pk_fma_f32 v[14:15], v[92:93], v[210:211], v[14:15]
	v_pk_fma_f32 v[12:13], v[94:95], v[212:213], v[12:13]
	v_pk_fma_f32 v[14:15], v[96:97], v[214:215], v[14:15]
	v_cvt_pk_bf16_f32 v130, v12, v13
	v_cvt_pk_bf16_f32 v131, v14, v15
	global_store_dwordx2 v3, v[130:131], s[20:21]
	s_add_u32 s20, s20, 0x200
	s_addc_u32 s21, s21, 0
	v_mov_b64_e32 v[12:13], v[196:197]
	v_mov_b64_e32 v[14:15], v[198:199]
	v_pk_fma_f32 v[12:13], v[86:87], v[200:201], v[12:13]
	v_pk_fma_f32 v[14:15], v[88:89], v[202:203], v[14:15]
; __device__ __forceinline__ unsigned pk2(float lo, float hi) { f32x2 v = {lo, hi}; bf16x2_t b = __builtin_convertvector(v, bf16x2_t); return __builtin_bit_cast(unsigned, b); }
; __device__ __forceinline__ float bflo(unsigned u) { return __uint_as_float(u << 16); }
; __device__ __forceinline__ float bfhi(unsigned u) { return __uint_as_float(u & 0xffff0000u); }
; __device__ __forceinline__ void prep_compute(const PrepRow& d, const PrepArgs& a, int row, int lane) {
;     ...
;     { f32x4 accv = *(const f32x4*)(a.convb + 4 * lane);
; #pragma unroll
;       for (int j = 0; j < 4; ++j) { const float mk = (ts - 3 + j >= 0) ? 1.f : 0.f; const f32x4 v = {bflo(d.cv[j].x), bfhi(d.cv[j].x), bflo(d.cv[j].y), bfhi(d.cv[j].y)};
;           accv += v * mk * *(const f32x4*)(a.convw + j * 256 + 4 * lane); }
;       u32x2 w; w.x = pk2(accv[0], accv[1]); w.y = pk2(accv[2], accv[3]);
;       *(u32x2*)(a.uconv + (size_t)row * 256 + 4 * lane) = w; }
	v_pk_fma_f32 v[12:13], v[90:91], v[204:205], v[12:13]
	v_pk_fma_f32 v[14:15], v[92:93], v[206:207], v[14:15]
	v_pk_fma_f32 v[12:13], v[94:95], v[208:209], v[12:13]
	v_pk_fma_f32 v[14:15], v[96:97], v[210:211], v[14:15]
	v_pk_fma_f32 v[12:13], v[98:99], v[212:213], v[12:13]
	v_pk_fma_f32 v[14:15], v[100:101], v[214:215], v[14:15]
	v_cvt_pk_bf16_f32 v130, v12, v13
	v_cvt_pk_bf16_f32 v131, v14, v15
	global_store_dwordx2 v3, v[130:131], s[20:21]
	s_add_u32 s20, s20, 0x200
	s_addc_u32 s21, s21, 0
	v_mov_b64_e32 v[12:13], v[196:197]
	v_mov_b64_e32 v[14:15], v[198:199]
	v_pk_fma_f32 v[12:13], v[90:91], v[200:201], v[12:13]
	v_pk_fma_f32 v[14:15], v[92:93], v[202:203], v[14:15]
	v_pk_fma_f32 v[12:13], v[94:95], v[204:205], v[12:13]
	v_pk_fma_f32 v[14:15], v[96:97], v[206:207], v[14:15]
	v_pk_fma_f32 v[12:13], v[98:99], v[208:209], v[12:13]
	v_pk_fma_f32 v[14:15], v[100:101], v[210:211], v[14:15]
	v_pk_fma_f32 v[12:13], v[102:103], v[212:213], v[12:13]
	v_pk_fma_f32 v[14:15], v[104:105], v[214:215], v[14:15]
	v_cvt_pk_bf16_f32 v130, v12, v13
	v_cvt_pk_bf16_f32 v131, v14, v15
	global_store_dwordx2 v3, v[130:131], s[20:21]
	s_add_u32 s20, s20, 0x200
	s_addc_u32 s21, s21, 0
	v_mov_b64_e32 v[12:13], v[196:197]
	v_mov_b64_e32 v[14:15], v[198:199]
	v_pk_fma_f32 v[12:13], v[94:95], v[200:201], v[12:13]
	v_pk_fma_f32 v[14:15], v[96:97], v[202:203], v[14:15]
	v_pk_fma_f32 v[12:13], v[98:99], v[204:205], v[12:13]
	v_pk_fma_f32 v[14:15], v[100:101], v[206:207], v[14:15]
	v_pk_fma_f32 v[12:13], v[102:103], v[208:209], v[12:13]
	v_pk_fma_f32 v[14:15], v[104:105], v[210:211], v[14:15]
	v_pk_fma_f32 v[12:13], v[106:107], v[212:213], v[12:13]
	v_pk_fma_f32 v[14:15], v[108:109], v[214:215], v[14:15]
	v_cvt_pk_bf16_f32 v130, v12, v13
	v_cvt_pk_bf16_f32 v131, v14, v15
	global_store_dwordx2 v3, v[130:131], s[20:21]
	s_add_u32 s20, s20, 0x200
	s_addc_u32 s21, s21, 0
	v_mov_b64_e32 v[12:13], v[196:197]
	v_mov_b64_e32 v[14:15], v[198:199]
	v_pk_fma_f32 v[12:13], v[98:99], v[200:201], v[12:13]
	v_pk_fma_f32 v[14:15], v[100:101], v[202:203], v[14:15]
	v_pk_fma_f32 v[12:13], v[102:103], v[204:205], v[12:13]
	v_pk_fma_f32 v[14:15], v[104:105], v[206:207], v[14:15]
	v_pk_fma_f32 v[12:13], v[106:107], v[208:209], v[12:13]
	v_pk_fma_f32 v[14:15], v[108:109], v[210:211], v[14:15]
	v_pk_fma_f32 v[12:13], v[110:111], v[212:213], v[12:13]
	v_pk_fma_f32 v[14:15], v[112:113], v[214:215], v[14:15]
	v_cvt_pk_bf16_f32 v130, v12, v13
	v_cvt_pk_bf16_f32 v131, v14, v15
	global_store_dwordx2 v3, v[130:131], s[20:21]
	s_add_u32 s20, s20, 0x200
	s_addc_u32 s21, s21, 0
	v_mov_b64_e32 v[12:13], v[196:197]
	v_mov_b64_e32 v[14:15], v[198:199]
	v_pk_fma_f32 v[12:13], v[102:103], v[200:201], v[12:13]
	v_pk_fma_f32 v[14:15], v[104:105], v[202:203], v[14:15]
	v_pk_fma_f32 v[12:13], v[106:107], v[204:205], v[12:13]
	v_pk_fma_f32 v[14:15], v[108:109], v[206:207], v[14:15]
	v_pk_fma_f32 v[12:13], v[110:111], v[208:209], v[12:13]
	v_pk_fma_f32 v[14:15], v[112:113], v[210:211], v[14:15]
	v_pk_fma_f32 v[12:13], v[114:115], v[212:213], v[12:13]
	v_pk_fma_f32 v[14:15], v[116:117], v[214:215], v[14:15]
	v_cvt_pk_bf16_f32 v130, v12, v13
	v_cvt_pk_bf16_f32 v131, v14, v15
	global_store_dwordx2 v3, v[130:131], s[20:21]
	s_add_u32 s20, s20, 0x200
	s_addc_u32 s21, s21, 0
	v_mov_b64_e32 v[12:13], v[196:197]
	v_mov_b64_e32 v[14:15], v[198:199]
	v_pk_fma_f32 v[12:13], v[106:107], v[200:201], v[12:13]
	v_pk_fma_f32 v[14:15], v[108:109], v[202:203], v[14:15]
	v_pk_fma_f32 v[12:13], v[110:111], v[204:205], v[12:13]
	v_pk_fma_f32 v[14:15], v[112:113], v[206:207], v[14:15]
	v_pk_fma_f32 v[12:13], v[114:115], v[208:209], v[12:13]
	v_pk_fma_f32 v[14:15], v[116:117], v[210:211], v[14:15]
	v_pk_fma_f32 v[12:13], v[118:119], v[212:213], v[12:13]
	v_pk_fma_f32 v[14:15], v[120:121], v[214:215], v[14:15]
	v_cvt_pk_bf16_f32 v130, v12, v13
	v_cvt_pk_bf16_f32 v131, v14, v15
	global_store_dwordx2 v3, v[130:131], s[20:21]
	s_add_u32 s20, s20, 0x200
	s_addc_u32 s21, s21, 0
	v_mov_b64_e32 v[12:13], v[196:197]
	v_mov_b64_e32 v[14:15], v[198:199]
	v_pk_fma_f32 v[12:13], v[110:111], v[200:201], v[12:13]
	v_pk_fma_f32 v[14:15], v[112:113], v[202:203], v[14:15]
	v_pk_fma_f32 v[12:13], v[114:115], v[204:205], v[12:13]
	v_pk_fma_f32 v[14:15], v[116:117], v[206:207], v[14:15]
	v_pk_fma_f32 v[12:13], v[118:119], v[208:209], v[12:13]
	v_pk_fma_f32 v[14:15], v[120:121], v[210:211], v[14:15]
	v_pk_fma_f32 v[12:13], v[122:123], v[212:213], v[12:13]
	v_pk_fma_f32 v[14:15], v[124:125], v[214:215], v[14:15]
	v_cvt_pk_bf16_f32 v130, v12, v13
	v_cvt_pk_bf16_f32 v131, v14, v15
	global_store_dwordx2 v3, v[130:131], s[20:21]
	s_add_u32 s20, s20, 0x200
	s_addc_u32 s21, s21, 0
	v_mov_b64_e32 v[12:13], v[196:197]
	v_mov_b64_e32 v[14:15], v[198:199]
	v_pk_fma_f32 v[12:13], v[114:115], v[200:201], v[12:13]
	v_pk_fma_f32 v[14:15], v[116:117], v[202:203], v[14:15]
	v_pk_fma_f32 v[12:13], v[118:119], v[204:205], v[12:13]
	v_pk_fma_f32 v[14:15], v[120:121], v[206:207], v[14:15]
	v_pk_fma_f32 v[12:13], v[122:123], v[208:209], v[12:13]
	v_pk_fma_f32 v[14:15], v[124:125], v[210:211], v[14:15]
	v_pk_fma_f32 v[12:13], v[126:127], v[212:213], v[12:13]
	v_pk_fma_f32 v[14:15], v[128:129], v[214:215], v[14:15]
	v_cvt_pk_bf16_f32 v130, v12, v13
	v_cvt_pk_bf16_f32 v131, v14, v15
	global_store_dwordx2 v3, v[130:131], s[20:21]
	s_waitcnt vmcnt(16)
; __device__ __forceinline__ float bflo(unsigned u) { return __uint_as_float(u << 16); }
; __device__ __forceinline__ float bfhi(unsigned u) { return __uint_as_float(u & 0xffff0000u); }
; __device__ __forceinline__ void prep_compute(const PrepRow& d, const PrepArgs& a, int row, int lane) {
;     ...
;     { const int win = 2 << (lane >> 4); const int n = (ts + 1 < win) ? ts + 1 : win;
;       f32x4 sum = {0.f, 0.f, 0.f, 0.f};
; #pragma unroll
;       for (int i = 0; i < 16; ++i) { const float mk = (i < n) ? 1.f : 0.f; const f32x4 v = {bflo(d.pool[i].x), bfhi(d.pool[i].x), bflo(d.pool[i].y), bfhi(d.pool[i].y)}; sum += v * mk; }
;       const f32x4 self = {bflo(d.pool[0].x), bfhi(d.pool[0].x), bflo(d.pool[0].y), bfhi(d.pool[0].y)};
	v_lshlrev_b32_e32 v12, 16, v134
	v_and_b32_e32 v13, 0xffff0000, v134
	v_lshlrev_b32_e32 v14, 16, v135
	v_and_b32_e32 v15, 0xffff0000, v135
	v_lshlrev_b32_e32 v16, 16, v136
	v_and_b32_e32 v17, 0xffff0000, v136
	v_lshlrev_b32_e32 v18, 16, v137
	v_and_b32_e32 v19, 0xffff0000, v137
	v_lshlrev_b32_e32 v20, 16, v138
	v_and_b32_e32 v21, 0xffff0000, v138
	v_lshlrev_b32_e32 v22, 16, v139
	v_and_b32_e32 v23, 0xffff0000, v139
	v_lshlrev_b32_e32 v24, 16, v140
	v_and_b32_e32 v25, 0xffff0000, v140
	v_lshlrev_b32_e32 v26, 16, v141
	v_and_b32_e32 v27, 0xffff0000, v141
	v_lshlrev_b32_e32 v28, 16, v142
	v_and_b32_e32 v29, 0xffff0000, v142
	v_lshlrev_b32_e32 v30, 16, v143
	v_and_b32_e32 v31, 0xffff0000, v143
	v_lshlrev_b32_e32 v32, 16, v144
	v_and_b32_e32 v33, 0xffff0000, v144
	v_lshlrev_b32_e32 v34, 16, v145
	v_and_b32_e32 v35, 0xffff0000, v145
	v_lshlrev_b32_e32 v36, 16, v146
	v_and_b32_e32 v37, 0xffff0000, v146
	v_lshlrev_b32_e32 v38, 16, v147
	v_and_b32_e32 v39, 0xffff0000, v147
	v_lshlrev_b32_e32 v40, 16, v148
	v_and_b32_e32 v41, 0xffff0000, v148
	v_lshlrev_b32_e32 v42, 16, v149
	v_and_b32_e32 v43, 0xffff0000, v149
	v_lshlrev_b32_e32 v44, 16, v150
	v_and_b32_e32 v45, 0xffff0000, v150
	v_lshlrev_b32_e32 v46, 16, v151
	v_and_b32_e32 v47, 0xffff0000, v151
	v_lshlrev_b32_e32 v48, 16, v152
	v_and_b32_e32 v49, 0xffff0000, v152
	v_lshlrev_b32_e32 v50, 16, v153
	v_and_b32_e32 v51, 0xffff0000, v153
	v_lshlrev_b32_e32 v52, 16, v154
	v_and_b32_e32 v53, 0xffff0000, v154
	v_lshlrev_b32_e32 v54, 16, v155
	v_and_b32_e32 v55, 0xffff0000, v155
	v_lshlrev_b32_e32 v56, 16, v156
	v_and_b32_e32 v57, 0xffff0000, v156
	v_lshlrev_b32_e32 v58, 16, v157
	v_and_b32_e32 v59, 0xffff0000, v157
	v_lshlrev_b32_e32 v60, 16, v158
	v_and_b32_e32 v61, 0xffff0000, v158
	v_lshlrev_b32_e32 v62, 16, v159
	v_and_b32_e32 v63, 0xffff0000, v159
	v_lshlrev_b32_e32 v64, 16, v160
	v_and_b32_e32 v65, 0xffff0000, v160
	v_lshlrev_b32_e32 v66, 16, v161
	v_and_b32_e32 v67, 0xffff0000, v161
	v_lshlrev_b32_e32 v68, 16, v162
	v_and_b32_e32 v69, 0xffff0000, v162
	v_lshlrev_b32_e32 v70, 16, v163
	v_and_b32_e32 v71, 0xffff0000, v163
	v_lshlrev_b32_e32 v72, 16, v164
	v_and_b32_e32 v73, 0xffff0000, v164
	v_lshlrev_b32_e32 v74, 16, v165
	v_and_b32_e32 v75, 0xffff0000, v165
	v_lshlrev_b32_e32 v76, 16, v166
	v_and_b32_e32 v77, 0xffff0000, v166
	v_lshlrev_b32_e32 v78, 16, v167
	v_and_b32_e32 v79, 0xffff0000, v167
	v_lshlrev_b32_e32 v80, 16, v168
	v_and_b32_e32 v81, 0xffff0000, v168
	v_lshlrev_b32_e32 v82, 16, v169
	v_and_b32_e32 v83, 0xffff0000, v169
	v_lshlrev_b32_e32 v84, 16, v170
	v_and_b32_e32 v85, 0xffff0000, v170
	v_lshlrev_b32_e32 v86, 16, v171
	v_and_b32_e32 v87, 0xffff0000, v171
	v_lshlrev_b32_e32 v88, 16, v172
	v_and_b32_e32 v89, 0xffff0000, v172
	v_lshlrev_b32_e32 v90, 16, v173
	v_and_b32_e32 v91, 0xffff0000, v173
	v_lshlrev_b32_e32 v92, 16, v174
	v_and_b32_e32 v93, 0xffff0000, v174
	v_lshlrev_b32_e32 v94, 16, v175
	v_and_b32_e32 v95, 0xffff0000, v175
	v_lshlrev_b32_e32 v96, 16, v176
	v_and_b32_e32 v97, 0xffff0000, v176
	v_lshlrev_b32_e32 v98, 16, v177
	v_and_b32_e32 v99, 0xffff0000, v177
	v_lshlrev_b32_e32 v100, 16, v178
	v_and_b32_e32 v101, 0xffff0000, v178
	v_lshlrev_b32_e32 v102, 16, v179
	v_and_b32_e32 v103, 0xffff0000, v179
	v_lshlrev_b32_e32 v104, 16, v180
	v_and_b32_e32 v105, 0xffff0000, v180
	v_lshlrev_b32_e32 v106, 16, v181
	v_and_b32_e32 v107, 0xffff0000, v181
	v_lshlrev_b32_e32 v108, 16, v182
	v_and_b32_e32 v109, 0xffff0000, v182
	v_lshlrev_b32_e32 v110, 16, v183
	v_and_b32_e32 v111, 0xffff0000, v183
	v_lshlrev_b32_e32 v112, 16, v184
	v_and_b32_e32 v113, 0xffff0000, v184
	v_lshlrev_b32_e32 v114, 16, v185
	v_and_b32_e32 v115, 0xffff0000, v185
	v_lshlrev_b32_e32 v116, 16, v216
	v_and_b32_e32 v117, 0xffff0000, v216
	v_lshlrev_b32_e32 v118, 16, v217
	v_and_b32_e32 v119, 0xffff0000, v217
	v_lshlrev_b32_e32 v120, 16, v218
	v_and_b32_e32 v121, 0xffff0000, v218
	v_lshlrev_b32_e32 v122, 16, v219
	v_and_b32_e32 v123, 0xffff0000, v219
	v_lshlrev_b32_e32 v124, 16, v220
	v_and_b32_e32 v125, 0xffff0000, v220
	v_lshlrev_b32_e32 v126, 16, v221
	v_and_b32_e32 v127, 0xffff0000, v221
	v_lshlrev_b32_e32 v128, 16, v232
	v_and_b32_e32 v129, 0xffff0000, v232
	v_lshlrev_b32_e32 v130, 16, v233
	v_and_b32_e32 v131, 0xffff0000, v233
	v_lshlrev_b32_e32 v132, 16, v234
	v_and_b32_e32 v133, 0xffff0000, v234
	v_lshlrev_b32_e32 v236, 16, v235
	v_and_b32_e32 v237, 0xffff0000, v235
	s_cmp_lg_u32 s13, 0
	s_cbranch_scc1 .Lprep_pz
	v_mov_b32_e32 v12, 0
	v_mov_b32_e32 v13, 0
	v_mov_b32_e32 v14, 0
	v_mov_b32_e32 v15, 0
	v_mov_b32_e32 v16, 0
	v_mov_b32_e32 v17, 0
	v_mov_b32_e32 v18, 0
	v_mov_b32_e32 v19, 0
	v_mov_b32_e32 v20, 0
	v_mov_b32_e32 v21, 0
	v_mov_b32_e32 v22, 0
	v_mov_b32_e32 v23, 0
	v_mov_b32_e32 v24, 0
	v_mov_b32_e32 v25, 0
	v_mov_b32_e32 v26, 0
	v_mov_b32_e32 v27, 0
	v_mov_b32_e32 v28, 0
	v_mov_b32_e32 v29, 0
	v_mov_b32_e32 v30, 0
	v_mov_b32_e32 v31, 0
	v_mov_b32_e32 v32, 0
	v_mov_b32_e32 v33, 0
	v_mov_b32_e32 v34, 0
	v_mov_b32_e32 v35, 0
	v_mov_b32_e32 v36, 0
	v_mov_b32_e32 v37, 0
	v_mov_b32_e32 v38, 0
	v_mov_b32_e32 v39, 0
	v_mov_b32_e32 v40, 0
	v_mov_b32_e32 v41, 0
	v_mov_b32_e32 v42, 0
	v_mov_b32_e32 v43, 0
	v_mov_b32_e32 v44, 0
	v_mov_b32_e32 v45, 0
	v_mov_b32_e32 v46, 0
	v_mov_b32_e32 v47, 0
	v_mov_b32_e32 v48, 0
	v_mov_b32_e32 v49, 0
	v_mov_b32_e32 v50, 0
	v_mov_b32_e32 v51, 0
	v_mov_b32_e32 v52, 0
	v_mov_b32_e32 v53, 0
	v_mov_b32_e32 v54, 0
	v_mov_b32_e32 v55, 0
	v_mov_b32_e32 v56, 0
	v_mov_b32_e32 v57, 0
	v_mov_b32_e32 v58, 0
	v_mov_b32_e32 v59, 0
	v_mov_b32_e32 v60, 0
	v_mov_b32_e32 v61, 0
	v_mov_b32_e32 v62, 0
	v_mov_b32_e32 v63, 0
	v_mov_b32_e32 v64, 0
	v_mov_b32_e32 v65, 0
	v_mov_b32_e32 v66, 0
	v_mov_b32_e32 v67, 0
	v_mov_b32_e32 v68, 0
	v_mov_b32_e32 v69, 0
	v_mov_b32_e32 v70, 0
	v_mov_b32_e32 v71, 0
; __device__ __forceinline__ float bflo(unsigned u) { return __uint_as_float(u << 16); }
; __device__ __forceinline__ float bfhi(unsigned u) { return __uint_as_float(u & 0xffff0000u); }
; __device__ __forceinline__ void prep_compute(const PrepRow& d, const PrepArgs& a, int row, int lane) {
;     ...
;     { const int win = 2 << (lane >> 4); const int n = (ts + 1 < win) ? ts + 1 : win;
;       f32x4 sum = {0.f, 0.f, 0.f, 0.f};
; #pragma unroll
;       for (int i = 0; i < 16; ++i) { const float mk = (i < n) ? 1.f : 0.f; const f32x4 v = {bflo(d.pool[i].x), bfhi(d.pool[i].x), bflo(d.pool[i].y), bfhi(d.pool[i].y)}; sum += v * mk; }
;       const f32x4 self = {bflo(d.pool[0].x), bfhi(d.pool[0].x), bflo(d.pool[0].y), bfhi(d.pool[0].y)};
.Lprep_pz:
	v_pk_add_f32 v[132:133], v[132:133], v[128:129]
	v_pk_add_f32 v[236:237], v[236:237], v[130:131]
	v_pk_add_f32 v[128:129], v[128:129], v[124:125]
	v_pk_add_f32 v[130:131], v[130:131], v[126:127]
	v_pk_add_f32 v[124:125], v[124:125], v[120:121]
	v_pk_add_f32 v[126:127], v[126:127], v[122:123]
	v_pk_add_f32 v[120:121], v[120:121], v[116:117]
	v_pk_add_f32 v[122:123], v[122:123], v[118:119]
	v_pk_add_f32 v[116:117], v[116:117], v[112:113]
	v_pk_add_f32 v[118:119], v[118:119], v[114:115]
	v_pk_add_f32 v[112:113], v[112:113], v[108:109]
	v_pk_add_f32 v[114:115], v[114:115], v[110:111]
	v_pk_add_f32 v[108:109], v[108:109], v[104:105]
	v_pk_add_f32 v[110:111], v[110:111], v[106:107]
	v_pk_add_f32 v[104:105], v[104:105], v[100:101]
	v_pk_add_f32 v[106:107], v[106:107], v[102:103]
	v_pk_add_f32 v[100:101], v[100:101], v[96:97]
	v_pk_add_f32 v[102:103], v[102:103], v[98:99]
	v_pk_add_f32 v[96:97], v[96:97], v[92:93]
	v_pk_add_f32 v[98:99], v[98:99], v[94:95]
	v_pk_add_f32 v[92:93], v[92:93], v[88:89]
	v_pk_add_f32 v[94:95], v[94:95], v[90:91]
	v_pk_add_f32 v[88:89], v[88:89], v[84:85]
	v_pk_add_f32 v[90:91], v[90:91], v[86:87]
	v_pk_add_f32 v[84:85], v[84:85], v[80:81]
	v_pk_add_f32 v[86:87], v[86:87], v[82:83]
	v_pk_add_f32 v[80:81], v[80:81], v[76:77]
	v_pk_add_f32 v[82:83], v[82:83], v[78:79]
	v_pk_add_f32 v[76:77], v[76:77], v[72:73]
	v_pk_add_f32 v[78:79], v[78:79], v[74:75]
	v_pk_add_f32 v[72:73], v[72:73], v[68:69]
	v_pk_add_f32 v[74:75], v[74:75], v[70:71]
	v_pk_add_f32 v[68:69], v[68:69], v[64:65]
	v_pk_add_f32 v[70:71], v[70:71], v[66:67]
	v_pk_add_f32 v[64:65], v[64:65], v[60:61]
	v_pk_add_f32 v[66:67], v[66:67], v[62:63]
	v_pk_add_f32 v[60:61], v[60:61], v[56:57]
	v_pk_add_f32 v[62:63], v[62:63], v[58:59]
	v_pk_add_f32 v[56:57], v[56:57], v[52:53]
	v_pk_add_f32 v[58:59], v[58:59], v[54:55]
	v_pk_add_f32 v[52:53], v[52:53], v[48:49]
	v_pk_add_f32 v[54:55], v[54:55], v[50:51]
	v_pk_add_f32 v[48:49], v[48:49], v[44:45]
	v_pk_add_f32 v[50:51], v[50:51], v[46:47]
	v_pk_add_f32 v[44:45], v[44:45], v[40:41]
	v_pk_add_f32 v[46:47], v[46:47], v[42:43]
	v_pk_add_f32 v[40:41], v[40:41], v[36:37]
	v_pk_add_f32 v[42:43], v[42:43], v[38:39]
	v_pk_add_f32 v[36:37], v[36:37], v[32:33]
	v_pk_add_f32 v[38:39], v[38:39], v[34:35]
	v_pk_add_f32 v[32:33], v[32:33], v[28:29]
	v_pk_add_f32 v[34:35], v[34:35], v[30:31]
	v_pk_add_f32 v[28:29], v[28:29], v[24:25]
	v_pk_add_f32 v[30:31], v[30:31], v[26:27]
	v_pk_add_f32 v[24:25], v[24:25], v[20:21]
	v_pk_add_f32 v[26:27], v[26:27], v[22:23]
	v_pk_add_f32 v[20:21], v[20:21], v[16:17]
	v_pk_add_f32 v[22:23], v[22:23], v[18:19]
	v_pk_add_f32 v[16:17], v[16:17], v[12:13]
	v_pk_add_f32 v[18:19], v[18:19], v[14:15]
	s_mov_b32 exec_lo, 0xffff0000
	v_pk_add_f32 v[132:133], v[132:133], v[124:125]
	v_pk_add_f32 v[236:237], v[236:237], v[126:127]
	v_pk_add_f32 v[128:129], v[128:129], v[120:121]
	v_pk_add_f32 v[130:131], v[130:131], v[122:123]
	v_pk_add_f32 v[124:125], v[124:125], v[116:117]
	v_pk_add_f32 v[126:127], v[126:127], v[118:119]
	v_pk_add_f32 v[120:121], v[120:121], v[112:113]
	v_pk_add_f32 v[122:123], v[122:123], v[114:115]
	v_pk_add_f32 v[116:117], v[116:117], v[108:109]
	v_pk_add_f32 v[118:119], v[118:119], v[110:111]
	v_pk_add_f32 v[112:113], v[112:113], v[104:105]
	v_pk_add_f32 v[114:115], v[114:115], v[106:107]
	v_pk_add_f32 v[108:109], v[108:109], v[100:101]
	v_pk_add_f32 v[110:111], v[110:111], v[102:103]
	v_pk_add_f32 v[104:105], v[104:105], v[96:97]
	v_pk_add_f32 v[106:107], v[106:107], v[98:99]
	v_pk_add_f32 v[100:101], v[100:101], v[92:93]
	v_pk_add_f32 v[102:103], v[102:103], v[94:95]
	v_pk_add_f32 v[96:97], v[96:97], v[88:89]
	v_pk_add_f32 v[98:99], v[98:99], v[90:91]
	v_pk_add_f32 v[92:93], v[92:93], v[84:85]
	v_pk_add_f32 v[94:95], v[94:95], v[86:87]
	v_pk_add_f32 v[88:89], v[88:89], v[80:81]
	v_pk_add_f32 v[90:91], v[90:91], v[82:83]
	v_pk_add_f32 v[84:85], v[84:85], v[76:77]
	v_pk_add_f32 v[86:87], v[86:87], v[78:79]
	v_pk_add_f32 v[80:81], v[80:81], v[72:73]
	v_pk_add_f32 v[82:83], v[82:83], v[74:75]
	v_pk_add_f32 v[76:77], v[76:77], v[68:69]
	v_pk_add_f32 v[78:79], v[78:79], v[70:71]
	v_pk_add_f32 v[72:73], v[72:73], v[64:65]
	v_pk_add_f32 v[74:75], v[74:75], v[66:67]
	v_pk_add_f32 v[68:69], v[68:69], v[60:61]
	v_pk_add_f32 v[70:71], v[70:71], v[62:63]
	v_pk_add_f32 v[64:65], v[64:65], v[56:57]
	v_pk_add_f32 v[66:67], v[66:67], v[58:59]
	v_pk_add_f32 v[60:61], v[60:61], v[52:53]
	v_pk_add_f32 v[62:63], v[62:63], v[54:55]
	v_pk_add_f32 v[56:57], v[56:57], v[48:49]
	v_pk_add_f32 v[58:59], v[58:59], v[50:51]
	v_pk_add_f32 v[52:53], v[52:53], v[44:45]
	v_pk_add_f32 v[54:55], v[54:55], v[46:47]
	v_pk_add_f32 v[48:49], v[48:49], v[40:41]
	v_pk_add_f32 v[50:51], v[50:51], v[42:43]
	v_pk_add_f32 v[44:45], v[44:45], v[36:37]
	v_pk_add_f32 v[46:47], v[46:47], v[38:39]
	v_pk_add_f32 v[40:41], v[40:41], v[32:33]
	v_pk_add_f32 v[42:43], v[42:43], v[34:35]
	v_pk_add_f32 v[36:37], v[36:37], v[28:29]
	v_pk_add_f32 v[38:39], v[38:39], v[30:31]
	v_pk_add_f32 v[32:33], v[32:33], v[24:25]
	v_pk_add_f32 v[34:35], v[34:35], v[26:27]
	v_pk_add_f32 v[28:29], v[28:29], v[20:21]
	v_pk_add_f32 v[30:31], v[30:31], v[22:23]
	v_pk_add_f32 v[24:25], v[24:25], v[16:17]
	v_pk_add_f32 v[26:27], v[26:27], v[18:19]
	s_mov_b32 exec_lo, 0
	v_pk_add_f32 v[132:133], v[132:133], v[116:117]
	v_pk_add_f32 v[236:237], v[236:237], v[118:119]
	v_pk_add_f32 v[128:129], v[128:129], v[112:113]
	v_pk_add_f32 v[130:131], v[130:131], v[114:115]
	v_pk_add_f32 v[124:125], v[124:125], v[108:109]
	v_pk_add_f32 v[126:127], v[126:127], v[110:111]
	v_pk_add_f32 v[120:121], v[120:121], v[104:105]
	v_pk_add_f32 v[122:123], v[122:123], v[106:107]
; __device__ __forceinline__ unsigned pk2(float lo, float hi) { f32x2 v = {lo, hi}; bf16x2_t b = __builtin_convertvector(v, bf16x2_t); return __builtin_bit_cast(unsigned, b); }
; __device__ __forceinline__ float bflo(unsigned u) { return __uint_as_float(u << 16); }
; __device__ __forceinline__ float bfhi(unsigned u) { return __uint_as_float(u & 0xffff0000u); }
; __device__ __forceinline__ void prep_compute(const PrepRow& d, const PrepArgs& a, int row, int lane) {
;     ...
;     { const int win = 2 << (lane >> 4); const int n = (ts + 1 < win) ? ts + 1 : win;
;       f32x4 sum = {0.f, 0.f, 0.f, 0.f};
; #pragma unroll
;       for (int i = 0; i < 16; ++i) { const float mk = (i < n) ? 1.f : 0.f; const f32x4 v = {bflo(d.pool[i].x), bfhi(d.pool[i].x), bflo(d.pool[i].y), bfhi(d.pool[i].y)}; sum += v * mk; }
;       const f32x4 self = {bflo(d.pool[0].x), bfhi(d.pool[0].x), bflo(d.pool[0].y), bfhi(d.pool[0].y)};
;       const f32x4 o = sum * (1.0f / (float)n) - self;
;       u32x2 w; w.x = pk2(o[0], o[1]); w.y = pk2(o[2], o[3]);
;       *(u32x2*)(a.PM + (size_t)row * 1024 + 4 * lane) = w; }
	v_pk_add_f32 v[116:117], v[116:117], v[100:101]
	v_pk_add_f32 v[118:119], v[118:119], v[102:103]
	v_pk_add_f32 v[112:113], v[112:113], v[96:97]
	v_pk_add_f32 v[114:115], v[114:115], v[98:99]
	v_pk_add_f32 v[108:109], v[108:109], v[92:93]
	v_pk_add_f32 v[110:111], v[110:111], v[94:95]
	v_pk_add_f32 v[104:105], v[104:105], v[88:89]
	v_pk_add_f32 v[106:107], v[106:107], v[90:91]
	v_pk_add_f32 v[100:101], v[100:101], v[84:85]
	v_pk_add_f32 v[102:103], v[102:103], v[86:87]
	v_pk_add_f32 v[96:97], v[96:97], v[80:81]
	v_pk_add_f32 v[98:99], v[98:99], v[82:83]
	v_pk_add_f32 v[92:93], v[92:93], v[76:77]
	v_pk_add_f32 v[94:95], v[94:95], v[78:79]
	v_pk_add_f32 v[88:89], v[88:89], v[72:73]
	v_pk_add_f32 v[90:91], v[90:91], v[74:75]
	v_pk_add_f32 v[84:85], v[84:85], v[68:69]
	v_pk_add_f32 v[86:87], v[86:87], v[70:71]
	v_pk_add_f32 v[80:81], v[80:81], v[64:65]
	v_pk_add_f32 v[82:83], v[82:83], v[66:67]
	v_pk_add_f32 v[76:77], v[76:77], v[60:61]
	v_pk_add_f32 v[78:79], v[78:79], v[62:63]
	v_pk_add_f32 v[72:73], v[72:73], v[56:57]
	v_pk_add_f32 v[74:75], v[74:75], v[58:59]
	v_pk_add_f32 v[68:69], v[68:69], v[52:53]
	v_pk_add_f32 v[70:71], v[70:71], v[54:55]
	v_pk_add_f32 v[64:65], v[64:65], v[48:49]
	v_pk_add_f32 v[66:67], v[66:67], v[50:51]
	v_pk_add_f32 v[60:61], v[60:61], v[44:45]
	v_pk_add_f32 v[62:63], v[62:63], v[46:47]
	v_pk_add_f32 v[56:57], v[56:57], v[40:41]
	v_pk_add_f32 v[58:59], v[58:59], v[42:43]
	v_pk_add_f32 v[52:53], v[52:53], v[36:37]
	v_pk_add_f32 v[54:55], v[54:55], v[38:39]
	v_pk_add_f32 v[48:49], v[48:49], v[32:33]
	v_pk_add_f32 v[50:51], v[50:51], v[34:35]
	v_pk_add_f32 v[44:45], v[44:45], v[28:29]
	v_pk_add_f32 v[46:47], v[46:47], v[30:31]
	v_pk_add_f32 v[40:41], v[40:41], v[24:25]
	v_pk_add_f32 v[42:43], v[42:43], v[26:27]
	s_mov_b32 exec_hi, 0xffff0000
	v_pk_add_f32 v[132:133], v[132:133], v[100:101]
	v_pk_add_f32 v[236:237], v[236:237], v[102:103]
	v_pk_add_f32 v[128:129], v[128:129], v[96:97]
	v_pk_add_f32 v[130:131], v[130:131], v[98:99]
	v_pk_add_f32 v[124:125], v[124:125], v[92:93]
	v_pk_add_f32 v[126:127], v[126:127], v[94:95]
	v_pk_add_f32 v[120:121], v[120:121], v[88:89]
	v_pk_add_f32 v[122:123], v[122:123], v[90:91]
	v_pk_add_f32 v[116:117], v[116:117], v[84:85]
	v_pk_add_f32 v[118:119], v[118:119], v[86:87]
	v_pk_add_f32 v[112:113], v[112:113], v[80:81]
	v_pk_add_f32 v[114:115], v[114:115], v[82:83]
	v_pk_add_f32 v[108:109], v[108:109], v[76:77]
	v_pk_add_f32 v[110:111], v[110:111], v[78:79]
	v_pk_add_f32 v[104:105], v[104:105], v[72:73]
	v_pk_add_f32 v[106:107], v[106:107], v[74:75]
	v_pk_add_f32 v[100:101], v[100:101], v[68:69]
	v_pk_add_f32 v[102:103], v[102:103], v[70:71]
	v_pk_add_f32 v[96:97], v[96:97], v[64:65]
	v_pk_add_f32 v[98:99], v[98:99], v[66:67]
	v_pk_add_f32 v[92:93], v[92:93], v[60:61]
	v_pk_add_f32 v[94:95], v[94:95], v[62:63]
	v_pk_add_f32 v[88:89], v[88:89], v[56:57]
	v_pk_add_f32 v[90:91], v[90:91], v[58:59]
	v_pk_add_f32 v[84:85], v[84:85], v[52:53]
	v_pk_add_f32 v[86:87], v[86:87], v[54:55]
	v_pk_add_f32 v[80:81], v[80:81], v[48:49]
	v_pk_add_f32 v[82:83], v[82:83], v[50:51]
	v_pk_add_f32 v[76:77], v[76:77], v[44:45]
	v_pk_add_f32 v[78:79], v[78:79], v[46:47]
	v_pk_add_f32 v[72:73], v[72:73], v[40:41]
	v_pk_add_f32 v[74:75], v[74:75], v[42:43]
	s_mov_b32 exec_lo, -1
	s_mov_b32 exec_hi, -1
	s_add_i32 s13, s13, 1
	v_min_u32_e32 v196, s13, v4
	v_cvt_f32_u32_e32 v196, v196
	v_rcp_f32_e32 v196, v196
	v_lshlrev_b32_e32 v198, 16, v164
	v_and_b32_e32 v199, 0xffff0000, v164
	v_lshlrev_b32_e32 v200, 16, v165
	v_and_b32_e32 v201, 0xffff0000, v165
	v_pk_fma_f32 v[202:203], v[72:73], v[196:197], v[198:199] op_sel_hi:[1,0,1] neg_lo:[0,0,1] neg_hi:[0,0,1]
	v_pk_fma_f32 v[204:205], v[74:75], v[196:197], v[200:201] op_sel_hi:[1,0,1] neg_lo:[0,0,1] neg_hi:[0,0,1]
	v_cvt_pk_bf16_f32 v206, v202, v203
	v_cvt_pk_bf16_f32 v207, v204, v205
	global_store_dwordx2 v3, v[206:207], s[44:45]
	s_add_i32 s13, s13, 1
	s_add_u32 s44, s44, 0x800
	s_addc_u32 s45, s45, 0
	v_min_u32_e32 v196, s13, v4
	v_cvt_f32_u32_e32 v196, v196
	v_rcp_f32_e32 v196, v196
	v_lshlrev_b32_e32 v198, 16, v166
	v_and_b32_e32 v199, 0xffff0000, v166
	v_lshlrev_b32_e32 v200, 16, v167
	v_and_b32_e32 v201, 0xffff0000, v167
	v_pk_fma_f32 v[202:203], v[76:77], v[196:197], v[198:199] op_sel_hi:[1,0,1] neg_lo:[0,0,1] neg_hi:[0,0,1]
	v_pk_fma_f32 v[204:205], v[78:79], v[196:197], v[200:201] op_sel_hi:[1,0,1] neg_lo:[0,0,1] neg_hi:[0,0,1]
	v_cvt_pk_bf16_f32 v206, v202, v203
	v_cvt_pk_bf16_f32 v207, v204, v205
	global_store_dwordx2 v3, v[206:207], s[44:45]
	s_add_i32 s13, s13, 1
	s_add_u32 s44, s44, 0x800
	s_addc_u32 s45, s45, 0
	v_min_u32_e32 v196, s13, v4
	v_cvt_f32_u32_e32 v196, v196
	v_rcp_f32_e32 v196, v196
	v_lshlrev_b32_e32 v198, 16, v168
	v_and_b32_e32 v199, 0xffff0000, v168
	v_lshlrev_b32_e32 v200, 16, v169
	v_and_b32_e32 v201, 0xffff0000, v169
	v_pk_fma_f32 v[202:203], v[80:81], v[196:197], v[198:199] op_sel_hi:[1,0,1] neg_lo:[0,0,1] neg_hi:[0,0,1]
	v_pk_fma_f32 v[204:205], v[82:83], v[196:197], v[200:201] op_sel_hi:[1,0,1] neg_lo:[0,0,1] neg_hi:[0,0,1]
	v_cvt_pk_bf16_f32 v206, v202, v203
	v_cvt_pk_bf16_f32 v207, v204, v205
	global_store_dwordx2 v3, v[206:207], s[44:45]
	s_add_i32 s13, s13, 1
	s_add_u32 s44, s44, 0x800
	s_addc_u32 s45, s45, 0
	v_min_u32_e32 v196, s13, v4
	v_cvt_f32_u32_e32 v196, v196
	v_rcp_f32_e32 v196, v196
	v_lshlrev_b32_e32 v198, 16, v170
	v_and_b32_e32 v199, 0xffff0000, v170
	v_lshlrev_b32_e32 v200, 16, v171
	v_and_b32_e32 v201, 0xffff0000, v171
	v_pk_fma_f32 v[202:203], v[84:85], v[196:197], v[198:199] op_sel_hi:[1,0,1] neg_lo:[0,0,1] neg_hi:[0,0,1]
	v_pk_fma_f32 v[204:205], v[86:87], v[196:197], v[200:201] op_sel_hi:[1,0,1] neg_lo:[0,0,1] neg_hi:[0,0,1]
; __device__ __forceinline__ unsigned pk2(float lo, float hi) { f32x2 v = {lo, hi}; bf16x2_t b = __builtin_convertvector(v, bf16x2_t); return __builtin_bit_cast(unsigned, b); }
; __device__ __forceinline__ float bflo(unsigned u) { return __uint_as_float(u << 16); }
; __device__ __forceinline__ float bfhi(unsigned u) { return __uint_as_float(u & 0xffff0000u); }
; __device__ __forceinline__ void prep_compute(const PrepRow& d, const PrepArgs& a, int row, int lane) {
;     ...
;     { const int win = 2 << (lane >> 4); const int n = (ts + 1 < win) ? ts + 1 : win;
;       f32x4 sum = {0.f, 0.f, 0.f, 0.f};
; #pragma unroll
;       for (int i = 0; i < 16; ++i) { const float mk = (i < n) ? 1.f : 0.f; const f32x4 v = {bflo(d.pool[i].x), bfhi(d.pool[i].x), bflo(d.pool[i].y), bfhi(d.pool[i].y)}; sum += v * mk; }
;       const f32x4 self = {bflo(d.pool[0].x), bfhi(d.pool[0].x), bflo(d.pool[0].y), bfhi(d.pool[0].y)};
;       const f32x4 o = sum * (1.0f / (float)n) - self;
;       u32x2 w; w.x = pk2(o[0], o[1]); w.y = pk2(o[2], o[3]);
;       *(u32x2*)(a.PM + (size_t)row * 1024 + 4 * lane) = w; }
	v_cvt_pk_bf16_f32 v206, v202, v203
	v_cvt_pk_bf16_f32 v207, v204, v205
	global_store_dwordx2 v3, v[206:207], s[44:45]
	s_add_i32 s13, s13, 1
	s_add_u32 s44, s44, 0x800
	s_addc_u32 s45, s45, 0
	v_min_u32_e32 v196, s13, v4
	v_cvt_f32_u32_e32 v196, v196
	v_rcp_f32_e32 v196, v196
	v_lshlrev_b32_e32 v198, 16, v172
	v_and_b32_e32 v199, 0xffff0000, v172
	v_lshlrev_b32_e32 v200, 16, v173
	v_and_b32_e32 v201, 0xffff0000, v173
	v_pk_fma_f32 v[202:203], v[88:89], v[196:197], v[198:199] op_sel_hi:[1,0,1] neg_lo:[0,0,1] neg_hi:[0,0,1]
	v_pk_fma_f32 v[204:205], v[90:91], v[196:197], v[200:201] op_sel_hi:[1,0,1] neg_lo:[0,0,1] neg_hi:[0,0,1]
	v_cvt_pk_bf16_f32 v206, v202, v203
	v_cvt_pk_bf16_f32 v207, v204, v205
	global_store_dwordx2 v3, v[206:207], s[44:45]
	s_add_i32 s13, s13, 1
	s_add_u32 s44, s44, 0x800
	s_addc_u32 s45, s45, 0
	v_min_u32_e32 v196, s13, v4
	v_cvt_f32_u32_e32 v196, v196
	v_rcp_f32_e32 v196, v196
	v_lshlrev_b32_e32 v198, 16, v174
	v_and_b32_e32 v199, 0xffff0000, v174
	v_lshlrev_b32_e32 v200, 16, v175
	v_and_b32_e32 v201, 0xffff0000, v175
	v_pk_fma_f32 v[202:203], v[92:93], v[196:197], v[198:199] op_sel_hi:[1,0,1] neg_lo:[0,0,1] neg_hi:[0,0,1]
	v_pk_fma_f32 v[204:205], v[94:95], v[196:197], v[200:201] op_sel_hi:[1,0,1] neg_lo:[0,0,1] neg_hi:[0,0,1]
	v_cvt_pk_bf16_f32 v206, v202, v203
	v_cvt_pk_bf16_f32 v207, v204, v205
	global_store_dwordx2 v3, v[206:207], s[44:45]
	s_add_i32 s13, s13, 1
	s_add_u32 s44, s44, 0x800
	s_addc_u32 s45, s45, 0
	v_min_u32_e32 v196, s13, v4
	v_cvt_f32_u32_e32 v196, v196
	v_rcp_f32_e32 v196, v196
	v_lshlrev_b32_e32 v198, 16, v176
	v_and_b32_e32 v199, 0xffff0000, v176
	v_lshlrev_b32_e32 v200, 16, v177
	v_and_b32_e32 v201, 0xffff0000, v177
	v_pk_fma_f32 v[202:203], v[96:97], v[196:197], v[198:199] op_sel_hi:[1,0,1] neg_lo:[0,0,1] neg_hi:[0,0,1]
	v_pk_fma_f32 v[204:205], v[98:99], v[196:197], v[200:201] op_sel_hi:[1,0,1] neg_lo:[0,0,1] neg_hi:[0,0,1]
	v_cvt_pk_bf16_f32 v206, v202, v203
	v_cvt_pk_bf16_f32 v207, v204, v205
	global_store_dwordx2 v3, v[206:207], s[44:45]
	s_add_i32 s13, s13, 1
	s_add_u32 s44, s44, 0x800
	s_addc_u32 s45, s45, 0
	v_min_u32_e32 v196, s13, v4
	v_cvt_f32_u32_e32 v196, v196
	v_rcp_f32_e32 v196, v196
	v_lshlrev_b32_e32 v198, 16, v178
	v_and_b32_e32 v199, 0xffff0000, v178
	v_lshlrev_b32_e32 v200, 16, v179
	v_and_b32_e32 v201, 0xffff0000, v179
	v_pk_fma_f32 v[202:203], v[100:101], v[196:197], v[198:199] op_sel_hi:[1,0,1] neg_lo:[0,0,1] neg_hi:[0,0,1]
	v_pk_fma_f32 v[204:205], v[102:103], v[196:197], v[200:201] op_sel_hi:[1,0,1] neg_lo:[0,0,1] neg_hi:[0,0,1]
	v_cvt_pk_bf16_f32 v206, v202, v203
	v_cvt_pk_bf16_f32 v207, v204, v205
	global_store_dwordx2 v3, v[206:207], s[44:45]
	s_add_i32 s13, s13, 1
	s_add_u32 s44, s44, 0x800
	s_addc_u32 s45, s45, 0
	v_min_u32_e32 v196, s13, v4
	v_cvt_f32_u32_e32 v196, v196
	v_rcp_f32_e32 v196, v196
	v_lshlrev_b32_e32 v198, 16, v180
	v_and_b32_e32 v199, 0xffff0000, v180
	v_lshlrev_b32_e32 v200, 16, v181
	v_and_b32_e32 v201, 0xffff0000, v181
	v_pk_fma_f32 v[202:203], v[104:105], v[196:197], v[198:199] op_sel_hi:[1,0,1] neg_lo:[0,0,1] neg_hi:[0,0,1]
	v_pk_fma_f32 v[204:205], v[106:107], v[196:197], v[200:201] op_sel_hi:[1,0,1] neg_lo:[0,0,1] neg_hi:[0,0,1]
	v_cvt_pk_bf16_f32 v206, v202, v203
	v_cvt_pk_bf16_f32 v207, v204, v205
	global_store_dwordx2 v3, v[206:207], s[44:45]
	s_add_i32 s13, s13, 1
	s_add_u32 s44, s44, 0x800
	s_addc_u32 s45, s45, 0
	v_min_u32_e32 v196, s13, v4
	v_cvt_f32_u32_e32 v196, v196
	v_rcp_f32_e32 v196, v196
	v_lshlrev_b32_e32 v198, 16, v182
	v_and_b32_e32 v199, 0xffff0000, v182
	v_lshlrev_b32_e32 v200, 16, v183
	v_and_b32_e32 v201, 0xffff0000, v183
	v_pk_fma_f32 v[202:203], v[108:109], v[196:197], v[198:199] op_sel_hi:[1,0,1] neg_lo:[0,0,1] neg_hi:[0,0,1]
	v_pk_fma_f32 v[204:205], v[110:111], v[196:197], v[200:201] op_sel_hi:[1,0,1] neg_lo:[0,0,1] neg_hi:[0,0,1]
	v_cvt_pk_bf16_f32 v206, v202, v203
	v_cvt_pk_bf16_f32 v207, v204, v205
	global_store_dwordx2 v3, v[206:207], s[44:45]
	s_add_i32 s13, s13, 1
	s_add_u32 s44, s44, 0x800
	s_addc_u32 s45, s45, 0
	v_min_u32_e32 v196, s13, v4
	v_cvt_f32_u32_e32 v196, v196
	v_rcp_f32_e32 v196, v196
	v_lshlrev_b32_e32 v198, 16, v184
	v_and_b32_e32 v199, 0xffff0000, v184
	v_lshlrev_b32_e32 v200, 16, v185
	v_and_b32_e32 v201, 0xffff0000, v185
	v_pk_fma_f32 v[202:203], v[112:113], v[196:197], v[198:199] op_sel_hi:[1,0,1] neg_lo:[0,0,1] neg_hi:[0,0,1]
	v_pk_fma_f32 v[204:205], v[114:115], v[196:197], v[200:201] op_sel_hi:[1,0,1] neg_lo:[0,0,1] neg_hi:[0,0,1]
	v_cvt_pk_bf16_f32 v206, v202, v203
	v_cvt_pk_bf16_f32 v207, v204, v205
	global_store_dwordx2 v3, v[206:207], s[44:45]
	s_add_i32 s13, s13, 1
	s_add_u32 s44, s44, 0x800
	s_addc_u32 s45, s45, 0
	v_min_u32_e32 v196, s13, v4
	v_cvt_f32_u32_e32 v196, v196
	v_rcp_f32_e32 v196, v196
	v_lshlrev_b32_e32 v198, 16, v216
	v_and_b32_e32 v199, 0xffff0000, v216
	v_lshlrev_b32_e32 v200, 16, v217
	v_and_b32_e32 v201, 0xffff0000, v217
	v_pk_fma_f32 v[202:203], v[116:117], v[196:197], v[198:199] op_sel_hi:[1,0,1] neg_lo:[0,0,1] neg_hi:[0,0,1]
	v_pk_fma_f32 v[204:205], v[118:119], v[196:197], v[200:201] op_sel_hi:[1,0,1] neg_lo:[0,0,1] neg_hi:[0,0,1]
	v_cvt_pk_bf16_f32 v206, v202, v203
	v_cvt_pk_bf16_f32 v207, v204, v205
	global_store_dwordx2 v3, v[206:207], s[44:45]
	s_add_i32 s13, s13, 1
	s_add_u32 s44, s44, 0x800
	s_addc_u32 s45, s45, 0
	v_min_u32_e32 v196, s13, v4
	v_cvt_f32_u32_e32 v196, v196
	v_rcp_f32_e32 v196, v196
	v_lshlrev_b32_e32 v198, 16, v218
	v_and_b32_e32 v199, 0xffff0000, v218
	v_lshlrev_b32_e32 v200, 16, v219
	v_and_b32_e32 v201, 0xffff0000, v219
	v_pk_fma_f32 v[202:203], v[120:121], v[196:197], v[198:199] op_sel_hi:[1,0,1] neg_lo:[0,0,1] neg_hi:[0,0,1]
; __device__ __forceinline__ unsigned pk2(float lo, float hi) { f32x2 v = {lo, hi}; bf16x2_t b = __builtin_convertvector(v, bf16x2_t); return __builtin_bit_cast(unsigned, b); }
; __device__ __forceinline__ void prep_load(PrepRow& d, const PrepArgs& a, int row, int lane) {
;     const bf16_t* pr = a.PA + (size_t)row * PA_LD; const int ts = row & (SEQ - 1);
;     { const int fi = ((lane & 7) * 4) & 15; d.r1 = *(const u32x2*)(pr + 896 + fi); d.r2 = *(const u32x2*)(pr + 912 + fi);
;       d.c = *(const f32x4*)(a.cs + ts * 16 + fi); d.s = *(const f32x4*)(a.sn + ts * 16 + fi); }
; __device__ __forceinline__ void prep_compute(const PrepRow& d, const PrepArgs& a, int row, int lane) {
;     ...
;       const f32x4 o = sum * (1.0f / (float)n) - self;
;       u32x2 w; w.x = pk2(o[0], o[1]); w.y = pk2(o[2], o[3]);
;       *(u32x2*)(a.PM + (size_t)row * 1024 + 4 * lane) = w; }
	v_pk_fma_f32 v[204:205], v[122:123], v[196:197], v[200:201] op_sel_hi:[1,0,1] neg_lo:[0,0,1] neg_hi:[0,0,1]
	v_cvt_pk_bf16_f32 v206, v202, v203
	v_cvt_pk_bf16_f32 v207, v204, v205
	global_store_dwordx2 v3, v[206:207], s[44:45]
	s_add_i32 s13, s13, 1
	s_add_u32 s44, s44, 0x800
	s_addc_u32 s45, s45, 0
	v_min_u32_e32 v196, s13, v4
	v_cvt_f32_u32_e32 v196, v196
	v_rcp_f32_e32 v196, v196
	v_lshlrev_b32_e32 v198, 16, v220
	v_and_b32_e32 v199, 0xffff0000, v220
	v_lshlrev_b32_e32 v200, 16, v221
	v_and_b32_e32 v201, 0xffff0000, v221
	v_pk_fma_f32 v[202:203], v[124:125], v[196:197], v[198:199] op_sel_hi:[1,0,1] neg_lo:[0,0,1] neg_hi:[0,0,1]
	v_pk_fma_f32 v[204:205], v[126:127], v[196:197], v[200:201] op_sel_hi:[1,0,1] neg_lo:[0,0,1] neg_hi:[0,0,1]
	v_cvt_pk_bf16_f32 v206, v202, v203
	v_cvt_pk_bf16_f32 v207, v204, v205
	global_store_dwordx2 v3, v[206:207], s[44:45]
	s_add_i32 s13, s13, 1
	s_add_u32 s44, s44, 0x800
	s_addc_u32 s45, s45, 0
	v_min_u32_e32 v196, s13, v4
	v_cvt_f32_u32_e32 v196, v196
	v_rcp_f32_e32 v196, v196
	v_lshlrev_b32_e32 v198, 16, v232
	v_and_b32_e32 v199, 0xffff0000, v232
	v_lshlrev_b32_e32 v200, 16, v233
	v_and_b32_e32 v201, 0xffff0000, v233
	v_pk_fma_f32 v[202:203], v[128:129], v[196:197], v[198:199] op_sel_hi:[1,0,1] neg_lo:[0,0,1] neg_hi:[0,0,1]
	v_pk_fma_f32 v[204:205], v[130:131], v[196:197], v[200:201] op_sel_hi:[1,0,1] neg_lo:[0,0,1] neg_hi:[0,0,1]
	v_cvt_pk_bf16_f32 v206, v202, v203
	v_cvt_pk_bf16_f32 v207, v204, v205
	global_store_dwordx2 v3, v[206:207], s[44:45]
	s_add_i32 s13, s13, 1
	s_add_u32 s44, s44, 0x800
	s_addc_u32 s45, s45, 0
	v_min_u32_e32 v196, s13, v4
	v_cvt_f32_u32_e32 v196, v196
	v_rcp_f32_e32 v196, v196
	v_lshlrev_b32_e32 v198, 16, v234
	v_and_b32_e32 v199, 0xffff0000, v234
	v_lshlrev_b32_e32 v200, 16, v235
	v_and_b32_e32 v201, 0xffff0000, v235
	v_pk_fma_f32 v[202:203], v[132:133], v[196:197], v[198:199] op_sel_hi:[1,0,1] neg_lo:[0,0,1] neg_hi:[0,0,1]
	v_pk_fma_f32 v[204:205], v[236:237], v[196:197], v[200:201] op_sel_hi:[1,0,1] neg_lo:[0,0,1] neg_hi:[0,0,1]
	v_cvt_pk_bf16_f32 v206, v202, v203
	v_cvt_pk_bf16_f32 v207, v204, v205
	global_store_dwordx2 v3, v[206:207], s[44:45]
	s_add_i32 s13, s13, 1
	global_load_dwordx2 v[12:13], v6, s[30:31]
	global_load_dwordx2 v[14:15], v6, s[30:31] offset:32
	global_load_dwordx4 v[16:19], v7, s[36:37] offset:0
	global_load_dwordx4 v[20:23], v7, s[40:41] offset:0
	s_add_u32 s30, s30, 0xa00
	s_addc_u32 s31, s31, 0
	s_nop 0
	global_load_dwordx2 v[24:25], v6, s[30:31]
	global_load_dwordx2 v[26:27], v6, s[30:31] offset:32
	global_load_dwordx4 v[28:31], v7, s[36:37] offset:64
	global_load_dwordx4 v[32:35], v7, s[40:41] offset:64
	s_add_u32 s30, s30, 0xa00
	s_addc_u32 s31, s31, 0
	s_nop 0
	global_load_dwordx2 v[36:37], v6, s[30:31]
	global_load_dwordx2 v[38:39], v6, s[30:31] offset:32
	global_load_dwordx4 v[40:43], v7, s[36:37] offset:128
	global_load_dwordx4 v[44:47], v7, s[40:41] offset:128
	s_add_u32 s30, s30, 0xa00
	s_addc_u32 s31, s31, 0
	s_nop 0
	global_load_dwordx2 v[48:49], v6, s[30:31]
	global_load_dwordx2 v[50:51], v6, s[30:31] offset:32
	global_load_dwordx4 v[52:55], v7, s[36:37] offset:192
	global_load_dwordx4 v[56:59], v7, s[40:41] offset:192
	s_add_u32 s30, s30, 0xa00
	s_addc_u32 s31, s31, 0
	s_nop 0
	global_load_dwordx2 v[60:61], v6, s[30:31]
	global_load_dwordx2 v[62:63], v6, s[30:31] offset:32
	global_load_dwordx4 v[64:67], v7, s[36:37] offset:256
	global_load_dwordx4 v[68:71], v7, s[40:41] offset:256
	s_add_u32 s30, s30, 0xa00
	s_addc_u32 s31, s31, 0
	s_nop 0
	global_load_dwordx2 v[72:73], v6, s[30:31]
	global_load_dwordx2 v[74:75], v6, s[30:31] offset:32
	global_load_dwordx4 v[76:79], v7, s[36:37] offset:320
	global_load_dwordx4 v[80:83], v7, s[40:41] offset:320
	s_add_u32 s30, s30, 0xa00
	s_addc_u32 s31, s31, 0
	s_nop 0
	global_load_dwordx2 v[84:85], v6, s[30:31]
	global_load_dwordx2 v[86:87], v6, s[30:31] offset:32
	global_load_dwordx4 v[88:91], v7, s[36:37] offset:384
	global_load_dwordx4 v[92:95], v7, s[40:41] offset:384
	s_add_u32 s30, s30, 0xa00
	s_addc_u32 s31, s31, 0
	s_nop 0
	global_load_dwordx2 v[96:97], v6, s[30:31]
	global_load_dwordx2 v[98:99], v6, s[30:31] offset:32
	global_load_dwordx4 v[100:103], v7, s[36:37] offset:448
	global_load_dwordx4 v[104:107], v7, s[40:41] offset:448
	s_add_u32 s30, s30, 0xa00
	s_addc_u32 s31, s31, 0
	s_nop 0
	global_load_dwordx2 v[108:109], v6, s[30:31]
	global_load_dwordx2 v[110:111], v6, s[30:31] offset:32
	global_load_dwordx4 v[112:115], v7, s[36:37] offset:512
	global_load_dwordx4 v[116:119], v7, s[40:41] offset:512
	s_add_u32 s30, s30, 0xa00
	s_addc_u32 s31, s31, 0
	s_nop 0
	global_load_dwordx2 v[120:121], v6, s[30:31]
	global_load_dwordx2 v[122:123], v6, s[30:31] offset:32
	global_load_dwordx4 v[124:127], v7, s[36:37] offset:576
	global_load_dwordx4 v[128:131], v7, s[40:41] offset:576
	s_add_u32 s30, s30, 0xa00
	s_addc_u32 s31, s31, 0
	s_nop 0
	global_load_dwordx2 v[132:133], v6, s[30:31]
	global_load_dwordx2 v[134:135], v6, s[30:31] offset:32
	global_load_dwordx4 v[136:139], v7, s[36:37] offset:640
	global_load_dwordx4 v[140:143], v7, s[40:41] offset:640
	s_add_u32 s30, s30, 0xa00
	s_addc_u32 s31, s31, 0
	s_nop 0
	global_load_dwordx2 v[144:145], v6, s[30:31]
	global_load_dwordx2 v[146:147], v6, s[30:31] offset:32
	global_load_dwordx4 v[148:151], v7, s[36:37] offset:704
	global_load_dwordx4 v[152:155], v7, s[40:41] offset:704
	s_add_u32 s30, s30, 0xa00
	s_addc_u32 s31, s31, 0
	s_nop 0
	global_load_dwordx2 v[156:157], v6, s[30:31]
	global_load_dwordx2 v[158:159], v6, s[30:31] offset:32
	global_load_dwordx4 v[160:163], v7, s[36:37] offset:768
	global_load_dwordx4 v[164:167], v7, s[40:41] offset:768
	s_add_u32 s30, s30, 0xa00
	s_addc_u32 s31, s31, 0
	s_nop 0
	global_load_dwordx2 v[168:169], v6, s[30:31]
	global_load_dwordx2 v[170:171], v6, s[30:31] offset:32
	global_load_dwordx4 v[172:175], v7, s[36:37] offset:832
	global_load_dwordx4 v[176:179], v7, s[40:41] offset:832
	s_add_u32 s30, s30, 0xa00
	s_addc_u32 s31, s31, 0
	s_nop 0
	global_load_dwordx2 v[196:197], v6, s[30:31]
	global_load_dwordx2 v[198:199], v6, s[30:31] offset:32
	global_load_dwordx4 v[200:203], v7, s[36:37] offset:896
	global_load_dwordx4 v[204:207], v7, s[40:41] offset:896
	s_add_u32 s30, s30, 0xa00
	s_addc_u32 s31, s31, 0
	s_nop 0
	global_load_dwordx2 v[208:209], v6, s[30:31]
	global_load_dwordx2 v[210:211], v6, s[30:31] offset:32
	global_load_dwordx4 v[212:215], v7, s[36:37] offset:960
	global_load_dwordx4 v[216:219], v7, s[40:41] offset:960
	s_waitcnt vmcnt(0)
; __device__ __forceinline__ unsigned pk2(float lo, float hi) { f32x2 v = {lo, hi}; bf16x2_t b = __builtin_convertvector(v, bf16x2_t); return __builtin_bit_cast(unsigned, b); }
; __device__ __forceinline__ float bflo(unsigned u) { return __uint_as_float(u << 16); }
; __device__ __forceinline__ float bfhi(unsigned u) { return __uint_as_float(u & 0xffff0000u); }
; __device__ __forceinline__ void prep_compute(const PrepRow& d, const PrepArgs& a, int row, int lane) {
;     ...
;     { const int hh = lane >> 3, jj = (lane & 7) * 4;
;       const f32x4 x1 = {bflo(d.r1.x), bfhi(d.r1.x), bflo(d.r1.y), bfhi(d.r1.y)}, x2 = {bflo(d.r2.x), bfhi(d.r2.x), bflo(d.r2.y), bfhi(d.r2.y)};
;       const f32x4 o = (jj < 16) ? (x1 * d.c - x2 * d.s) : (x2 * d.c + x1 * d.s);
;       u32x2 w; w.x = pk2(o[0], o[1]); w.y = pk2(o[2], o[3]);
;       *(u32x2*)(a.Kb + (size_t)row * 768 + hh * 96 + 64 + jj) = w; }
	v_lshlrev_b32_e32 v232, 16, v12
	v_and_b32_e32 v233, 0xffff0000, v12
	v_lshlrev_b32_e32 v234, 16, v13
	v_and_b32_e32 v235, 0xffff0000, v13
	v_lshlrev_b32_e32 v246, 16, v14
	v_and_b32_e32 v247, 0xffff0000, v14
	v_lshlrev_b32_e32 v248, 16, v15
	v_and_b32_e32 v249, 0xffff0000, v15
	v_pk_mul_f32 v[180:181], v[232:233], v[16:17]
	v_pk_mul_f32 v[182:183], v[234:235], v[18:19]
	v_pk_mul_f32 v[184:185], v[232:233], v[20:21]
	v_pk_mul_f32 v[250:251], v[234:235], v[22:23]
	v_pk_fma_f32 v[180:181], v[246:247], v[20:21], v[180:181] neg_lo:[1,0,0] neg_hi:[1,0,0]
	v_pk_fma_f32 v[182:183], v[248:249], v[22:23], v[182:183] neg_lo:[1,0,0] neg_hi:[1,0,0]
	v_pk_fma_f32 v[184:185], v[246:247], v[16:17], v[184:185]
	v_pk_fma_f32 v[250:251], v[248:249], v[18:19], v[250:251]
	v_cndmask_b32_e64 v180, v184, v180, s[38:39]
	v_cndmask_b32_e64 v181, v185, v181, s[38:39]
	v_cndmask_b32_e64 v182, v250, v182, s[38:39]
	v_cndmask_b32_e64 v183, v251, v183, s[38:39]
	v_cvt_pk_bf16_f32 v236, v180, v181
	v_cvt_pk_bf16_f32 v237, v182, v183
	global_store_dwordx2 v8, v[236:237], s[42:43]
	s_add_u32 s42, s42, 0x600
	s_addc_u32 s43, s43, 0
	v_lshlrev_b32_e32 v232, 16, v24
	v_and_b32_e32 v233, 0xffff0000, v24
	v_lshlrev_b32_e32 v234, 16, v25
	v_and_b32_e32 v235, 0xffff0000, v25
	v_lshlrev_b32_e32 v246, 16, v26
	v_and_b32_e32 v247, 0xffff0000, v26
	v_lshlrev_b32_e32 v248, 16, v27
	v_and_b32_e32 v249, 0xffff0000, v27
	v_pk_mul_f32 v[180:181], v[232:233], v[28:29]
	v_pk_mul_f32 v[182:183], v[234:235], v[30:31]
	v_pk_mul_f32 v[184:185], v[232:233], v[32:33]
	v_pk_mul_f32 v[250:251], v[234:235], v[34:35]
	v_pk_fma_f32 v[180:181], v[246:247], v[32:33], v[180:181] neg_lo:[1,0,0] neg_hi:[1,0,0]
	v_pk_fma_f32 v[182:183], v[248:249], v[34:35], v[182:183] neg_lo:[1,0,0] neg_hi:[1,0,0]
	v_pk_fma_f32 v[184:185], v[246:247], v[28:29], v[184:185]
	v_pk_fma_f32 v[250:251], v[248:249], v[30:31], v[250:251]
	v_cndmask_b32_e64 v180, v184, v180, s[38:39]
	v_cndmask_b32_e64 v181, v185, v181, s[38:39]
	v_cndmask_b32_e64 v182, v250, v182, s[38:39]
	v_cndmask_b32_e64 v183, v251, v183, s[38:39]
	v_cvt_pk_bf16_f32 v236, v180, v181
	v_cvt_pk_bf16_f32 v237, v182, v183
	global_store_dwordx2 v8, v[236:237], s[42:43]
	s_add_u32 s42, s42, 0x600
	s_addc_u32 s43, s43, 0
	v_lshlrev_b32_e32 v232, 16, v36
	v_and_b32_e32 v233, 0xffff0000, v36
	v_lshlrev_b32_e32 v234, 16, v37
	v_and_b32_e32 v235, 0xffff0000, v37
	v_lshlrev_b32_e32 v246, 16, v38
	v_and_b32_e32 v247, 0xffff0000, v38
	v_lshlrev_b32_e32 v248, 16, v39
	v_and_b32_e32 v249, 0xffff0000, v39
	v_pk_mul_f32 v[180:181], v[232:233], v[40:41]
	v_pk_mul_f32 v[182:183], v[234:235], v[42:43]
	v_pk_mul_f32 v[184:185], v[232:233], v[44:45]
	v_pk_mul_f32 v[250:251], v[234:235], v[46:47]
	v_pk_fma_f32 v[180:181], v[246:247], v[44:45], v[180:181] neg_lo:[1,0,0] neg_hi:[1,0,0]
	v_pk_fma_f32 v[182:183], v[248:249], v[46:47], v[182:183] neg_lo:[1,0,0] neg_hi:[1,0,0]
	v_pk_fma_f32 v[184:185], v[246:247], v[40:41], v[184:185]
	v_pk_fma_f32 v[250:251], v[248:249], v[42:43], v[250:251]
	v_cndmask_b32_e64 v180, v184, v180, s[38:39]
	v_cndmask_b32_e64 v181, v185, v181, s[38:39]
	v_cndmask_b32_e64 v182, v250, v182, s[38:39]
	v_cndmask_b32_e64 v183, v251, v183, s[38:39]
	v_cvt_pk_bf16_f32 v236, v180, v181
	v_cvt_pk_bf16_f32 v237, v182, v183
	global_store_dwordx2 v8, v[236:237], s[42:43]
	s_add_u32 s42, s42, 0x600
	s_addc_u32 s43, s43, 0
	v_lshlrev_b32_e32 v232, 16, v48
	v_and_b32_e32 v233, 0xffff0000, v48
	v_lshlrev_b32_e32 v234, 16, v49
	v_and_b32_e32 v235, 0xffff0000, v49
	v_lshlrev_b32_e32 v246, 16, v50
	v_and_b32_e32 v247, 0xffff0000, v50
	v_lshlrev_b32_e32 v248, 16, v51
	v_and_b32_e32 v249, 0xffff0000, v51
	v_pk_mul_f32 v[180:181], v[232:233], v[52:53]
	v_pk_mul_f32 v[182:183], v[234:235], v[54:55]
	v_pk_mul_f32 v[184:185], v[232:233], v[56:57]
	v_pk_mul_f32 v[250:251], v[234:235], v[58:59]
	v_pk_fma_f32 v[180:181], v[246:247], v[56:57], v[180:181] neg_lo:[1,0,0] neg_hi:[1,0,0]
	v_pk_fma_f32 v[182:183], v[248:249], v[58:59], v[182:183] neg_lo:[1,0,0] neg_hi:[1,0,0]
	v_pk_fma_f32 v[184:185], v[246:247], v[52:53], v[184:185]
	v_pk_fma_f32 v[250:251], v[248:249], v[54:55], v[250:251]
	v_cndmask_b32_e64 v180, v184, v180, s[38:39]
	v_cndmask_b32_e64 v181, v185, v181, s[38:39]
	v_cndmask_b32_e64 v182, v250, v182, s[38:39]
	v_cndmask_b32_e64 v183, v251, v183, s[38:39]
	v_cvt_pk_bf16_f32 v236, v180, v181
	v_cvt_pk_bf16_f32 v237, v182, v183
	global_store_dwordx2 v8, v[236:237], s[42:43]
	s_add_u32 s42, s42, 0x600
	s_addc_u32 s43, s43, 0
	v_lshlrev_b32_e32 v232, 16, v60
	v_and_b32_e32 v233, 0xffff0000, v60
	v_lshlrev_b32_e32 v234, 16, v61
	v_and_b32_e32 v235, 0xffff0000, v61
	v_lshlrev_b32_e32 v246, 16, v62
	v_and_b32_e32 v247, 0xffff0000, v62
	v_lshlrev_b32_e32 v248, 16, v63
	v_and_b32_e32 v249, 0xffff0000, v63
	v_pk_mul_f32 v[180:181], v[232:233], v[64:65]
	v_pk_mul_f32 v[182:183], v[234:235], v[66:67]
	v_pk_mul_f32 v[184:185], v[232:233], v[68:69]
	v_pk_mul_f32 v[250:251], v[234:235], v[70:71]
	v_pk_fma_f32 v[180:181], v[246:247], v[68:69], v[180:181] neg_lo:[1,0,0] neg_hi:[1,0,0]
	v_pk_fma_f32 v[182:183], v[248:249], v[70:71], v[182:183] neg_lo:[1,0,0] neg_hi:[1,0,0]
	v_pk_fma_f32 v[184:185], v[246:247], v[64:65], v[184:185]
	v_pk_fma_f32 v[250:251], v[248:249], v[66:67], v[250:251]
	v_cndmask_b32_e64 v180, v184, v180, s[38:39]
	v_cndmask_b32_e64 v181, v185, v181, s[38:39]
	v_cndmask_b32_e64 v182, v250, v182, s[38:39]
	v_cndmask_b32_e64 v183, v251, v183, s[38:39]
	v_cvt_pk_bf16_f32 v236, v180, v181
	v_cvt_pk_bf16_f32 v237, v182, v183
	global_store_dwordx2 v8, v[236:237], s[42:43]
	s_add_u32 s42, s42, 0x600
	s_addc_u32 s43, s43, 0
	v_lshlrev_b32_e32 v232, 16, v72
; __device__ __forceinline__ unsigned pk2(float lo, float hi) { f32x2 v = {lo, hi}; bf16x2_t b = __builtin_convertvector(v, bf16x2_t); return __builtin_bit_cast(unsigned, b); }
; __device__ __forceinline__ float bflo(unsigned u) { return __uint_as_float(u << 16); }
; __device__ __forceinline__ float bfhi(unsigned u) { return __uint_as_float(u & 0xffff0000u); }
; __device__ __forceinline__ void prep_compute(const PrepRow& d, const PrepArgs& a, int row, int lane) {
;     ...
;     { const int hh = lane >> 3, jj = (lane & 7) * 4;
;       const f32x4 x1 = {bflo(d.r1.x), bfhi(d.r1.x), bflo(d.r1.y), bfhi(d.r1.y)}, x2 = {bflo(d.r2.x), bfhi(d.r2.x), bflo(d.r2.y), bfhi(d.r2.y)};
;       const f32x4 o = (jj < 16) ? (x1 * d.c - x2 * d.s) : (x2 * d.c + x1 * d.s);
;       u32x2 w; w.x = pk2(o[0], o[1]); w.y = pk2(o[2], o[3]);
;       *(u32x2*)(a.Kb + (size_t)row * 768 + hh * 96 + 64 + jj) = w; }
	v_and_b32_e32 v233, 0xffff0000, v72
	v_lshlrev_b32_e32 v234, 16, v73
	v_and_b32_e32 v235, 0xffff0000, v73
	v_lshlrev_b32_e32 v246, 16, v74
	v_and_b32_e32 v247, 0xffff0000, v74
	v_lshlrev_b32_e32 v248, 16, v75
	v_and_b32_e32 v249, 0xffff0000, v75
	v_pk_mul_f32 v[180:181], v[232:233], v[76:77]
	v_pk_mul_f32 v[182:183], v[234:235], v[78:79]
	v_pk_mul_f32 v[184:185], v[232:233], v[80:81]
	v_pk_mul_f32 v[250:251], v[234:235], v[82:83]
	v_pk_fma_f32 v[180:181], v[246:247], v[80:81], v[180:181] neg_lo:[1,0,0] neg_hi:[1,0,0]
	v_pk_fma_f32 v[182:183], v[248:249], v[82:83], v[182:183] neg_lo:[1,0,0] neg_hi:[1,0,0]
	v_pk_fma_f32 v[184:185], v[246:247], v[76:77], v[184:185]
	v_pk_fma_f32 v[250:251], v[248:249], v[78:79], v[250:251]
	v_cndmask_b32_e64 v180, v184, v180, s[38:39]
	v_cndmask_b32_e64 v181, v185, v181, s[38:39]
	v_cndmask_b32_e64 v182, v250, v182, s[38:39]
	v_cndmask_b32_e64 v183, v251, v183, s[38:39]
	v_cvt_pk_bf16_f32 v236, v180, v181
	v_cvt_pk_bf16_f32 v237, v182, v183
	global_store_dwordx2 v8, v[236:237], s[42:43]
	s_add_u32 s42, s42, 0x600
	s_addc_u32 s43, s43, 0
	v_lshlrev_b32_e32 v232, 16, v84
	v_and_b32_e32 v233, 0xffff0000, v84
	v_lshlrev_b32_e32 v234, 16, v85
	v_and_b32_e32 v235, 0xffff0000, v85
	v_lshlrev_b32_e32 v246, 16, v86
	v_and_b32_e32 v247, 0xffff0000, v86
	v_lshlrev_b32_e32 v248, 16, v87
	v_and_b32_e32 v249, 0xffff0000, v87
	v_pk_mul_f32 v[180:181], v[232:233], v[88:89]
	v_pk_mul_f32 v[182:183], v[234:235], v[90:91]
	v_pk_mul_f32 v[184:185], v[232:233], v[92:93]
	v_pk_mul_f32 v[250:251], v[234:235], v[94:95]
	v_pk_fma_f32 v[180:181], v[246:247], v[92:93], v[180:181] neg_lo:[1,0,0] neg_hi:[1,0,0]
	v_pk_fma_f32 v[182:183], v[248:249], v[94:95], v[182:183] neg_lo:[1,0,0] neg_hi:[1,0,0]
	v_pk_fma_f32 v[184:185], v[246:247], v[88:89], v[184:185]
	v_pk_fma_f32 v[250:251], v[248:249], v[90:91], v[250:251]
	v_cndmask_b32_e64 v180, v184, v180, s[38:39]
	v_cndmask_b32_e64 v181, v185, v181, s[38:39]
	v_cndmask_b32_e64 v182, v250, v182, s[38:39]
	v_cndmask_b32_e64 v183, v251, v183, s[38:39]
	v_cvt_pk_bf16_f32 v236, v180, v181
	v_cvt_pk_bf16_f32 v237, v182, v183
	global_store_dwordx2 v8, v[236:237], s[42:43]
	s_add_u32 s42, s42, 0x600
	s_addc_u32 s43, s43, 0
	v_lshlrev_b32_e32 v232, 16, v96
	v_and_b32_e32 v233, 0xffff0000, v96
	v_lshlrev_b32_e32 v234, 16, v97
	v_and_b32_e32 v235, 0xffff0000, v97
	v_lshlrev_b32_e32 v246, 16, v98
	v_and_b32_e32 v247, 0xffff0000, v98
	v_lshlrev_b32_e32 v248, 16, v99
	v_and_b32_e32 v249, 0xffff0000, v99
	v_pk_mul_f32 v[180:181], v[232:233], v[100:101]
	v_pk_mul_f32 v[182:183], v[234:235], v[102:103]
	v_pk_mul_f32 v[184:185], v[232:233], v[104:105]
	v_pk_mul_f32 v[250:251], v[234:235], v[106:107]
	v_pk_fma_f32 v[180:181], v[246:247], v[104:105], v[180:181] neg_lo:[1,0,0] neg_hi:[1,0,0]
	v_pk_fma_f32 v[182:183], v[248:249], v[106:107], v[182:183] neg_lo:[1,0,0] neg_hi:[1,0,0]
	v_pk_fma_f32 v[184:185], v[246:247], v[100:101], v[184:185]
	v_pk_fma_f32 v[250:251], v[248:249], v[102:103], v[250:251]
	v_cndmask_b32_e64 v180, v184, v180, s[38:39]
	v_cndmask_b32_e64 v181, v185, v181, s[38:39]
	v_cndmask_b32_e64 v182, v250, v182, s[38:39]
	v_cndmask_b32_e64 v183, v251, v183, s[38:39]
	v_cvt_pk_bf16_f32 v236, v180, v181
	v_cvt_pk_bf16_f32 v237, v182, v183
	global_store_dwordx2 v8, v[236:237], s[42:43]
	s_add_u32 s42, s42, 0x600
	s_addc_u32 s43, s43, 0
	v_lshlrev_b32_e32 v232, 16, v108
	v_and_b32_e32 v233, 0xffff0000, v108
	v_lshlrev_b32_e32 v234, 16, v109
	v_and_b32_e32 v235, 0xffff0000, v109
	v_lshlrev_b32_e32 v246, 16, v110
	v_and_b32_e32 v247, 0xffff0000, v110
	v_lshlrev_b32_e32 v248, 16, v111
	v_and_b32_e32 v249, 0xffff0000, v111
	v_pk_mul_f32 v[180:181], v[232:233], v[112:113]
	v_pk_mul_f32 v[182:183], v[234:235], v[114:115]
	v_pk_mul_f32 v[184:185], v[232:233], v[116:117]
	v_pk_mul_f32 v[250:251], v[234:235], v[118:119]
	v_pk_fma_f32 v[180:181], v[246:247], v[116:117], v[180:181] neg_lo:[1,0,0] neg_hi:[1,0,0]
	v_pk_fma_f32 v[182:183], v[248:249], v[118:119], v[182:183] neg_lo:[1,0,0] neg_hi:[1,0,0]
	v_pk_fma_f32 v[184:185], v[246:247], v[112:113], v[184:185]
	v_pk_fma_f32 v[250:251], v[248:249], v[114:115], v[250:251]
	v_cndmask_b32_e64 v180, v184, v180, s[38:39]
	v_cndmask_b32_e64 v181, v185, v181, s[38:39]
	v_cndmask_b32_e64 v182, v250, v182, s[38:39]
	v_cndmask_b32_e64 v183, v251, v183, s[38:39]
	v_cvt_pk_bf16_f32 v236, v180, v181
	v_cvt_pk_bf16_f32 v237, v182, v183
	global_store_dwordx2 v8, v[236:237], s[42:43]
	s_add_u32 s42, s42, 0x600
	s_addc_u32 s43, s43, 0
	v_lshlrev_b32_e32 v232, 16, v120
	v_and_b32_e32 v233, 0xffff0000, v120
	v_lshlrev_b32_e32 v234, 16, v121
	v_and_b32_e32 v235, 0xffff0000, v121
	v_lshlrev_b32_e32 v246, 16, v122
	v_and_b32_e32 v247, 0xffff0000, v122
	v_lshlrev_b32_e32 v248, 16, v123
	v_and_b32_e32 v249, 0xffff0000, v123
	v_pk_mul_f32 v[180:181], v[232:233], v[124:125]
	v_pk_mul_f32 v[182:183], v[234:235], v[126:127]
	v_pk_mul_f32 v[184:185], v[232:233], v[128:129]
	v_pk_mul_f32 v[250:251], v[234:235], v[130:131]
	v_pk_fma_f32 v[180:181], v[246:247], v[128:129], v[180:181] neg_lo:[1,0,0] neg_hi:[1,0,0]
	v_pk_fma_f32 v[182:183], v[248:249], v[130:131], v[182:183] neg_lo:[1,0,0] neg_hi:[1,0,0]
	v_pk_fma_f32 v[184:185], v[246:247], v[124:125], v[184:185]
	v_pk_fma_f32 v[250:251], v[248:249], v[126:127], v[250:251]
	v_cndmask_b32_e64 v180, v184, v180, s[38:39]
	v_cndmask_b32_e64 v181, v185, v181, s[38:39]
	v_cndmask_b32_e64 v182, v250, v182, s[38:39]
	v_cndmask_b32_e64 v183, v251, v183, s[38:39]
	v_cvt_pk_bf16_f32 v236, v180, v181
	v_cvt_pk_bf16_f32 v237, v182, v183
	global_store_dwordx2 v8, v[236:237], s[42:43]
	s_add_u32 s42, s42, 0x600
	s_addc_u32 s43, s43, 0
	v_lshlrev_b32_e32 v232, 16, v132
; __device__ __forceinline__ unsigned pk2(float lo, float hi) { f32x2 v = {lo, hi}; bf16x2_t b = __builtin_convertvector(v, bf16x2_t); return __builtin_bit_cast(unsigned, b); }
; __device__ __forceinline__ float bflo(unsigned u) { return __uint_as_float(u << 16); }
; __device__ __forceinline__ float bfhi(unsigned u) { return __uint_as_float(u & 0xffff0000u); }
; __device__ __forceinline__ void prep_compute(const PrepRow& d, const PrepArgs& a, int row, int lane) {
;     ...
;     { const int hh = lane >> 3, jj = (lane & 7) * 4;
;       const f32x4 x1 = {bflo(d.r1.x), bfhi(d.r1.x), bflo(d.r1.y), bfhi(d.r1.y)}, x2 = {bflo(d.r2.x), bfhi(d.r2.x), bflo(d.r2.y), bfhi(d.r2.y)};
;       const f32x4 o = (jj < 16) ? (x1 * d.c - x2 * d.s) : (x2 * d.c + x1 * d.s);
;       u32x2 w; w.x = pk2(o[0], o[1]); w.y = pk2(o[2], o[3]);
;       *(u32x2*)(a.Kb + (size_t)row * 768 + hh * 96 + 64 + jj) = w; }
	v_and_b32_e32 v233, 0xffff0000, v132
	v_lshlrev_b32_e32 v234, 16, v133
	v_and_b32_e32 v235, 0xffff0000, v133
	v_lshlrev_b32_e32 v246, 16, v134
	v_and_b32_e32 v247, 0xffff0000, v134
	v_lshlrev_b32_e32 v248, 16, v135
	v_and_b32_e32 v249, 0xffff0000, v135
	v_pk_mul_f32 v[180:181], v[232:233], v[136:137]
	v_pk_mul_f32 v[182:183], v[234:235], v[138:139]
	v_pk_mul_f32 v[184:185], v[232:233], v[140:141]
	v_pk_mul_f32 v[250:251], v[234:235], v[142:143]
	v_pk_fma_f32 v[180:181], v[246:247], v[140:141], v[180:181] neg_lo:[1,0,0] neg_hi:[1,0,0]
	v_pk_fma_f32 v[182:183], v[248:249], v[142:143], v[182:183] neg_lo:[1,0,0] neg_hi:[1,0,0]
	v_pk_fma_f32 v[184:185], v[246:247], v[136:137], v[184:185]
	v_pk_fma_f32 v[250:251], v[248:249], v[138:139], v[250:251]
	v_cndmask_b32_e64 v180, v184, v180, s[38:39]
	v_cndmask_b32_e64 v181, v185, v181, s[38:39]
	v_cndmask_b32_e64 v182, v250, v182, s[38:39]
	v_cndmask_b32_e64 v183, v251, v183, s[38:39]
	v_cvt_pk_bf16_f32 v236, v180, v181
	v_cvt_pk_bf16_f32 v237, v182, v183
	global_store_dwordx2 v8, v[236:237], s[42:43]
	s_add_u32 s42, s42, 0x600
	s_addc_u32 s43, s43, 0
	v_lshlrev_b32_e32 v232, 16, v144
	v_and_b32_e32 v233, 0xffff0000, v144
	v_lshlrev_b32_e32 v234, 16, v145
	v_and_b32_e32 v235, 0xffff0000, v145
	v_lshlrev_b32_e32 v246, 16, v146
	v_and_b32_e32 v247, 0xffff0000, v146
	v_lshlrev_b32_e32 v248, 16, v147
	v_and_b32_e32 v249, 0xffff0000, v147
	v_pk_mul_f32 v[180:181], v[232:233], v[148:149]
	v_pk_mul_f32 v[182:183], v[234:235], v[150:151]
	v_pk_mul_f32 v[184:185], v[232:233], v[152:153]
	v_pk_mul_f32 v[250:251], v[234:235], v[154:155]
	v_pk_fma_f32 v[180:181], v[246:247], v[152:153], v[180:181] neg_lo:[1,0,0] neg_hi:[1,0,0]
	v_pk_fma_f32 v[182:183], v[248:249], v[154:155], v[182:183] neg_lo:[1,0,0] neg_hi:[1,0,0]
	v_pk_fma_f32 v[184:185], v[246:247], v[148:149], v[184:185]
	v_pk_fma_f32 v[250:251], v[248:249], v[150:151], v[250:251]
	v_cndmask_b32_e64 v180, v184, v180, s[38:39]
	v_cndmask_b32_e64 v181, v185, v181, s[38:39]
	v_cndmask_b32_e64 v182, v250, v182, s[38:39]
	v_cndmask_b32_e64 v183, v251, v183, s[38:39]
	v_cvt_pk_bf16_f32 v236, v180, v181
	v_cvt_pk_bf16_f32 v237, v182, v183
	global_store_dwordx2 v8, v[236:237], s[42:43]
	s_add_u32 s42, s42, 0x600
	s_addc_u32 s43, s43, 0
	v_lshlrev_b32_e32 v232, 16, v156
	v_and_b32_e32 v233, 0xffff0000, v156
	v_lshlrev_b32_e32 v234, 16, v157
	v_and_b32_e32 v235, 0xffff0000, v157
	v_lshlrev_b32_e32 v246, 16, v158
	v_and_b32_e32 v247, 0xffff0000, v158
	v_lshlrev_b32_e32 v248, 16, v159
	v_and_b32_e32 v249, 0xffff0000, v159
	v_pk_mul_f32 v[180:181], v[232:233], v[160:161]
	v_pk_mul_f32 v[182:183], v[234:235], v[162:163]
	v_pk_mul_f32 v[184:185], v[232:233], v[164:165]
	v_pk_mul_f32 v[250:251], v[234:235], v[166:167]
	v_pk_fma_f32 v[180:181], v[246:247], v[164:165], v[180:181] neg_lo:[1,0,0] neg_hi:[1,0,0]
	v_pk_fma_f32 v[182:183], v[248:249], v[166:167], v[182:183] neg_lo:[1,0,0] neg_hi:[1,0,0]
	v_pk_fma_f32 v[184:185], v[246:247], v[160:161], v[184:185]
	v_pk_fma_f32 v[250:251], v[248:249], v[162:163], v[250:251]
	v_cndmask_b32_e64 v180, v184, v180, s[38:39]
	v_cndmask_b32_e64 v181, v185, v181, s[38:39]
	v_cndmask_b32_e64 v182, v250, v182, s[38:39]
	v_cndmask_b32_e64 v183, v251, v183, s[38:39]
	v_cvt_pk_bf16_f32 v236, v180, v181
	v_cvt_pk_bf16_f32 v237, v182, v183
	global_store_dwordx2 v8, v[236:237], s[42:43]
	s_add_u32 s42, s42, 0x600
	s_addc_u32 s43, s43, 0
	v_lshlrev_b32_e32 v232, 16, v168
	v_and_b32_e32 v233, 0xffff0000, v168
	v_lshlrev_b32_e32 v234, 16, v169
	v_and_b32_e32 v235, 0xffff0000, v169
	v_lshlrev_b32_e32 v246, 16, v170
	v_and_b32_e32 v247, 0xffff0000, v170
	v_lshlrev_b32_e32 v248, 16, v171
	v_and_b32_e32 v249, 0xffff0000, v171
	v_pk_mul_f32 v[180:181], v[232:233], v[172:173]
	v_pk_mul_f32 v[182:183], v[234:235], v[174:175]
	v_pk_mul_f32 v[184:185], v[232:233], v[176:177]
	v_pk_mul_f32 v[250:251], v[234:235], v[178:179]
	v_pk_fma_f32 v[180:181], v[246:247], v[176:177], v[180:181] neg_lo:[1,0,0] neg_hi:[1,0,0]
	v_pk_fma_f32 v[182:183], v[248:249], v[178:179], v[182:183] neg_lo:[1,0,0] neg_hi:[1,0,0]
	v_pk_fma_f32 v[184:185], v[246:247], v[172:173], v[184:185]
	v_pk_fma_f32 v[250:251], v[248:249], v[174:175], v[250:251]
	v_cndmask_b32_e64 v180, v184, v180, s[38:39]
	v_cndmask_b32_e64 v181, v185, v181, s[38:39]
	v_cndmask_b32_e64 v182, v250, v182, s[38:39]
	v_cndmask_b32_e64 v183, v251, v183, s[38:39]
	v_cvt_pk_bf16_f32 v236, v180, v181
	v_cvt_pk_bf16_f32 v237, v182, v183
	global_store_dwordx2 v8, v[236:237], s[42:43]
	s_add_u32 s42, s42, 0x600
	s_addc_u32 s43, s43, 0
	v_lshlrev_b32_e32 v232, 16, v196
	v_and_b32_e32 v233, 0xffff0000, v196
	v_lshlrev_b32_e32 v234, 16, v197
	v_and_b32_e32 v235, 0xffff0000, v197
	v_lshlrev_b32_e32 v246, 16, v198
	v_and_b32_e32 v247, 0xffff0000, v198
	v_lshlrev_b32_e32 v248, 16, v199
	v_and_b32_e32 v249, 0xffff0000, v199
	v_pk_mul_f32 v[180:181], v[232:233], v[200:201]
	v_pk_mul_f32 v[182:183], v[234:235], v[202:203]
	v_pk_mul_f32 v[184:185], v[232:233], v[204:205]
	v_pk_mul_f32 v[250:251], v[234:235], v[206:207]
	v_pk_fma_f32 v[180:181], v[246:247], v[204:205], v[180:181] neg_lo:[1,0,0] neg_hi:[1,0,0]
	v_pk_fma_f32 v[182:183], v[248:249], v[206:207], v[182:183] neg_lo:[1,0,0] neg_hi:[1,0,0]
	v_pk_fma_f32 v[184:185], v[246:247], v[200:201], v[184:185]
	v_pk_fma_f32 v[250:251], v[248:249], v[202:203], v[250:251]
	v_cndmask_b32_e64 v180, v184, v180, s[38:39]
	v_cndmask_b32_e64 v181, v185, v181, s[38:39]
	v_cndmask_b32_e64 v182, v250, v182, s[38:39]
	v_cndmask_b32_e64 v183, v251, v183, s[38:39]
	v_cvt_pk_bf16_f32 v236, v180, v181
	v_cvt_pk_bf16_f32 v237, v182, v183
	global_store_dwordx2 v8, v[236:237], s[42:43]
	s_add_u32 s42, s42, 0x600
	s_addc_u32 s43, s43, 0
	v_lshlrev_b32_e32 v232, 16, v208
	v_and_b32_e32 v233, 0xffff0000, v208
	v_lshlrev_b32_e32 v234, 16, v209
	v_and_b32_e32 v235, 0xffff0000, v209
	v_lshlrev_b32_e32 v246, 16, v210
	v_and_b32_e32 v247, 0xffff0000, v210
	v_lshlrev_b32_e32 v248, 16, v211
	v_and_b32_e32 v249, 0xffff0000, v211
	v_pk_mul_f32 v[180:181], v[232:233], v[212:213]
	v_pk_mul_f32 v[182:183], v[234:235], v[214:215]
	v_pk_mul_f32 v[184:185], v[232:233], v[216:217]
	v_pk_mul_f32 v[250:251], v[234:235], v[218:219]
	v_pk_fma_f32 v[180:181], v[246:247], v[216:217], v[180:181] neg_lo:[1,0,0] neg_hi:[1,0,0]
	v_pk_fma_f32 v[182:183], v[248:249], v[218:219], v[182:183] neg_lo:[1,0,0] neg_hi:[1,0,0]
	v_pk_fma_f32 v[184:185], v[246:247], v[212:213], v[184:185]
	v_pk_fma_f32 v[250:251], v[248:249], v[214:215], v[250:251]
	v_cndmask_b32_e64 v180, v184, v180, s[38:39]
	v_cndmask_b32_e64 v181, v185, v181, s[38:39]
	v_cndmask_b32_e64 v182, v250, v182, s[38:39]
	v_cndmask_b32_e64 v183, v251, v183, s[38:39]
	v_cvt_pk_bf16_f32 v236, v180, v181
	v_cvt_pk_bf16_f32 v237, v182, v183
	global_store_dwordx2 v8, v[236:237], s[42:43]
	s_branch .LBB0_566

; __device__ __forceinline__ void prep_load(PrepRow& d, const PrepArgs& a, int row, int lane) {
;     const bf16_t* pr = a.PA + (size_t)row * PA_LD; const int ts = row & (SEQ - 1);
;     { const int fi = ((lane & 7) * 4) & 15; d.r1 = *(const u32x2*)(pr + 896 + fi); d.r2 = *(const u32x2*)(pr + 912 + fi);
;       d.c = *(const f32x4*)(a.cs + ts * 16 + fi); d.s = *(const f32x4*)(a.sn + ts * 16 + fi); }
;     { const int win = 2 << (lane >> 4); const int n = (ts + 1 < win) ? ts + 1 : win;
; #pragma unroll
;       for (int i = 0; i < 16; ++i) { const int ii = (i < n) ? i : 0; d.pool[i] = *(const u32x2*)(pr - (size_t)ii * PA_LD + 4 * lane); } }
; #pragma unroll
;     for (int j = 0; j < 4; ++j) { const int back = (ts - 3 + j >= 0) ? (3 - j) : 0; d.cv[j] = *(const u32x2*)(pr - (size_t)back * PA_LD + 256 + 4 * lane); }
; }
; __device__ __forceinline__ void prep_phase(const PrepArgs& a, int gw, int NGW, int lane) {
;     ...
;     for (; row < TOK; row += 2 * NGW) {
;         const int r1 = row + NGW, r2 = row + 2 * NGW;
;         prep_load(dB, a, r1 < TOK ? r1 : row, lane);
.LBB0_564:
	s_add_i32 s24, s20, s94
	s_add_i32 s13, s12, s20
	s_cmp_lt_i32 s24, 0x8000
	s_cselect_b32 s0, s24, s20
	s_mul_i32 s14, s0, 0xa00
	s_mul_hi_i32 s1, s0, 0xa00
	s_add_u32 s16, s60, s14
	s_addc_u32 s17, s61, s1
	s_and_b32 s0, s0, 0xfff
	s_add_i32 s19, s0, 1
	v_min_u32_e32 v118, s19, v122
	v_mov_b32_e32 v33, v1
	v_cmp_lt_u32_e32 vcc, 2, v118
	v_mov_b32_e32 v123, 0xffffec00
	v_lshl_add_u64 v[72:73], s[16:17], 0, v[32:33]
	v_cndmask_b32_e64 v75, 0, -1, vcc
	v_cndmask_b32_e32 v74, 0, v123, vcc
	v_cmp_lt_u32_e32 vcc, 3, v118
	v_mov_b32_e32 v132, 0xffffe200
	v_lshl_add_u64 v[124:125], v[72:73], 0, v[74:75]
	v_cndmask_b32_e64 v75, 0, -1, vcc
	v_cndmask_b32_e32 v74, 0, v132, vcc
	v_cmp_lt_u32_e32 vcc, 4, v118
	v_mov_b32_e32 v133, 0xffffd800
	s_lshl_b32 s48, s0, 6
	v_cndmask_b32_e64 v77, 0, -1, vcc
	v_cndmask_b32_e32 v76, 0, v133, vcc
	v_cmp_lt_u32_e32 vcc, 5, v118
	v_mov_b32_e32 v134, 0xffffce00
	s_cmp_eq_u32 s0, 0
	v_lshl_add_u64 v[10:11], s[16:17], 0, v[0:1]
	v_cndmask_b32_e64 v79, 0, -1, vcc
	v_cndmask_b32_e32 v78, 0, v134, vcc
	v_cmp_lt_u32_e32 vcc, 6, v118
	v_mov_b32_e32 v135, 0xffffc400
	s_cselect_b32 s45, 0, -1
	s_cselect_b32 s44, 0, 0xfffff600
	s_cmp_lt_u32 s0, 3
	global_load_dwordx2 v[114:115], v[10:11], off offset:1792
	global_load_dwordx2 v[112:113], v[10:11], off offset:1824
	v_lshl_add_u64 v[10:11], v[18:19], 0, s[48:49]
	v_lshl_add_u64 v[12:13], v[20:21], 0, s[48:49]
	v_lshl_add_u64 v[74:75], v[72:73], 0, v[74:75]
	v_cndmask_b32_e64 v81, 0, -1, vcc
	v_cndmask_b32_e32 v80, 0, v135, vcc
	v_cmp_lt_u32_e32 vcc, 7, v118
	v_mov_b32_e32 v136, 0xffffba00
	s_cselect_b32 s14, 0, 0xffffe200
	global_load_dwordx4 v[14:17], v[10:11], off
	s_nop 0
	global_load_dwordx4 v[10:13], v[12:13], off
	v_lshl_add_u64 v[76:77], v[72:73], 0, v[76:77]
	v_lshl_add_u64 v[78:79], v[72:73], 0, v[78:79]
	v_lshl_add_u64 v[80:81], v[72:73], 0, v[80:81]
	global_load_dwordx2 v[110:111], v[74:75], off
	global_load_dwordx2 v[108:109], v[76:77], off
	global_load_dwordx2 v[104:105], v[78:79], off
	global_load_dwordx2 v[100:101], v[80:81], off
	v_cndmask_b32_e64 v75, 0, -1, vcc
	v_cndmask_b32_e32 v74, 0, v136, vcc
	v_cmp_lt_u32_e32 vcc, 8, v118
	v_mov_b32_e32 v137, 0xffffb000
	s_cselect_b32 s1, 0, -1
	s_add_u32 s36, s16, s14
	v_cndmask_b32_e64 v77, 0, -1, vcc
	v_cndmask_b32_e32 v76, 0, v137, vcc
	v_cmp_lt_u32_e32 vcc, 9, v118
	v_mov_b32_e32 v138, 0xffffa600
	s_addc_u32 s37, s17, s1
	v_cndmask_b32_e64 v79, 0, -1, vcc
	v_cndmask_b32_e32 v78, 0, v138, vcc
	v_cmp_lt_u32_e32 vcc, 10, v118
	v_mov_b32_e32 v139, 0xffff9c00
	s_cmp_lt_u32 s0, 2
	v_lshl_add_u64 v[74:75], v[72:73], 0, v[74:75]
	v_cndmask_b32_e64 v81, 0, -1, vcc
	v_cndmask_b32_e32 v80, 0, v139, vcc
	v_cmp_lt_u32_e32 vcc, 11, v118
	v_mov_b32_e32 v140, 0xffff9200
	s_cselect_b32 s1, 0, 0xffffec00
	v_lshl_add_u64 v[76:77], v[72:73], 0, v[76:77]
	v_lshl_add_u64 v[78:79], v[72:73], 0, v[78:79]
	v_lshl_add_u64 v[80:81], v[72:73], 0, v[80:81]
	global_load_dwordx2 v[106:107], v[74:75], off
	global_load_dwordx2 v[102:103], v[76:77], off
	global_load_dwordx2 v[96:97], v[78:79], off
	global_load_dwordx2 v[92:93], v[80:81], off
	v_cndmask_b32_e64 v75, 0, -1, vcc
	v_cndmask_b32_e32 v74, 0, v140, vcc
	v_cmp_lt_u32_e32 vcc, 12, v118
	v_mov_b32_e32 v141, 0xffff8800
	s_cselect_b32 s0, 0, -1
	s_add_u32 s40, s16, s1
	v_cndmask_b32_e64 v77, 0, -1, vcc
	v_cndmask_b32_e32 v76, 0, v141, vcc
	v_cmp_lt_u32_e32 vcc, 13, v118
	v_mov_b32_e32 v142, 0xffff7e00
	s_addc_u32 s41, s17, s0
	v_cndmask_b32_e64 v79, 0, -1, vcc
	v_cndmask_b32_e32 v78, 0, v142, vcc
	v_cmp_lt_u32_e32 vcc, 14, v118
	v_mov_b32_e32 v143, 0xffff7400
	s_add_u32 s42, s16, s44
	v_lshl_add_u64 v[74:75], v[72:73], 0, v[74:75]
	v_cndmask_b32_e64 v81, 0, -1, vcc
	v_cndmask_b32_e32 v80, 0, v143, vcc
	v_cmp_lt_u32_e32 vcc, 15, v118
	v_mov_b32_e32 v144, 0xffff6a00
	s_addc_u32 s43, s17, s45
	v_lshl_add_u64 v[76:77], v[72:73], 0, v[76:77]
	v_lshl_add_u64 v[78:79], v[72:73], 0, v[78:79]
	v_lshl_add_u64 v[80:81], v[72:73], 0, v[80:81]
	global_load_dwordx2 v[98:99], v[74:75], off
	global_load_dwordx2 v[94:95], v[76:77], off
	global_load_dwordx2 v[88:89], v[78:79], off
	global_load_dwordx2 v[84:85], v[80:81], off
	v_cndmask_b32_e64 v75, 0, -1, vcc
	v_cndmask_b32_e32 v74, 0, v144, vcc
	v_lshl_add_u64 v[116:117], v[72:73], 0, s[44:45]
	v_lshl_add_u64 v[74:75], v[72:73], 0, v[74:75]
	v_lshl_add_u64 v[76:77], s[36:37], 0, v[32:33]
	v_lshl_add_u64 v[118:119], s[40:41], 0, v[32:33]
	v_lshl_add_u64 v[120:121], s[42:43], 0, v[32:33]
	global_load_dwordx2 v[80:81], v[74:75], off
	global_load_dwordx2 v[78:79], v[76:77], off offset:512
	s_nop 0
	global_load_dwordx2 v[76:77], v[118:119], off offset:512
	global_load_dwordx2 v[74:75], v[120:121], off offset:512
	s_nop 0
	global_load_dwordx2 v[120:121], v[72:73], off
	global_load_dwordx2 v[118:119], v[116:117], off
	s_nop 0
	global_load_dwordx2 v[116:117], v[124:125], off
	s_nop 0
	global_load_dwordx2 v[72:73], v[72:73], off offset:512
	s_waitcnt vmcnt(24) lgkmcnt(0)
; __device__ __forceinline__ unsigned pk2(float lo, float hi) { f32x2 v = {lo, hi}; bf16x2_t b = __builtin_convertvector(v, bf16x2_t); return __builtin_bit_cast(unsigned, b); }
; __device__ __forceinline__ float bflo(unsigned u) { return __uint_as_float(u << 16); }
; __device__ __forceinline__ float bfhi(unsigned u) { return __uint_as_float(u & 0xffff0000u); }
; __device__ __forceinline__ void prep_compute(const PrepRow& d, const PrepArgs& a, int row, int lane) {
;     const int ts = row & (SEQ - 1);
;     { const int hh = lane >> 3, jj = (lane & 7) * 4;
;       const f32x4 x1 = {bflo(d.r1.x), bfhi(d.r1.x), bflo(d.r1.y), bfhi(d.r1.y)}, x2 = {bflo(d.r2.x), bfhi(d.r2.x), bflo(d.r2.y), bfhi(d.r2.y)};
;       const f32x4 o = (jj < 16) ? (x1 * d.c - x2 * d.s) : (x2 * d.c + x1 * d.s);
;       u32x2 w; w.x = pk2(o[0], o[1]); w.y = pk2(o[2], o[3]);
;       *(u32x2*)(a.Kb + (size_t)row * 768 + hh * 96 + 64 + jj) = w; }
;     { const int win = 2 << (lane >> 4); const int n = (ts + 1 < win) ? ts + 1 : win;
;       f32x4 sum = {0.f, 0.f, 0.f, 0.f};
; #pragma unroll
;       for (int i = 0; i < 16; ++i) { const float mk = (i < n) ? 1.f : 0.f; const f32x4 v = {bflo(d.pool[i].x), bfhi(d.pool[i].x), bflo(d.pool[i].y), bfhi(d.pool[i].y)}; sum += v * mk; }
;       const f32x4 self = {bflo(d.pool[0].x), bfhi(d.pool[0].x), bflo(d.pool[0].y), bfhi(d.pool[0].y)};
	v_lshlrev_b32_e32 v124, 16, v44
	v_and_b32_e32 v125, 0xffff0000, v44
	v_lshlrev_b32_e32 v44, 16, v45
	v_and_b32_e32 v45, 0xffff0000, v45
	v_lshlrev_b32_e32 v126, 16, v42
	v_and_b32_e32 v127, 0xffff0000, v42
	v_lshlrev_b32_e32 v42, 16, v43
	v_and_b32_e32 v43, 0xffff0000, v43
	v_pk_mul_f32 v[128:129], v[8:9], v[42:43]
	v_pk_mul_f32 v[130:131], v[6:7], v[126:127]
	v_pk_mul_f32 v[8:9], v[8:9], v[44:45]
	v_pk_mul_f32 v[6:7], v[6:7], v[124:125]
	s_and_b32 s14, s20, 0xfff
	v_pk_fma_f32 v[130:131], v[2:3], v[124:125], v[130:131] neg_lo:[0,0,1] neg_hi:[0,0,1]
	v_pk_fma_f32 v[128:129], v[4:5], v[44:45], v[128:129] neg_lo:[0,0,1] neg_hi:[0,0,1]
	v_pk_fma_f32 v[2:3], v[2:3], v[126:127], v[6:7]
	v_pk_fma_f32 v[4:5], v[4:5], v[42:43], v[8:9]
	s_ashr_i32 s21, s20, 31
	s_add_i32 s15, s14, 1
	v_cndmask_b32_e64 v5, v5, v129, s[38:39]
	v_cndmask_b32_e64 v4, v4, v128, s[38:39]
	v_cndmask_b32_e64 v3, v3, v131, s[38:39]
	v_cndmask_b32_e64 v2, v2, v130, s[38:39]
	s_cmp_eq_u32 s14, 0
	v_cvt_pk_bf16_f32 v2, v2, v3
	v_cvt_pk_bf16_f32 v3, v4, v5
	v_mad_i64_i32 v[4:5], s[16:17], s20, v229, v[30:31]
	s_cselect_b64 s[0:1], -1, 0
	global_store_dwordx2 v[4:5], v[2:3], off offset:128
	v_min_u32_e32 v3, s15, v122
	v_lshlrev_b32_e32 v4, 16, v90
	v_and_b32_e32 v5, 0xffff0000, v90
	v_lshlrev_b32_e32 v6, 16, v91
	v_and_b32_e32 v7, 0xffff0000, v91
	v_pk_add_f32 v[8:9], v[6:7], 0 op_sel_hi:[1,0]
	v_pk_add_f32 v[42:43], v[4:5], 0 op_sel_hi:[1,0]
	v_cndmask_b32_e64 v2, 1.0, 0, s[0:1]
	v_lshlrev_b32_e32 v44, 16, v86
	v_and_b32_e32 v45, 0xffff0000, v86
	v_lshlrev_b32_e32 v86, 16, v87
	v_and_b32_e32 v87, 0xffff0000, v87
	v_cmp_lt_u32_e32 vcc, 2, v3
	v_pk_fma_f32 v[42:43], v[2:3], v[44:45], v[42:43] op_sel_hi:[0,1,1]
	v_pk_fma_f32 v[8:9], v[2:3], v[86:87], v[8:9] op_sel_hi:[0,1,1]
	v_cndmask_b32_e64 v44, 0, 1.0, vcc
	v_lshlrev_b32_e32 v86, 16, v82
	v_and_b32_e32 v87, 0xffff0000, v82
	v_lshlrev_b32_e32 v82, 16, v83
	v_and_b32_e32 v83, 0xffff0000, v83
	v_cmp_lt_u32_e32 vcc, 3, v3
	v_pk_fma_f32 v[8:9], v[44:45], v[82:83], v[8:9] op_sel_hi:[0,1,1]
	v_pk_fma_f32 v[42:43], v[44:45], v[86:87], v[42:43] op_sel_hi:[0,1,1]
	v_cndmask_b32_e64 v44, 0, 1.0, vcc
	v_lshlrev_b32_e32 v82, 16, v62
	v_and_b32_e32 v83, 0xffff0000, v62
	v_lshlrev_b32_e32 v62, 16, v63
	v_and_b32_e32 v63, 0xffff0000, v63
	v_cmp_lt_u32_e32 vcc, 4, v3
	v_pk_fma_f32 v[42:43], v[44:45], v[82:83], v[42:43] op_sel_hi:[0,1,1]
	v_pk_fma_f32 v[8:9], v[44:45], v[62:63], v[8:9] op_sel_hi:[0,1,1]
	v_cndmask_b32_e64 v44, 0, 1.0, vcc
	v_lshlrev_b32_e32 v62, 16, v56
	v_and_b32_e32 v63, 0xffff0000, v56
	v_lshlrev_b32_e32 v56, 16, v57
	v_and_b32_e32 v57, 0xffff0000, v57
	v_cmp_lt_u32_e32 vcc, 5, v3
	v_pk_fma_f32 v[8:9], v[44:45], v[56:57], v[8:9] op_sel_hi:[0,1,1]
	v_pk_fma_f32 v[42:43], v[44:45], v[62:63], v[42:43] op_sel_hi:[0,1,1]
	v_cndmask_b32_e64 v44, 0, 1.0, vcc
	v_lshlrev_b32_e32 v56, 16, v50
	v_and_b32_e32 v57, 0xffff0000, v50
	v_lshlrev_b32_e32 v50, 16, v51
	v_and_b32_e32 v51, 0xffff0000, v51
	v_cmp_lt_u32_e32 vcc, 6, v3
	v_pk_fma_f32 v[42:43], v[44:45], v[56:57], v[42:43] op_sel_hi:[0,1,1]
	v_pk_fma_f32 v[8:9], v[44:45], v[50:51], v[8:9] op_sel_hi:[0,1,1]
	v_cndmask_b32_e64 v44, 0, 1.0, vcc
	v_lshlrev_b32_e32 v50, 16, v46
	v_and_b32_e32 v51, 0xffff0000, v46
	v_lshlrev_b32_e32 v46, 16, v47
	v_and_b32_e32 v47, 0xffff0000, v47
	v_cmp_lt_u32_e32 vcc, 7, v3
	v_pk_fma_f32 v[8:9], v[44:45], v[46:47], v[8:9] op_sel_hi:[0,1,1]
	v_pk_fma_f32 v[42:43], v[44:45], v[50:51], v[42:43] op_sel_hi:[0,1,1]
	v_cndmask_b32_e64 v44, 0, 1.0, vcc
	v_lshlrev_b32_e32 v46, 16, v68
	v_and_b32_e32 v47, 0xffff0000, v68
	v_lshlrev_b32_e32 v50, 16, v69
	v_and_b32_e32 v51, 0xffff0000, v69
	v_cmp_lt_u32_e32 vcc, 8, v3
	v_pk_fma_f32 v[42:43], v[44:45], v[46:47], v[42:43] op_sel_hi:[0,1,1]
	v_pk_fma_f32 v[8:9], v[44:45], v[50:51], v[8:9] op_sel_hi:[0,1,1]
	v_cndmask_b32_e64 v44, 0, 1.0, vcc
	v_lshlrev_b32_e32 v46, 16, v60
	v_and_b32_e32 v47, 0xffff0000, v60
	v_lshlrev_b32_e32 v50, 16, v61
	v_and_b32_e32 v51, 0xffff0000, v61
	v_cmp_lt_u32_e32 vcc, 9, v3
	v_pk_fma_f32 v[8:9], v[44:45], v[50:51], v[8:9] op_sel_hi:[0,1,1]
	v_pk_fma_f32 v[42:43], v[44:45], v[46:47], v[42:43] op_sel_hi:[0,1,1]
	v_cndmask_b32_e64 v44, 0, 1.0, vcc
	v_lshlrev_b32_e32 v46, 16, v54
	v_and_b32_e32 v47, 0xffff0000, v54
	v_lshlrev_b32_e32 v50, 16, v55
	v_and_b32_e32 v51, 0xffff0000, v55
	v_cmp_lt_u32_e32 vcc, 10, v3
	v_pk_fma_f32 v[42:43], v[44:45], v[46:47], v[42:43] op_sel_hi:[0,1,1]
	v_pk_fma_f32 v[8:9], v[44:45], v[50:51], v[8:9] op_sel_hi:[0,1,1]
	v_cndmask_b32_e64 v44, 0, 1.0, vcc
	v_lshlrev_b32_e32 v46, 16, v48
	v_and_b32_e32 v47, 0xffff0000, v48
	v_lshlrev_b32_e32 v48, 16, v49
	v_and_b32_e32 v49, 0xffff0000, v49
	v_cmp_lt_u32_e32 vcc, 11, v3
	v_pk_fma_f32 v[8:9], v[44:45], v[48:49], v[8:9] op_sel_hi:[0,1,1]
	v_pk_fma_f32 v[42:43], v[44:45], v[46:47], v[42:43] op_sel_hi:[0,1,1]
	v_cndmask_b32_e64 v44, 0, 1.0, vcc
	v_lshlrev_b32_e32 v46, 16, v70
	v_and_b32_e32 v47, 0xffff0000, v70
	v_lshlrev_b32_e32 v48, 16, v71
	v_and_b32_e32 v49, 0xffff0000, v71
	v_cmp_lt_u32_e32 vcc, 12, v3
	v_pk_fma_f32 v[42:43], v[44:45], v[46:47], v[42:43] op_sel_hi:[0,1,1]
	v_pk_fma_f32 v[8:9], v[44:45], v[48:49], v[8:9] op_sel_hi:[0,1,1]
	v_cndmask_b32_e64 v44, 0, 1.0, vcc
	v_lshlrev_b32_e32 v46, 16, v66
	v_and_b32_e32 v47, 0xffff0000, v66
	v_lshlrev_b32_e32 v48, 16, v67
	v_and_b32_e32 v49, 0xffff0000, v67
	v_cmp_lt_u32_e32 vcc, 13, v3
	v_pk_fma_f32 v[8:9], v[44:45], v[48:49], v[8:9] op_sel_hi:[0,1,1]
	v_pk_fma_f32 v[42:43], v[44:45], v[46:47], v[42:43] op_sel_hi:[0,1,1]
	v_cndmask_b32_e64 v44, 0, 1.0, vcc
	v_lshlrev_b32_e32 v46, 16, v58
	v_and_b32_e32 v47, 0xffff0000, v58
	v_lshlrev_b32_e32 v48, 16, v59
; __device__ __forceinline__ unsigned pk2(float lo, float hi) { f32x2 v = {lo, hi}; bf16x2_t b = __builtin_convertvector(v, bf16x2_t); return __builtin_bit_cast(unsigned, b); }
; __device__ __forceinline__ float bflo(unsigned u) { return __uint_as_float(u << 16); }
; __device__ __forceinline__ float bfhi(unsigned u) { return __uint_as_float(u & 0xffff0000u); }
; __device__ __forceinline__ void prep_load(PrepRow& d, const PrepArgs& a, int row, int lane) {
;     const bf16_t* pr = a.PA + (size_t)row * PA_LD; const int ts = row & (SEQ - 1);
;     { const int fi = ((lane & 7) * 4) & 15; d.r1 = *(const u32x2*)(pr + 896 + fi); d.r2 = *(const u32x2*)(pr + 912 + fi);
;       d.c = *(const f32x4*)(a.cs + ts * 16 + fi); d.s = *(const f32x4*)(a.sn + ts * 16 + fi); }
;     { const int win = 2 << (lane >> 4); const int n = (ts + 1 < win) ? ts + 1 : win;
; #pragma unroll
;       for (int i = 0; i < 16; ++i) { const int ii = (i < n) ? i : 0; d.pool[i] = *(const u32x2*)(pr - (size_t)ii * PA_LD + 4 * lane); } }
; #pragma unroll
;     for (int j = 0; j < 4; ++j) { const int back = (ts - 3 + j >= 0) ? (3 - j) : 0; d.cv[j] = *(const u32x2*)(pr - (size_t)back * PA_LD + 256 + 4 * lane); }
; }
; __device__ __forceinline__ void prep_compute(const PrepRow& d, const PrepArgs& a, int row, int lane) {
;     ...
;     { const int win = 2 << (lane >> 4); const int n = (ts + 1 < win) ? ts + 1 : win;
;       f32x4 sum = {0.f, 0.f, 0.f, 0.f};
; #pragma unroll
;       for (int i = 0; i < 16; ++i) { const float mk = (i < n) ? 1.f : 0.f; const f32x4 v = {bflo(d.pool[i].x), bfhi(d.pool[i].x), bflo(d.pool[i].y), bfhi(d.pool[i].y)}; sum += v * mk; }
;       const f32x4 self = {bflo(d.pool[0].x), bfhi(d.pool[0].x), bflo(d.pool[0].y), bfhi(d.pool[0].y)};
;       const f32x4 o = sum * (1.0f / (float)n) - self;
;       u32x2 w; w.x = pk2(o[0], o[1]); w.y = pk2(o[2], o[3]);
;       *(u32x2*)(a.PM + (size_t)row * 1024 + 4 * lane) = w; }
;     { f32x4 accv = *(const f32x4*)(a.convb + 4 * lane);
; #pragma unroll
;       for (int j = 0; j < 4; ++j) { const float mk = (ts - 3 + j >= 0) ? 1.f : 0.f; const f32x4 v = {bflo(d.cv[j].x), bfhi(d.cv[j].x), bflo(d.cv[j].y), bfhi(d.cv[j].y)};
;           accv += v * mk * *(const f32x4*)(a.convw + j * 256 + 4 * lane); }
;       u32x2 w; w.x = pk2(accv[0], accv[1]); w.y = pk2(accv[2], accv[3]);
;       *(u32x2*)(a.uconv + (size_t)row * 256 + 4 * lane) = w; }
	v_and_b32_e32 v49, 0xffff0000, v59
	v_cmp_lt_u32_e32 vcc, 14, v3
	v_pk_fma_f32 v[42:43], v[44:45], v[46:47], v[42:43] op_sel_hi:[0,1,1]
	v_pk_fma_f32 v[8:9], v[44:45], v[48:49], v[8:9] op_sel_hi:[0,1,1]
	v_cndmask_b32_e64 v44, 0, 1.0, vcc
	v_lshlrev_b32_e32 v46, 16, v52
	v_and_b32_e32 v47, 0xffff0000, v52
	v_lshlrev_b32_e32 v48, 16, v53
	v_and_b32_e32 v49, 0xffff0000, v53
	v_cmp_lt_u32_e32 vcc, 15, v3
	v_cvt_f32_ubyte0_e32 v3, v3
	v_pk_fma_f32 v[8:9], v[44:45], v[48:49], v[8:9] op_sel_hi:[0,1,1]
	v_pk_fma_f32 v[42:43], v[44:45], v[46:47], v[42:43] op_sel_hi:[0,1,1]
	v_div_scale_f32 v45, s[0:1], v3, v3, 1.0
	v_rcp_f32_e32 v50, v45
	v_cndmask_b32_e64 v44, 0, 1.0, vcc
	v_lshlrev_b32_e32 v46, 16, v64
	v_and_b32_e32 v47, 0xffff0000, v64
	v_lshlrev_b32_e32 v48, 16, v65
	v_and_b32_e32 v49, 0xffff0000, v65
	v_pk_fma_f32 v[42:43], v[44:45], v[46:47], v[42:43] op_sel_hi:[0,1,1]
	v_pk_fma_f32 v[8:9], v[44:45], v[48:49], v[8:9] op_sel_hi:[0,1,1]
	v_fma_f32 v44, -v45, v50, 1.0
	v_fmac_f32_e32 v50, v44, v50
	v_div_scale_f32 v44, vcc, 1.0, v3, 1.0
	v_mul_f32_e32 v46, v44, v50
	v_fma_f32 v47, -v45, v46, v44
	v_fmac_f32_e32 v46, v47, v50
	v_fma_f32 v44, -v45, v46, v44
	v_div_fmas_f32 v44, v44, v50, v46
	v_div_fixup_f32 v44, v44, v3, 1.0
	v_xor_b32_e32 v7, 0x80000000, v7
	v_xor_b32_e32 v6, 0x80000000, v6
	v_xor_b32_e32 v5, 0x80000000, v5
	v_xor_b32_e32 v4, 0x80000000, v4
	s_lshl_b64 s[30:31], s[20:21], 11
	v_pk_fma_f32 v[6:7], v[44:45], v[8:9], v[6:7] op_sel_hi:[0,1,1]
	v_pk_fma_f32 v[4:5], v[44:45], v[42:43], v[4:5] op_sel_hi:[0,1,1]
	v_cvt_pk_bf16_f32 v4, v4, v5
	v_cvt_pk_bf16_f32 v5, v6, v7
	v_lshl_add_u64 v[6:7], v[22:23], 0, s[30:31]
	global_store_dwordx2 v[6:7], v[4:5], off
	v_mov_b64_e32 v[4:5], v[146:147]
	v_mov_b64_e32 v[6:7], v[148:149]
	s_nop 0
	v_mov_b64_e32 v[42:43], v[150:151]
	v_mov_b64_e32 v[44:45], v[152:153]
	v_mov_b64_e32 v[46:47], v[154:155]
	v_mov_b64_e32 v[48:49], v[156:157]
	v_mov_b64_e32 v[50:51], v[158:159]
	v_mov_b64_e32 v[52:53], v[160:161]
	v_mov_b64_e32 v[54:55], v[162:163]
	v_mov_b64_e32 v[56:57], v[164:165]
	s_cmp_gt_u32 s14, 2
	s_cselect_b64 s[16:17], -1, 0
	s_cmp_gt_u32 s14, 1
	s_cselect_b64 s[14:15], -1, 0
	s_lshl_b64 s[36:37], s[20:21], 9
	s_cmp_lt_i32 s13, 0x8000
	s_cselect_b32 s0, s13, s20
	s_mul_i32 s13, s0, 0xa00
	v_cndmask_b32_e64 v8, 0, 1.0, s[16:17]
	v_lshlrev_b32_e32 v58, 16, v40
	v_and_b32_e32 v59, 0xffff0000, v40
	v_lshlrev_b32_e32 v40, 16, v41
	v_and_b32_e32 v41, 0xffff0000, v41
	s_mul_hi_i32 s1, s0, 0xa00
	s_add_u32 s40, s60, s13
	v_pk_mul_f32 v[40:41], v[8:9], v[40:41] op_sel_hi:[0,1]
	v_pk_mul_f32 v[8:9], v[8:9], v[58:59] op_sel_hi:[0,1]
	s_addc_u32 s41, s61, s1
	s_and_b32 s13, s0, 0xfff
	s_add_i32 s19, s13, 1
	v_min_u32_e32 v64, s19, v122
	v_cmp_lt_u32_e32 vcc, 2, v64
	s_lshl_b32 s42, s13, 6
	s_mov_b32 s43, s49
	s_cmp_eq_u32 s13, 0
	s_cselect_b32 s45, 0, -1
	s_cselect_b32 s44, 0, 0xfffff600
	s_cmp_lt_u32 s13, 3
	s_cselect_b32 s0, 0, 0xffffe200
	s_cselect_b32 s1, 0, -1
	s_add_u32 s0, s40, s0
	s_addc_u32 s1, s41, s1
	s_cmp_lt_u32 s13, 2
	s_cselect_b32 s20, 0, 0xffffec00
	s_cselect_b32 s13, 0, -1
	s_add_u32 s20, s40, s20
	s_addc_u32 s21, s41, s13
	s_add_u32 s30, s40, s44
	s_addc_u32 s31, s41, s45
	v_lshl_add_u64 v[86:87], s[20:21], 0, v[32:33]
	v_lshl_add_u64 v[90:91], s[30:31], 0, v[32:33]
	v_mov_b32_e32 v238, 0xffffce00
	v_mov_b32_e32 v239, 0xffffc400
	v_mov_b32_e32 v240, 0xffffba00
	v_mov_b32_e32 v241, 0xffffb000
	v_mov_b32_e32 v242, 0xffffa600
	v_mov_b32_e32 v243, 0xffff9c00
	v_mov_b32_e32 v244, 0xffff9200
	v_mov_b32_e32 v245, 0xffff8800
	v_mov_b32_e32 v223, 0xffff7e00
	v_mov_b32_e32 v228, 0xffff7400
	v_mov_b32_e32 v227, 0xffff6a00
	s_cmpk_gt_i32 s24, 0x7fff
	s_nop 0
	v_pk_fma_f32 v[4:5], v[8:9], v[42:43], v[4:5]
	v_pk_fma_f32 v[6:7], v[40:41], v[44:45], v[6:7]
	v_cndmask_b32_e64 v8, 0, 1.0, s[14:15]
	v_lshlrev_b32_e32 v40, 16, v38
	v_and_b32_e32 v41, 0xffff0000, v38
	v_lshlrev_b32_e32 v38, 16, v39
	v_and_b32_e32 v39, 0xffff0000, v39
	v_pk_mul_f32 v[40:41], v[8:9], v[40:41] op_sel_hi:[0,1]
	v_pk_mul_f32 v[8:9], v[8:9], v[38:39] op_sel_hi:[0,1]
	v_pk_fma_f32 v[6:7], v[8:9], v[48:49], v[6:7]
	v_lshlrev_b32_e32 v8, 16, v36
	v_and_b32_e32 v9, 0xffff0000, v36
	v_lshlrev_b32_e32 v36, 16, v37
	v_and_b32_e32 v37, 0xffff0000, v37
	v_pk_fma_f32 v[4:5], v[40:41], v[46:47], v[4:5]
	v_pk_mul_f32 v[36:37], v[2:3], v[36:37] op_sel_hi:[0,1]
	v_pk_mul_f32 v[2:3], v[2:3], v[8:9] op_sel_hi:[0,1]
	v_pk_fma_f32 v[2:3], v[2:3], v[50:51], v[4:5]
	v_pk_fma_f32 v[4:5], v[36:37], v[52:53], v[6:7]
	v_lshlrev_b32_e32 v6, 16, v34
	v_and_b32_e32 v7, 0xffff0000, v34
	v_lshlrev_b32_e32 v8, 16, v35
	v_and_b32_e32 v9, 0xffff0000, v35
	v_lshl_add_u64 v[34:35], s[40:41], 0, v[32:33]
	v_cndmask_b32_e64 v37, 0, -1, vcc
	v_cndmask_b32_e32 v36, 0, v123, vcc
	v_cmp_lt_u32_e32 vcc, 3, v64
	v_pk_fma_f32 v[4:5], v[56:57], v[8:9], v[4:5]
	v_pk_fma_f32 v[2:3], v[54:55], v[6:7], v[2:3]
	v_lshl_add_u64 v[124:125], v[34:35], 0, v[36:37]
	v_cndmask_b32_e64 v37, 0, -1, vcc
	v_cndmask_b32_e32 v36, 0, v132, vcc
	v_cmp_lt_u32_e32 vcc, 4, v64
	v_cvt_pk_bf16_f32 v2, v2, v3
	v_cvt_pk_bf16_f32 v3, v4, v5
	v_lshl_add_u64 v[4:5], v[28:29], 0, s[36:37]
	v_cndmask_b32_e64 v39, 0, -1, vcc
	v_cndmask_b32_e32 v38, 0, v133, vcc
	v_cmp_lt_u32_e32 vcc, 5, v64
	global_store_dwordx2 v[4:5], v[2:3], off
	v_lshl_add_u64 v[2:3], s[40:41], 0, v[0:1]
	v_cndmask_b32_e64 v41, 0, -1, vcc
	v_cndmask_b32_e32 v40, 0, v134, vcc
	v_cmp_lt_u32_e32 vcc, 6, v64
	global_load_dwordx2 v[44:45], v[2:3], off offset:1792
	global_load_dwordx2 v[42:43], v[2:3], off offset:1824
	v_cndmask_b32_e64 v47, 0, -1, vcc
	v_cndmask_b32_e32 v46, 0, v135, vcc
	v_lshl_add_u64 v[2:3], v[18:19], 0, s[42:43]
; __device__ __forceinline__ unsigned pk2(float lo, float hi) { f32x2 v = {lo, hi}; bf16x2_t b = __builtin_convertvector(v, bf16x2_t); return __builtin_bit_cast(unsigned, b); }
; __device__ __forceinline__ float bflo(unsigned u) { return __uint_as_float(u << 16); }
; __device__ __forceinline__ void prep_load(PrepRow& d, const PrepArgs& a, int row, int lane) {
;     const bf16_t* pr = a.PA + (size_t)row * PA_LD; const int ts = row & (SEQ - 1);
;     { const int fi = ((lane & 7) * 4) & 15; d.r1 = *(const u32x2*)(pr + 896 + fi); d.r2 = *(const u32x2*)(pr + 912 + fi);
;       d.c = *(const f32x4*)(a.cs + ts * 16 + fi); d.s = *(const f32x4*)(a.sn + ts * 16 + fi); }
;     { const int win = 2 << (lane >> 4); const int n = (ts + 1 < win) ? ts + 1 : win;
; #pragma unroll
;       for (int i = 0; i < 16; ++i) { const int ii = (i < n) ? i : 0; d.pool[i] = *(const u32x2*)(pr - (size_t)ii * PA_LD + 4 * lane); } }
; #pragma unroll
;     for (int j = 0; j < 4; ++j) { const int back = (ts - 3 + j >= 0) ? (3 - j) : 0; d.cv[j] = *(const u32x2*)(pr - (size_t)back * PA_LD + 256 + 4 * lane); }
; }
; __device__ __forceinline__ void prep_compute(const PrepRow& d, const PrepArgs& a, int row, int lane) {
;     const int ts = row & (SEQ - 1);
;     { const int hh = lane >> 3, jj = (lane & 7) * 4;
;       const f32x4 x1 = {bflo(d.r1.x), bfhi(d.r1.x), bflo(d.r1.y), bfhi(d.r1.y)}, x2 = {bflo(d.r2.x), bfhi(d.r2.x), bflo(d.r2.y), bfhi(d.r2.y)};
;       const f32x4 o = (jj < 16) ? (x1 * d.c - x2 * d.s) : (x2 * d.c + x1 * d.s);
;       u32x2 w; w.x = pk2(o[0], o[1]); w.y = pk2(o[2], o[3]);
;       *(u32x2*)(a.Kb + (size_t)row * 768 + hh * 96 + 64 + jj) = w; }
;     { const int win = 2 << (lane >> 4); const int n = (ts + 1 < win) ? ts + 1 : win;
;       f32x4 sum = {0.f, 0.f, 0.f, 0.f};
; #pragma unroll
;       for (int i = 0; i < 16; ++i) { const float mk = (i < n) ? 1.f : 0.f; const f32x4 v = {bflo(d.pool[i].x), bfhi(d.pool[i].x), bflo(d.pool[i].y), bfhi(d.pool[i].y)}; sum += v * mk; }
;       const f32x4 self = {bflo(d.pool[0].x), bfhi(d.pool[0].x), bflo(d.pool[0].y), bfhi(d.pool[0].y)};
; __device__ __forceinline__ void prep_phase(const PrepArgs& a, int gw, int NGW, int lane) {
;     ...
;         prep_load(dA, a, r2 < TOK ? r2 : row, lane);
;         if (r1 < TOK) prep_compute(dB, a, r1, lane);
;         asm volatile("" ::: "memory");
	v_lshl_add_u64 v[6:7], v[20:21], 0, s[42:43]
	v_lshl_add_u64 v[36:37], v[34:35], 0, v[36:37]
	v_lshl_add_u64 v[46:47], v[34:35], 0, v[46:47]
	v_cmp_lt_u32_e32 vcc, 7, v64
	global_load_dwordx4 v[2:5], v[2:3], off
	s_nop 0
	global_load_dwordx4 v[6:9], v[6:7], off
	v_lshl_add_u64 v[38:39], v[34:35], 0, v[38:39]
	v_lshl_add_u64 v[40:41], v[34:35], 0, v[40:41]
	global_load_dwordx2 v[62:63], v[36:37], off
	global_load_dwordx2 v[56:57], v[38:39], off
	global_load_dwordx2 v[50:51], v[40:41], off
	s_nop 0
	global_load_dwordx2 v[46:47], v[46:47], off
	v_cndmask_b32_e64 v37, 0, -1, vcc
	v_cndmask_b32_e32 v36, 0, v136, vcc
	v_cmp_lt_u32_e32 vcc, 8, v64
	v_lshl_add_u64 v[36:37], v[34:35], 0, v[36:37]
	v_lshl_add_u64 v[82:83], v[34:35], 0, s[44:45]
	v_cndmask_b32_e64 v39, 0, -1, vcc
	v_cndmask_b32_e32 v38, 0, v137, vcc
	v_cmp_lt_u32_e32 vcc, 9, v64
	v_lshl_add_u64 v[38:39], v[34:35], 0, v[38:39]
	s_nop 0
	v_cndmask_b32_e64 v41, 0, -1, vcc
	v_cndmask_b32_e32 v40, 0, v138, vcc
	v_cmp_lt_u32_e32 vcc, 10, v64
	v_lshl_add_u64 v[40:41], v[34:35], 0, v[40:41]
	s_nop 0
	v_cndmask_b32_e64 v49, 0, -1, vcc
	v_cndmask_b32_e32 v48, 0, v139, vcc
	v_lshl_add_u64 v[48:49], v[34:35], 0, v[48:49]
	v_cmp_lt_u32_e32 vcc, 11, v64
	global_load_dwordx2 v[68:69], v[36:37], off
	global_load_dwordx2 v[60:61], v[38:39], off
	global_load_dwordx2 v[54:55], v[40:41], off
	s_nop 0
	global_load_dwordx2 v[48:49], v[48:49], off
	v_cndmask_b32_e64 v37, 0, -1, vcc
	v_cndmask_b32_e32 v36, 0, v140, vcc
	v_cmp_lt_u32_e32 vcc, 12, v64
	v_lshl_add_u64 v[36:37], v[34:35], 0, v[36:37]
	s_nop 0
	v_cndmask_b32_e64 v39, 0, -1, vcc
	v_cndmask_b32_e32 v38, 0, v141, vcc
	v_cmp_lt_u32_e32 vcc, 13, v64
	v_lshl_add_u64 v[38:39], v[34:35], 0, v[38:39]
	s_nop 0
	v_cndmask_b32_e64 v41, 0, -1, vcc
	v_cndmask_b32_e32 v40, 0, v142, vcc
	v_cmp_lt_u32_e32 vcc, 14, v64
	v_lshl_add_u64 v[40:41], v[34:35], 0, v[40:41]
	s_nop 0
	v_cndmask_b32_e64 v53, 0, -1, vcc
	v_cndmask_b32_e32 v52, 0, v143, vcc
	v_lshl_add_u64 v[52:53], v[34:35], 0, v[52:53]
	v_cmp_lt_u32_e32 vcc, 15, v64
	global_load_dwordx2 v[70:71], v[36:37], off
	global_load_dwordx2 v[66:67], v[38:39], off
	global_load_dwordx2 v[58:59], v[40:41], off
	s_nop 0
	global_load_dwordx2 v[52:53], v[52:53], off
	v_cndmask_b32_e64 v37, 0, -1, vcc
	v_cndmask_b32_e32 v36, 0, v144, vcc
	v_lshl_add_u64 v[36:37], v[34:35], 0, v[36:37]
	v_lshl_add_u64 v[38:39], s[0:1], 0, v[32:33]
	global_load_dwordx2 v[64:65], v[36:37], off
	global_load_dwordx2 v[40:41], v[38:39], off offset:512
	s_nop 0
	global_load_dwordx2 v[38:39], v[86:87], off offset:512
	global_load_dwordx2 v[36:37], v[90:91], off offset:512
	s_nop 0
	global_load_dwordx2 v[90:91], v[34:35], off
	global_load_dwordx2 v[86:87], v[82:83], off
	s_nop 0
	global_load_dwordx2 v[82:83], v[124:125], off
	s_nop 0
	global_load_dwordx2 v[34:35], v[34:35], off offset:512
	s_cbranch_scc1 .LBB0_563
	s_waitcnt vmcnt(27)
	v_lshlrev_b32_e32 v126, 16, v112
	v_and_b32_e32 v127, 0xffff0000, v112
	v_lshlrev_b32_e32 v112, 16, v113
	v_and_b32_e32 v113, 0xffff0000, v113
	v_lshlrev_b32_e32 v124, 16, v114
	v_and_b32_e32 v125, 0xffff0000, v114
	v_lshlrev_b32_e32 v114, 16, v115
	v_and_b32_e32 v115, 0xffff0000, v115
	v_pk_mul_f32 v[128:129], v[12:13], v[112:113]
	v_pk_mul_f32 v[130:131], v[10:11], v[126:127]
	v_pk_fma_f32 v[128:129], v[16:17], v[114:115], v[128:129] neg_lo:[0,0,1] neg_hi:[0,0,1]
	v_pk_fma_f32 v[130:131], v[14:15], v[124:125], v[130:131] neg_lo:[0,0,1] neg_hi:[0,0,1]
	v_pk_mul_f32 v[16:17], v[16:17], v[112:113]
	v_pk_mul_f32 v[14:15], v[14:15], v[126:127]
	v_pk_fma_f32 v[12:13], v[12:13], v[114:115], v[16:17]
	v_pk_fma_f32 v[10:11], v[10:11], v[124:125], v[14:15]
	s_and_b32 s0, s24, 0xfff
	v_cndmask_b32_e64 v13, v13, v129, s[38:39]
	v_cndmask_b32_e64 v12, v12, v128, s[38:39]
	v_cndmask_b32_e64 v11, v11, v131, s[38:39]
	v_cndmask_b32_e64 v10, v10, v130, s[38:39]
	s_ashr_i32 s25, s24, 31
	s_add_i32 s1, s0, 1
	v_cvt_pk_bf16_f32 v10, v10, v11
	v_cvt_pk_bf16_f32 v11, v12, v13
	v_mad_i64_i32 v[12:13], s[14:15], s24, v229, v[30:31]
	s_cmp_eq_u32 s0, 0
	global_store_dwordx2 v[12:13], v[10:11], off offset:128
	v_min_u32_e32 v11, s1, v122
	v_lshlrev_b32_e32 v12, 16, v120
	v_and_b32_e32 v13, 0xffff0000, v120
	v_lshlrev_b32_e32 v14, 16, v121
	v_and_b32_e32 v15, 0xffff0000, v121
	s_cselect_b64 s[14:15], -1, 0
	v_pk_add_f32 v[16:17], v[14:15], 0 op_sel_hi:[1,0]
	v_pk_add_f32 v[112:113], v[12:13], 0 op_sel_hi:[1,0]
	v_cndmask_b32_e64 v10, 1.0, 0, s[14:15]
	v_lshlrev_b32_e32 v114, 16, v118
	v_and_b32_e32 v115, 0xffff0000, v118
	v_lshlrev_b32_e32 v118, 16, v119
	v_and_b32_e32 v119, 0xffff0000, v119
	v_cmp_lt_u32_e32 vcc, 2, v11
	v_pk_fma_f32 v[112:113], v[10:11], v[114:115], v[112:113] op_sel_hi:[0,1,1]
	v_pk_fma_f32 v[16:17], v[10:11], v[118:119], v[16:17] op_sel_hi:[0,1,1]
	v_cndmask_b32_e64 v114, 0, 1.0, vcc
	v_lshlrev_b32_e32 v118, 16, v116
	v_and_b32_e32 v119, 0xffff0000, v116
	v_lshlrev_b32_e32 v116, 16, v117
	v_and_b32_e32 v117, 0xffff0000, v117
	v_cmp_lt_u32_e32 vcc, 3, v11
	v_pk_fma_f32 v[16:17], v[114:115], v[116:117], v[16:17] op_sel_hi:[0,1,1]
	v_pk_fma_f32 v[112:113], v[114:115], v[118:119], v[112:113] op_sel_hi:[0,1,1]
	v_cndmask_b32_e64 v114, 0, 1.0, vcc
	v_lshlrev_b32_e32 v116, 16, v110
	v_and_b32_e32 v117, 0xffff0000, v110
	v_lshlrev_b32_e32 v110, 16, v111
	v_and_b32_e32 v111, 0xffff0000, v111
	v_cmp_lt_u32_e32 vcc, 4, v11
	v_pk_fma_f32 v[112:113], v[114:115], v[116:117], v[112:113] op_sel_hi:[0,1,1]
	v_pk_fma_f32 v[16:17], v[114:115], v[110:111], v[16:17] op_sel_hi:[0,1,1]
	v_cndmask_b32_e64 v110, 0, 1.0, vcc
	v_lshlrev_b32_e32 v114, 16, v108
	v_and_b32_e32 v115, 0xffff0000, v108
	v_lshlrev_b32_e32 v108, 16, v109
; __device__ __forceinline__ float bflo(unsigned u) { return __uint_as_float(u << 16); }
; __device__ __forceinline__ float bfhi(unsigned u) { return __uint_as_float(u & 0xffff0000u); }
; __device__ __forceinline__ void prep_compute(const PrepRow& d, const PrepArgs& a, int row, int lane) {
;     ...
;     { const int win = 2 << (lane >> 4); const int n = (ts + 1 < win) ? ts + 1 : win;
;       f32x4 sum = {0.f, 0.f, 0.f, 0.f};
; #pragma unroll
;       for (int i = 0; i < 16; ++i) { const float mk = (i < n) ? 1.f : 0.f; const f32x4 v = {bflo(d.pool[i].x), bfhi(d.pool[i].x), bflo(d.pool[i].y), bfhi(d.pool[i].y)}; sum += v * mk; }
;       const f32x4 self = {bflo(d.pool[0].x), bfhi(d.pool[0].x), bflo(d.pool[0].y), bfhi(d.pool[0].y)};
	v_and_b32_e32 v109, 0xffff0000, v109
	v_cmp_lt_u32_e32 vcc, 5, v11
	v_pk_fma_f32 v[16:17], v[110:111], v[108:109], v[16:17] op_sel_hi:[0,1,1]
	v_pk_fma_f32 v[108:109], v[110:111], v[114:115], v[112:113] op_sel_hi:[0,1,1]
	v_cndmask_b32_e64 v110, 0, 1.0, vcc
	v_lshlrev_b32_e32 v112, 16, v104
	v_and_b32_e32 v113, 0xffff0000, v104
	v_lshlrev_b32_e32 v104, 16, v105
	v_and_b32_e32 v105, 0xffff0000, v105
	v_cmp_lt_u32_e32 vcc, 6, v11
	v_pk_fma_f32 v[108:109], v[110:111], v[112:113], v[108:109] op_sel_hi:[0,1,1]
	v_pk_fma_f32 v[16:17], v[110:111], v[104:105], v[16:17] op_sel_hi:[0,1,1]
	v_cndmask_b32_e64 v104, 0, 1.0, vcc
	v_lshlrev_b32_e32 v110, 16, v100
	v_and_b32_e32 v111, 0xffff0000, v100
	v_lshlrev_b32_e32 v100, 16, v101
	v_and_b32_e32 v101, 0xffff0000, v101
	v_cmp_lt_u32_e32 vcc, 7, v11
	v_pk_fma_f32 v[16:17], v[104:105], v[100:101], v[16:17] op_sel_hi:[0,1,1]
	v_pk_fma_f32 v[100:101], v[104:105], v[110:111], v[108:109] op_sel_hi:[0,1,1]
	v_cndmask_b32_e64 v104, 0, 1.0, vcc
	v_lshlrev_b32_e32 v108, 16, v106
	v_and_b32_e32 v109, 0xffff0000, v106
	v_lshlrev_b32_e32 v106, 16, v107
	v_and_b32_e32 v107, 0xffff0000, v107
	v_cmp_lt_u32_e32 vcc, 8, v11
	v_pk_fma_f32 v[100:101], v[104:105], v[108:109], v[100:101] op_sel_hi:[0,1,1]
	v_pk_fma_f32 v[16:17], v[104:105], v[106:107], v[16:17] op_sel_hi:[0,1,1]
	v_cndmask_b32_e64 v104, 0, 1.0, vcc
	v_lshlrev_b32_e32 v106, 16, v102
	v_and_b32_e32 v107, 0xffff0000, v102
	v_lshlrev_b32_e32 v102, 16, v103
	v_and_b32_e32 v103, 0xffff0000, v103
	v_cmp_lt_u32_e32 vcc, 9, v11
	v_pk_fma_f32 v[16:17], v[104:105], v[102:103], v[16:17] op_sel_hi:[0,1,1]
	v_pk_fma_f32 v[100:101], v[104:105], v[106:107], v[100:101] op_sel_hi:[0,1,1]
	v_cndmask_b32_e64 v102, 0, 1.0, vcc
	v_lshlrev_b32_e32 v104, 16, v96
	v_and_b32_e32 v105, 0xffff0000, v96
	v_lshlrev_b32_e32 v96, 16, v97
	v_and_b32_e32 v97, 0xffff0000, v97
	v_cmp_lt_u32_e32 vcc, 10, v11
	v_pk_fma_f32 v[100:101], v[102:103], v[104:105], v[100:101] op_sel_hi:[0,1,1]
	v_pk_fma_f32 v[16:17], v[102:103], v[96:97], v[16:17] op_sel_hi:[0,1,1]
	v_cndmask_b32_e64 v96, 0, 1.0, vcc
	v_lshlrev_b32_e32 v102, 16, v92
	v_and_b32_e32 v103, 0xffff0000, v92
	v_lshlrev_b32_e32 v92, 16, v93
	v_and_b32_e32 v93, 0xffff0000, v93
	v_cmp_lt_u32_e32 vcc, 11, v11
	v_pk_fma_f32 v[16:17], v[96:97], v[92:93], v[16:17] op_sel_hi:[0,1,1]
	v_pk_fma_f32 v[92:93], v[96:97], v[102:103], v[100:101] op_sel_hi:[0,1,1]
	v_cndmask_b32_e64 v96, 0, 1.0, vcc
	v_lshlrev_b32_e32 v100, 16, v98
	v_and_b32_e32 v101, 0xffff0000, v98
	v_lshlrev_b32_e32 v98, 16, v99
	v_and_b32_e32 v99, 0xffff0000, v99
	v_cmp_lt_u32_e32 vcc, 12, v11
	v_pk_fma_f32 v[92:93], v[96:97], v[100:101], v[92:93] op_sel_hi:[0,1,1]
	v_pk_fma_f32 v[16:17], v[96:97], v[98:99], v[16:17] op_sel_hi:[0,1,1]
	v_cndmask_b32_e64 v96, 0, 1.0, vcc
	v_lshlrev_b32_e32 v98, 16, v94
	v_and_b32_e32 v99, 0xffff0000, v94
	v_lshlrev_b32_e32 v94, 16, v95
	v_and_b32_e32 v95, 0xffff0000, v95
	v_cmp_lt_u32_e32 vcc, 13, v11
	v_pk_fma_f32 v[16:17], v[96:97], v[94:95], v[16:17] op_sel_hi:[0,1,1]
	v_pk_fma_f32 v[92:93], v[96:97], v[98:99], v[92:93] op_sel_hi:[0,1,1]
	v_cndmask_b32_e64 v94, 0, 1.0, vcc
	v_lshlrev_b32_e32 v96, 16, v88
	v_and_b32_e32 v97, 0xffff0000, v88
	v_lshlrev_b32_e32 v88, 16, v89
	v_and_b32_e32 v89, 0xffff0000, v89
	v_cmp_lt_u32_e32 vcc, 14, v11
	v_pk_fma_f32 v[16:17], v[94:95], v[88:89], v[16:17] op_sel_hi:[0,1,1]
	v_pk_fma_f32 v[92:93], v[94:95], v[96:97], v[92:93] op_sel_hi:[0,1,1]
	v_cndmask_b32_e64 v88, 0, 1.0, vcc
	v_cmp_lt_u32_e32 vcc, 15, v11
	v_cvt_f32_ubyte0_e32 v11, v11
	v_lshlrev_b32_e32 v94, 16, v84
; __device__ __forceinline__ unsigned pk2(float lo, float hi) { f32x2 v = {lo, hi}; bf16x2_t b = __builtin_convertvector(v, bf16x2_t); return __builtin_bit_cast(unsigned, b); }
; __device__ __forceinline__ float bflo(unsigned u) { return __uint_as_float(u << 16); }
; __device__ __forceinline__ float bfhi(unsigned u) { return __uint_as_float(u & 0xffff0000u); }
; __device__ __forceinline__ void prep_compute(const PrepRow& d, const PrepArgs& a, int row, int lane) {
;     ...
;     { const int win = 2 << (lane >> 4); const int n = (ts + 1 < win) ? ts + 1 : win;
;       f32x4 sum = {0.f, 0.f, 0.f, 0.f};
; #pragma unroll
;       for (int i = 0; i < 16; ++i) { const float mk = (i < n) ? 1.f : 0.f; const f32x4 v = {bflo(d.pool[i].x), bfhi(d.pool[i].x), bflo(d.pool[i].y), bfhi(d.pool[i].y)}; sum += v * mk; }
;       const f32x4 self = {bflo(d.pool[0].x), bfhi(d.pool[0].x), bflo(d.pool[0].y), bfhi(d.pool[0].y)};
;       const f32x4 o = sum * (1.0f / (float)n) - self;
;       u32x2 w; w.x = pk2(o[0], o[1]); w.y = pk2(o[2], o[3]);
;       *(u32x2*)(a.PM + (size_t)row * 1024 + 4 * lane) = w; }
;     { f32x4 accv = *(const f32x4*)(a.convb + 4 * lane);
; #pragma unroll
;       for (int j = 0; j < 4; ++j) { const float mk = (ts - 3 + j >= 0) ? 1.f : 0.f; const f32x4 v = {bflo(d.cv[j].x), bfhi(d.cv[j].x), bflo(d.cv[j].y), bfhi(d.cv[j].y)};
;           accv += v * mk * *(const f32x4*)(a.convw + j * 256 + 4 * lane); }
;       u32x2 w; w.x = pk2(accv[0], accv[1]); w.y = pk2(accv[2], accv[3]);
;       *(u32x2*)(a.uconv + (size_t)row * 256 + 4 * lane) = w; }
; __device__ __forceinline__ void prep_phase(const PrepArgs& a, int gw, int NGW, int lane) {
;     ...
;     for (; row < TOK; row += 2 * NGW) {
;         const int r1 = row + NGW, r2 = row + 2 * NGW;
;         prep_load(dB, a, r1 < TOK ? r1 : row, lane);
;         prep_compute(dA, a, row, lane); asm volatile("" ::: "memory");
;         prep_load(dA, a, r2 < TOK ? r2 : row, lane);
;         if (r1 < TOK) prep_compute(dB, a, r1, lane);
;         asm volatile("" ::: "memory");
;     }
	v_and_b32_e32 v95, 0xffff0000, v84
	v_lshlrev_b32_e32 v84, 16, v85
	v_and_b32_e32 v85, 0xffff0000, v85
	v_div_scale_f32 v33, s[14:15], v11, v11, 1.0
	v_pk_fma_f32 v[16:17], v[88:89], v[84:85], v[16:17] op_sel_hi:[0,1,1]
	v_pk_fma_f32 v[84:85], v[88:89], v[94:95], v[92:93] op_sel_hi:[0,1,1]
	v_rcp_f32_e32 v89, v33
	v_cndmask_b32_e64 v88, 0, 1.0, vcc
	v_lshlrev_b32_e32 v92, 16, v80
	v_and_b32_e32 v93, 0xffff0000, v80
	v_lshlrev_b32_e32 v80, 16, v81
	v_and_b32_e32 v81, 0xffff0000, v81
	v_pk_fma_f32 v[16:17], v[88:89], v[80:81], v[16:17] op_sel_hi:[0,1,1]
	v_fma_f32 v80, -v33, v89, 1.0
	v_pk_fma_f32 v[84:85], v[88:89], v[92:93], v[84:85] op_sel_hi:[0,1,1]
	v_fmac_f32_e32 v89, v80, v89
	v_div_scale_f32 v80, vcc, 1.0, v11, 1.0
	v_mul_f32_e32 v81, v80, v89
	v_fma_f32 v88, -v33, v81, v80
	v_fmac_f32_e32 v81, v88, v89
	v_fma_f32 v33, -v33, v81, v80
	v_div_fmas_f32 v33, v33, v89, v81
	v_div_fixup_f32 v80, v33, v11, 1.0
	v_xor_b32_e32 v15, 0x80000000, v15
	v_xor_b32_e32 v14, 0x80000000, v14
	v_xor_b32_e32 v13, 0x80000000, v13
	v_xor_b32_e32 v12, 0x80000000, v12
	v_pk_fma_f32 v[14:15], v[80:81], v[16:17], v[14:15] op_sel_hi:[0,1,1]
	v_pk_fma_f32 v[12:13], v[80:81], v[84:85], v[12:13] op_sel_hi:[0,1,1]
	s_lshl_b64 s[14:15], s[24:25], 11
	v_cvt_pk_bf16_f32 v12, v12, v13
	v_cvt_pk_bf16_f32 v13, v14, v15
	v_lshl_add_u64 v[14:15], v[22:23], 0, s[14:15]
	global_store_dwordx2 v[14:15], v[12:13], off
	v_mov_b64_e32 v[12:13], v[146:147]
	v_mov_b64_e32 v[14:15], v[148:149]
	s_nop 0
	v_mov_b64_e32 v[92:93], v[150:151]
	v_mov_b64_e32 v[94:95], v[152:153]
	v_mov_b64_e32 v[96:97], v[154:155]
	v_mov_b64_e32 v[98:99], v[156:157]
	v_mov_b64_e32 v[100:101], v[158:159]
	v_mov_b64_e32 v[102:103], v[160:161]
	v_mov_b64_e32 v[104:105], v[162:163]
	v_mov_b64_e32 v[106:107], v[164:165]
	s_cmp_gt_u32 s0, 2
	s_cselect_b64 s[14:15], -1, 0
	v_cndmask_b32_e64 v16, 0, 1.0, s[14:15]
	v_lshlrev_b32_e32 v80, 16, v78
	v_and_b32_e32 v81, 0xffff0000, v78
	v_lshlrev_b32_e32 v78, 16, v79
	v_and_b32_e32 v79, 0xffff0000, v79
	s_cmp_gt_u32 s0, 1
	v_pk_mul_f32 v[78:79], v[16:17], v[78:79] op_sel_hi:[0,1]
	v_pk_mul_f32 v[16:17], v[16:17], v[80:81] op_sel_hi:[0,1]
	s_cselect_b64 s[0:1], -1, 0
	s_nop 0
	v_pk_fma_f32 v[12:13], v[16:17], v[92:93], v[12:13]
	v_pk_fma_f32 v[14:15], v[78:79], v[94:95], v[14:15]
	v_cndmask_b32_e64 v16, 0, 1.0, s[0:1]
	v_lshlrev_b32_e32 v78, 16, v76
	v_and_b32_e32 v79, 0xffff0000, v76
	v_lshlrev_b32_e32 v76, 16, v77
	v_and_b32_e32 v77, 0xffff0000, v77
	v_pk_mul_f32 v[78:79], v[16:17], v[78:79] op_sel_hi:[0,1]
	v_pk_mul_f32 v[16:17], v[16:17], v[76:77] op_sel_hi:[0,1]
	v_pk_fma_f32 v[14:15], v[16:17], v[98:99], v[14:15]
	v_lshlrev_b32_e32 v16, 16, v74
	v_and_b32_e32 v17, 0xffff0000, v74
	v_lshlrev_b32_e32 v74, 16, v75
	v_and_b32_e32 v75, 0xffff0000, v75
	v_pk_fma_f32 v[12:13], v[78:79], v[96:97], v[12:13]
	v_pk_mul_f32 v[74:75], v[10:11], v[74:75] op_sel_hi:[0,1]
	v_pk_mul_f32 v[10:11], v[10:11], v[16:17] op_sel_hi:[0,1]
	v_pk_fma_f32 v[10:11], v[10:11], v[100:101], v[12:13]
	v_pk_fma_f32 v[12:13], v[74:75], v[102:103], v[14:15]
	v_lshlrev_b32_e32 v14, 16, v72
	v_and_b32_e32 v15, 0xffff0000, v72
	v_lshlrev_b32_e32 v16, 16, v73
	v_and_b32_e32 v17, 0xffff0000, v73
	v_pk_fma_f32 v[12:13], v[106:107], v[16:17], v[12:13]
	v_pk_fma_f32 v[10:11], v[104:105], v[14:15], v[10:11]
	s_lshl_b64 s[0:1], s[24:25], 9
	v_cvt_pk_bf16_f32 v10, v10, v11
	v_cvt_pk_bf16_f32 v11, v12, v13
	v_lshl_add_u64 v[12:13], v[28:29], 0, s[0:1]
	global_store_dwordx2 v[12:13], v[10:11], off
	s_branch .LBB0_563
.LBB0_566:
	s_waitcnt vmcnt(0)
	s_mov_b64 s[0:1], 0
